# K-loop code placement: peeled first iteration 8-byte aligned, loop heads 64-byte aligned (s_nop padding)
# speedup vs baseline: 1.0035x; 1.0035x over previous
; #define PG8_STAGE(bufoff, gbase, voff) do { _Pragma("unroll") for (int _i = 0; _i < 2; ++_i) \
;         __builtin_amdgcn_global_load_lds((const unsigned*)((const char*)(gbase) + (voff)[_i]), (PG8_LAS unsigned*)(lds + (bufoff) + ldsw + _i * 8192), 16, 0, 0); } while (0)
; #define PG8_LDA(dst, b, h) do { _Pragma("unroll") for (int m = 0; m < 4; ++m) _Pragma("unroll") for (int k = 0; k < 2; ++k) dst[m][k] = *(const PG8_LAS bf16x8*)(lds + PG8_SA(b, h) + aoff + m * 2048 + k * 1024); } while (0)
; #define PG8_LDB(dst, b, h) do { _Pragma("unroll") for (int n = 0; n < 2; ++n) _Pragma("unroll") for (int k = 0; k < 2; ++k) dst[n][k] = *(const PG8_LAS bf16x8*)(lds + PG8_SB(b, h) + boff + n * 2048 + k * 1024); } while (0)
; #define PG8_MMA(ai, bj, At, Bt) do { __builtin_amdgcn_s_setprio(1); _Pragma("unroll") for (int m = 0; m < 4; ++m) _Pragma("unroll") for (int n = 0; n < 2; ++n) _Pragma("unroll") for (int k = 0; k < 2; ++k) \
;         acc[ai][bj][m][n] = __builtin_amdgcn_mfma_f32_16x16x32_bf16(Bt[n][k], At[m][k], acc[ai][bj][m][n], 0, 0, 0); __builtin_amdgcn_s_setprio(0); } while (0)
; template <class Epi, class Sched, bool ALIGN_EPI = false, bool SP2 = false>
; __device__ __forceinline__ void gemm_phase(PG8_LAS unsigned char* lds, const Gemm g, const Sched& S, const Epi& E, int wave_in) {
;     ...
;         const char* nA = has_next ? (const char*)g.A + (size_t)(nxt.pm >> g.ash) * g.astride + (size_t)nxt.pm * tstep : cA; const char* nB = has_next ? (const char*)g.Bt + (size_t)(nxt.pm >> g.bsh) * g.bstride + (size_t)nxt.pn * tstep : cB;
;         for (int t = 0; t < nt; t += 2) {
;             const bool last = (t == nt - 2);
;             const char* a1 = cA + (size_t)(t + 1) * kstep;
;             const char* a2 = last ? nA : cA + (size_t)(t + 2) * kstep; const char* b2 = last ? nB : cB + (size_t)(t + 2) * kstep;
;             const char* a3 = a2 + kstep; const char* b3 = b2 + kstep;
;             if (last && has_next) S.a_ready(nxt);
;             if constexpr (SP2) {
;             PG8_LDB(B0, 0, 0); PG8_LDB(B1, 0, 1); PG8_SCHED; PG8_LDA(At, 0, 0); PG8_STAGE(PG8_SA(1, 1), a1 + hstep, voffA);
;             PG8_WAIT_V(8); PG8_WAIT_L(0); PG8_BAR; PG8_MMA(0, 0, At, B0); PG8_MMA(0, 1, At, B1); PG8_BAR; PG8_SCHED;
;             PG8_LDA(At, 0, 1); PG8_STAGE(PG8_SB(0, 0), b2, voffB); PG8_STAGE(PG8_SB(0, 1), b2 + hstep, voffB); PG8_STAGE(PG8_SA(0, 0), a2, voffA);
.LBB0_253:
	s_ashr_i32 s23, s22, 31
	s_lshl_b64 s[24:25], s[22:23], 19
	s_add_u32 s24, s62, s24
	s_addc_u32 s25, s63, s25
	s_and_b64 s[26:27], s[18:19], exec
	s_cselect_b32 s23, s25, s37
	s_cselect_b32 s29, s24, s36
	s_ashr_i32 s21, s20, 31
	s_lshl_b64 s[26:27], s[20:21], 19
	s_add_u32 s26, s64, s26
	s_addc_u32 s27, s65, s27
	s_and_b64 s[38:39], s[18:19], exec
	s_cselect_b32 s21, s27, s35
	s_cselect_b32 s31, s26, s34
	s_add_u32 s76, s34, 0x100
	s_addc_u32 s77, s35, 0
	s_add_u32 s34, s36, 0x40080
	s_addc_u32 s35, s37, 0
	s_mov_b32 s78, -2
	.p2alignl 3, 3212836864
	v_add_u32_e32 v174, s43, v160
	v_add_u32_e32 v190, s44, v160
	ds_read_b128 v[162:165], v174
	ds_read_b128 v[166:169], v174 offset:1024
	ds_read_b128 v[170:173], v174 offset:2048
	ds_read_b128 v[174:177], v174 offset:3072
	ds_read_b128 v[178:181], v190
	ds_read_b128 v[182:185], v190 offset:1024
	ds_read_b128 v[186:189], v190 offset:2048
	ds_read_b128 v[190:193], v190 offset:3072
	s_add_u32 s36, s34, 0xfffc0080
	s_addc_u32 s37, s35, -1
	s_cmp_eq_u32 s78, 12
	s_cselect_b32 s39, s23, s37
	s_cselect_b32 s38, s29, s36
	s_cselect_b32 s37, s21, s77
	s_cselect_b32 s36, s31, s76
	v_lshl_add_u64 v[226:227], s[34:35], 0, v[156:157]
	s_add_i32 m0, s67, 0xc000
	ds_read_b128 v[194:197], v161
	ds_read_b128 v[198:201], v161 offset:1024
	ds_read_b128 v[202:205], v161 offset:2048
	ds_read_b128 v[206:209], v161 offset:3072
	ds_read_b128 v[210:213], v161 offset:4096
	ds_read_b128 v[214:217], v161 offset:5120
	ds_read_b128 v[218:221], v161 offset:6144
	ds_read_b128 v[222:225], v161 offset:7168
	global_load_lds_dwordx4 v[226:227], off
	v_lshl_add_u64 v[226:227], s[34:35], 0, v[154:155]
	s_add_i32 m0, s67, 0xe000
	s_nop 0
	global_load_lds_dwordx4 v[226:227], off
	s_waitcnt vmcnt(8)
	s_waitcnt lgkmcnt(0)
	s_barrier
	s_setprio 1
	s_waitcnt lgkmcnt(0)
	v_mfma_f32_16x16x32_bf16 v[124:127], v[162:165], v[194:197], 0
	v_mfma_f32_16x16x32_bf16 v[120:123], v[170:173], v[194:197], 0
	v_mfma_f32_16x16x32_bf16 v[116:119], v[162:165], v[202:205], 0
	v_mfma_f32_16x16x32_bf16 v[108:111], v[170:173], v[202:205], 0
	v_mfma_f32_16x16x32_bf16 v[100:103], v[162:165], v[210:213], 0
	v_mfma_f32_16x16x32_bf16 v[92:95], v[170:173], v[210:213], 0
	v_mfma_f32_16x16x32_bf16 v[84:87], v[162:165], v[218:221], 0
	v_mfma_f32_16x16x32_bf16 v[76:79], v[170:173], v[218:221], 0
	v_mfma_f32_16x16x32_bf16 v[124:127], v[166:169], v[198:201], v[124:127]
	v_mfma_f32_16x16x32_bf16 v[120:123], v[174:177], v[198:201], v[120:123]
	v_mfma_f32_16x16x32_bf16 v[116:119], v[166:169], v[206:209], v[116:119]
	v_mfma_f32_16x16x32_bf16 v[108:111], v[174:177], v[206:209], v[108:111]
	v_mfma_f32_16x16x32_bf16 v[100:103], v[166:169], v[214:217], v[100:103]
	v_mfma_f32_16x16x32_bf16 v[92:95], v[174:177], v[214:217], v[92:95]
	v_mfma_f32_16x16x32_bf16 v[84:87], v[166:169], v[222:225], v[84:87]
	v_mfma_f32_16x16x32_bf16 v[76:79], v[174:177], v[222:225], v[76:79]
	s_setprio 0
	s_setprio 1
	v_mfma_f32_16x16x32_bf16 v[112:115], v[178:181], v[194:197], 0
	v_mfma_f32_16x16x32_bf16 v[104:107], v[186:189], v[194:197], 0
	v_mfma_f32_16x16x32_bf16 v[96:99], v[178:181], v[202:205], 0
	v_mfma_f32_16x16x32_bf16 v[88:91], v[186:189], v[202:205], 0
	v_mfma_f32_16x16x32_bf16 v[80:83], v[178:181], v[210:213], 0
	v_mfma_f32_16x16x32_bf16 v[72:75], v[186:189], v[210:213], 0
	v_mfma_f32_16x16x32_bf16 v[68:71], v[178:181], v[218:221], 0
	v_mfma_f32_16x16x32_bf16 v[64:67], v[186:189], v[218:221], 0
	v_mfma_f32_16x16x32_bf16 v[112:115], v[182:185], v[198:201], v[112:115]
	v_mfma_f32_16x16x32_bf16 v[104:107], v[190:193], v[198:201], v[104:107]
	v_mfma_f32_16x16x32_bf16 v[96:99], v[182:185], v[206:209], v[96:99]
	v_mfma_f32_16x16x32_bf16 v[88:91], v[190:193], v[206:209], v[88:91]
	v_mfma_f32_16x16x32_bf16 v[80:83], v[182:185], v[214:217], v[80:83]
	v_mfma_f32_16x16x32_bf16 v[72:75], v[190:193], v[214:217], v[72:75]
	v_mfma_f32_16x16x32_bf16 v[68:71], v[182:185], v[222:225], v[68:71]
	v_mfma_f32_16x16x32_bf16 v[64:67], v[190:193], v[222:225], v[64:67]
	s_setprio 0
	s_barrier
	s_add_i32 s79, s43, s66
	v_lshl_add_u64 v[226:227], s[36:37], 0, v[132:133]
	s_mov_b32 m0, s79
	ds_read_b128 v[194:197], v161 offset:16384
	ds_read_b128 v[198:201], v161 offset:17408
	ds_read_b128 v[202:205], v161 offset:18432
	ds_read_b128 v[206:209], v161 offset:19456
	ds_read_b128 v[210:213], v161 offset:20480
	ds_read_b128 v[214:217], v161 offset:21504
	ds_read_b128 v[218:221], v161 offset:22528
	ds_read_b128 v[222:225], v161 offset:23552
	global_load_lds_dwordx4 v[226:227], off
	s_add_i32 m0, s79, 0x2000
	s_add_u32 s80, s36, 0x40000
	v_lshl_add_u64 v[228:229], s[36:37], 0, v[136:137]
	s_addc_u32 s81, s37, 0
	s_add_i32 s79, s44, s66
	global_load_lds_dwordx4 v[228:229], off
	v_lshl_add_u64 v[230:231], s[80:81], 0, v[132:133]
	s_mov_b32 m0, s79
	v_lshl_add_u64 v[232:233], s[38:39], 0, v[134:135]
	global_load_lds_dwordx4 v[230:231], off
	v_lshl_add_u64 v[230:231], s[80:81], 0, v[136:137]
	s_add_i32 m0, s79, 0x2000
	s_nop 0
	global_load_lds_dwordx4 v[230:231], off
	v_lshl_add_u64 v[230:231], s[38:39], 0, v[130:131]
	s_mov_b32 m0, s67
	s_nop 0
	global_load_lds_dwordx4 v[230:231], off
	s_mov_b32 m0, s68
	s_nop 0
	global_load_lds_dwordx4 v[232:233], off
	s_waitcnt vmcnt(8)
	s_waitcnt lgkmcnt(0)
	s_barrier
; #define PG8_STAGE(bufoff, gbase, voff) do { _Pragma("unroll") for (int _i = 0; _i < 2; ++_i) \
;         __builtin_amdgcn_global_load_lds((const unsigned*)((const char*)(gbase) + (voff)[_i]), (PG8_LAS unsigned*)(lds + (bufoff) + ldsw + _i * 8192), 16, 0, 0); } while (0)
; #define PG8_LDA(dst, b, h) do { _Pragma("unroll") for (int m = 0; m < 4; ++m) _Pragma("unroll") for (int k = 0; k < 2; ++k) dst[m][k] = *(const PG8_LAS bf16x8*)(lds + PG8_SA(b, h) + aoff + m * 2048 + k * 1024); } while (0)
; #define PG8_LDB(dst, b, h) do { _Pragma("unroll") for (int n = 0; n < 2; ++n) _Pragma("unroll") for (int k = 0; k < 2; ++k) dst[n][k] = *(const PG8_LAS bf16x8*)(lds + PG8_SB(b, h) + boff + n * 2048 + k * 1024); } while (0)
; #define PG8_MMA(ai, bj, At, Bt) do { __builtin_amdgcn_s_setprio(1); _Pragma("unroll") for (int m = 0; m < 4; ++m) _Pragma("unroll") for (int n = 0; n < 2; ++n) _Pragma("unroll") for (int k = 0; k < 2; ++k) \
;         acc[ai][bj][m][n] = __builtin_amdgcn_mfma_f32_16x16x32_bf16(Bt[n][k], At[m][k], acc[ai][bj][m][n], 0, 0, 0); __builtin_amdgcn_s_setprio(0); } while (0)
; #define PG8_WAIT_V(n) asm volatile("s_waitcnt vmcnt(" #n ")" ::: "memory")
; #define PG8_WAIT_L(n) asm volatile("s_waitcnt lgkmcnt(" #n ")" ::: "memory")
; #define PG8_BAR __builtin_amdgcn_s_barrier()
; #define PG8_SCHED __builtin_amdgcn_sched_barrier(0)
; template <class Epi, class Sched, bool ALIGN_EPI = false, bool SP2 = false>
; __device__ __forceinline__ void gemm_phase(PG8_LAS unsigned char* lds, const Gemm g, const Sched& S, const Epi& E, int wave_in) {
;     ...
;             PG8_LDA(At, 0, 1); PG8_STAGE(PG8_SB(0, 0), b2, voffB); PG8_STAGE(PG8_SB(0, 1), b2 + hstep, voffB); PG8_STAGE(PG8_SA(0, 0), a2, voffA);
;             PG8_WAIT_V(8); PG8_WAIT_L(0); PG8_BAR; PG8_MMA(1, 0, At, B0); PG8_MMA(1, 1, At, B1); PG8_BAR; PG8_SCHED;
;             PG8_LDB(B0, 1, 0); PG8_LDB(B1, 1, 1); PG8_SCHED; PG8_LDA(At, 1, 0); PG8_STAGE(PG8_SA(0, 1), a2 + hstep, voffA);
;             PG8_WAIT_V(8); PG8_WAIT_L(0); PG8_BAR; PG8_MMA(0, 0, At, B0); PG8_MMA(0, 1, At, B1); PG8_BAR; PG8_SCHED;
	s_setprio 1
	s_waitcnt lgkmcnt(0)
	v_mfma_f32_16x16x32_bf16 v[60:63], v[162:165], v[194:197], 0
	v_mfma_f32_16x16x32_bf16 v[56:59], v[170:173], v[194:197], 0
	v_mfma_f32_16x16x32_bf16 v[52:55], v[162:165], v[202:205], 0
	v_mfma_f32_16x16x32_bf16 v[44:47], v[170:173], v[202:205], 0
	v_mfma_f32_16x16x32_bf16 v[36:39], v[162:165], v[210:213], 0
	v_mfma_f32_16x16x32_bf16 v[28:31], v[170:173], v[210:213], 0
	v_mfma_f32_16x16x32_bf16 v[20:23], v[162:165], v[218:221], 0
	v_mfma_f32_16x16x32_bf16 v[12:15], v[170:173], v[218:221], 0
	v_mfma_f32_16x16x32_bf16 v[60:63], v[166:169], v[198:201], v[60:63]
	v_mfma_f32_16x16x32_bf16 v[56:59], v[174:177], v[198:201], v[56:59]
	v_mfma_f32_16x16x32_bf16 v[52:55], v[166:169], v[206:209], v[52:55]
	v_mfma_f32_16x16x32_bf16 v[44:47], v[174:177], v[206:209], v[44:47]
	v_mfma_f32_16x16x32_bf16 v[36:39], v[166:169], v[214:217], v[36:39]
	v_mfma_f32_16x16x32_bf16 v[28:31], v[174:177], v[214:217], v[28:31]
	v_mfma_f32_16x16x32_bf16 v[20:23], v[166:169], v[222:225], v[20:23]
	v_mfma_f32_16x16x32_bf16 v[12:15], v[174:177], v[222:225], v[12:15]
	s_setprio 0
	s_setprio 1
	v_mfma_f32_16x16x32_bf16 v[48:51], v[178:181], v[194:197], 0
	v_mfma_f32_16x16x32_bf16 v[40:43], v[186:189], v[194:197], 0
	v_mfma_f32_16x16x32_bf16 v[32:35], v[178:181], v[202:205], 0
	v_mfma_f32_16x16x32_bf16 v[24:27], v[186:189], v[202:205], 0
	v_mfma_f32_16x16x32_bf16 v[16:19], v[178:181], v[210:213], 0
	v_mfma_f32_16x16x32_bf16 v[8:11], v[186:189], v[210:213], 0
	v_mfma_f32_16x16x32_bf16 v[4:7], v[178:181], v[218:221], 0
	v_mfma_f32_16x16x32_bf16 v[0:3], v[186:189], v[218:221], 0
	v_mfma_f32_16x16x32_bf16 v[48:51], v[182:185], v[198:201], v[48:51]
	v_mfma_f32_16x16x32_bf16 v[40:43], v[190:193], v[198:201], v[40:43]
	v_mfma_f32_16x16x32_bf16 v[32:35], v[182:185], v[206:209], v[32:35]
	v_mfma_f32_16x16x32_bf16 v[24:27], v[190:193], v[206:209], v[24:27]
	v_mfma_f32_16x16x32_bf16 v[16:19], v[182:185], v[214:217], v[16:19]
	v_mfma_f32_16x16x32_bf16 v[8:11], v[190:193], v[214:217], v[8:11]
	v_mfma_f32_16x16x32_bf16 v[4:7], v[182:185], v[222:225], v[4:7]
	v_mfma_f32_16x16x32_bf16 v[0:3], v[190:193], v[222:225], v[0:3]
	s_setprio 0
	s_barrier
	v_add_u32_e32 v174, s45, v160
	v_add_u32_e32 v190, s46, v160
	ds_read_b128 v[162:165], v174
	ds_read_b128 v[166:169], v174 offset:1024
	ds_read_b128 v[170:173], v174 offset:2048
	ds_read_b128 v[174:177], v174 offset:3072
	ds_read_b128 v[178:181], v190
	ds_read_b128 v[182:185], v190 offset:1024
	ds_read_b128 v[186:189], v190 offset:2048
	ds_read_b128 v[190:193], v190 offset:3072
	s_add_u32 s38, s38, 0x40000
	s_addc_u32 s39, s39, 0
	s_mov_b32 m0, s69
	v_lshl_add_u64 v[234:235], s[38:39], 0, v[130:131]
	ds_read_b128 v[194:197], v161 offset:32768
	ds_read_b128 v[198:201], v161 offset:33792
	ds_read_b128 v[202:205], v161 offset:34816
	ds_read_b128 v[206:209], v161 offset:35840
	ds_read_b128 v[210:213], v161 offset:36864
	ds_read_b128 v[214:217], v161 offset:37888
	ds_read_b128 v[218:221], v161 offset:38912
	ds_read_b128 v[222:225], v161 offset:39936
	global_load_lds_dwordx4 v[234:235], off
	v_lshl_add_u64 v[234:235], s[38:39], 0, v[134:135]
	s_mov_b32 m0, s70
	s_nop 0
	global_load_lds_dwordx4 v[234:235], off
	s_waitcnt vmcnt(8)
	s_waitcnt lgkmcnt(0)
	s_barrier
	s_setprio 1
	s_waitcnt lgkmcnt(0)
	v_mfma_f32_16x16x32_bf16 v[124:127], v[162:165], v[194:197], v[124:127]
	v_mfma_f32_16x16x32_bf16 v[120:123], v[170:173], v[194:197], v[120:123]
	v_mfma_f32_16x16x32_bf16 v[116:119], v[162:165], v[202:205], v[116:119]
	v_mfma_f32_16x16x32_bf16 v[108:111], v[170:173], v[202:205], v[108:111]
	v_mfma_f32_16x16x32_bf16 v[100:103], v[162:165], v[210:213], v[100:103]
	v_mfma_f32_16x16x32_bf16 v[92:95], v[170:173], v[210:213], v[92:95]
	v_mfma_f32_16x16x32_bf16 v[84:87], v[162:165], v[218:221], v[84:87]
	v_mfma_f32_16x16x32_bf16 v[76:79], v[170:173], v[218:221], v[76:79]
	v_mfma_f32_16x16x32_bf16 v[124:127], v[166:169], v[198:201], v[124:127]
	v_mfma_f32_16x16x32_bf16 v[120:123], v[174:177], v[198:201], v[120:123]
	v_mfma_f32_16x16x32_bf16 v[116:119], v[166:169], v[206:209], v[116:119]
	v_mfma_f32_16x16x32_bf16 v[108:111], v[174:177], v[206:209], v[108:111]
	v_mfma_f32_16x16x32_bf16 v[100:103], v[166:169], v[214:217], v[100:103]
	v_mfma_f32_16x16x32_bf16 v[92:95], v[174:177], v[214:217], v[92:95]
	v_mfma_f32_16x16x32_bf16 v[84:87], v[166:169], v[222:225], v[84:87]
	v_mfma_f32_16x16x32_bf16 v[76:79], v[174:177], v[222:225], v[76:79]
	s_setprio 0
	s_setprio 1
	v_mfma_f32_16x16x32_bf16 v[112:115], v[178:181], v[194:197], v[112:115]
	v_mfma_f32_16x16x32_bf16 v[104:107], v[186:189], v[194:197], v[104:107]
	v_mfma_f32_16x16x32_bf16 v[96:99], v[178:181], v[202:205], v[96:99]
	v_mfma_f32_16x16x32_bf16 v[88:91], v[186:189], v[202:205], v[88:91]
	v_mfma_f32_16x16x32_bf16 v[80:83], v[178:181], v[210:213], v[80:83]
	v_mfma_f32_16x16x32_bf16 v[72:75], v[186:189], v[210:213], v[72:75]
	v_mfma_f32_16x16x32_bf16 v[68:71], v[178:181], v[218:221], v[68:71]
	v_mfma_f32_16x16x32_bf16 v[64:67], v[186:189], v[218:221], v[64:67]
	v_mfma_f32_16x16x32_bf16 v[112:115], v[182:185], v[198:201], v[112:115]
	v_mfma_f32_16x16x32_bf16 v[104:107], v[190:193], v[198:201], v[104:107]
	v_mfma_f32_16x16x32_bf16 v[96:99], v[182:185], v[206:209], v[96:99]
	v_mfma_f32_16x16x32_bf16 v[88:91], v[190:193], v[206:209], v[88:91]
	v_mfma_f32_16x16x32_bf16 v[80:83], v[182:185], v[214:217], v[80:83]
	v_mfma_f32_16x16x32_bf16 v[72:75], v[190:193], v[214:217], v[72:75]
	v_mfma_f32_16x16x32_bf16 v[68:71], v[182:185], v[222:225], v[68:71]
	v_mfma_f32_16x16x32_bf16 v[64:67], v[190:193], v[222:225], v[64:67]
	s_setprio 0
	s_barrier
; #define PG8_STAGE(bufoff, gbase, voff) do { _Pragma("unroll") for (int _i = 0; _i < 2; ++_i) \
;         __builtin_amdgcn_global_load_lds((const unsigned*)((const char*)(gbase) + (voff)[_i]), (PG8_LAS unsigned*)(lds + (bufoff) + ldsw + _i * 8192), 16, 0, 0); } while (0)
; #define PG8_LDA(dst, b, h) do { _Pragma("unroll") for (int m = 0; m < 4; ++m) _Pragma("unroll") for (int k = 0; k < 2; ++k) dst[m][k] = *(const PG8_LAS bf16x8*)(lds + PG8_SA(b, h) + aoff + m * 2048 + k * 1024); } while (0)
; #define PG8_MMA(ai, bj, At, Bt) do { __builtin_amdgcn_s_setprio(1); _Pragma("unroll") for (int m = 0; m < 4; ++m) _Pragma("unroll") for (int n = 0; n < 2; ++n) _Pragma("unroll") for (int k = 0; k < 2; ++k) \
;         acc[ai][bj][m][n] = __builtin_amdgcn_mfma_f32_16x16x32_bf16(Bt[n][k], At[m][k], acc[ai][bj][m][n], 0, 0, 0); __builtin_amdgcn_s_setprio(0); } while (0)
; #define PG8_WAIT_V(n) asm volatile("s_waitcnt vmcnt(" #n ")" ::: "memory")
; #define PG8_WAIT_L(n) asm volatile("s_waitcnt lgkmcnt(" #n ")" ::: "memory")
; #define PG8_BAR __builtin_amdgcn_s_barrier()
; #define PG8_SCHED __builtin_amdgcn_sched_barrier(0)
; template <class Epi, class Sched, bool ALIGN_EPI = false, bool SP2 = false>
; __device__ __forceinline__ void gemm_phase(PG8_LAS unsigned char* lds, const Gemm g, const Sched& S, const Epi& E, int wave_in) {
;     ...
;             PG8_WAIT_V(8); PG8_WAIT_L(0); PG8_BAR; PG8_MMA(0, 0, At, B0); PG8_MMA(0, 1, At, B1); PG8_BAR; PG8_SCHED;
;             PG8_LDA(At, 1, 1); PG8_STAGE(PG8_SB(1, 0), b3, voffB); PG8_STAGE(PG8_SB(1, 1), b3 + hstep, voffB); PG8_STAGE(PG8_SA(1, 0), a3, voffA);
;             PG8_WAIT_V(8); PG8_WAIT_L(0); PG8_BAR; PG8_MMA(1, 0, At, B0); PG8_MMA(1, 1, At, B1); PG8_BAR; PG8_SCHED;
	s_add_i32 s38, s45, s66
	v_lshl_add_u64 v[226:227], v[226:227], 0, s[6:7]
	s_mov_b32 m0, s38
	ds_read_b128 v[194:197], v161 offset:49152
	ds_read_b128 v[198:201], v161 offset:50176
	ds_read_b128 v[202:205], v161 offset:51200
	ds_read_b128 v[206:209], v161 offset:52224
	ds_read_b128 v[210:213], v161 offset:53248
	ds_read_b128 v[214:217], v161 offset:54272
	ds_read_b128 v[218:221], v161 offset:55296
	ds_read_b128 v[222:225], v161 offset:56320
	global_load_lds_dwordx4 v[226:227], off
	s_add_i32 m0, s38, 0x2000
	s_add_u32 s36, s36, 0x40080
	v_lshl_add_u64 v[226:227], v[228:229], 0, s[6:7]
	s_addc_u32 s37, s37, 0
	s_add_i32 s38, s46, s66
	global_load_lds_dwordx4 v[226:227], off
	v_lshl_add_u64 v[226:227], s[36:37], 0, v[132:133]
	s_mov_b32 m0, s38
	s_nop 0
	global_load_lds_dwordx4 v[226:227], off
	v_lshl_add_u64 v[226:227], s[36:37], 0, v[136:137]
	s_add_i32 m0, s38, 0x2000
	s_nop 0
	global_load_lds_dwordx4 v[226:227], off
	v_lshl_add_u64 v[226:227], v[230:231], 0, s[6:7]
	s_mov_b32 m0, s73
	s_nop 0
	global_load_lds_dwordx4 v[226:227], off
	v_lshl_add_u64 v[226:227], v[232:233], 0, s[6:7]
	s_mov_b32 m0, s74
	s_nop 0
	global_load_lds_dwordx4 v[226:227], off
	s_waitcnt vmcnt(8)
	s_waitcnt lgkmcnt(0)
	s_barrier
	s_setprio 1
	s_waitcnt lgkmcnt(0)
	v_mfma_f32_16x16x32_bf16 v[60:63], v[162:165], v[194:197], v[60:63]
	v_mfma_f32_16x16x32_bf16 v[56:59], v[170:173], v[194:197], v[56:59]
	v_mfma_f32_16x16x32_bf16 v[52:55], v[162:165], v[202:205], v[52:55]
	v_mfma_f32_16x16x32_bf16 v[44:47], v[170:173], v[202:205], v[44:47]
	v_mfma_f32_16x16x32_bf16 v[36:39], v[162:165], v[210:213], v[36:39]
	v_mfma_f32_16x16x32_bf16 v[28:31], v[170:173], v[210:213], v[28:31]
	v_mfma_f32_16x16x32_bf16 v[20:23], v[162:165], v[218:221], v[20:23]
	v_mfma_f32_16x16x32_bf16 v[12:15], v[170:173], v[218:221], v[12:15]
	v_mfma_f32_16x16x32_bf16 v[60:63], v[166:169], v[198:201], v[60:63]
	v_mfma_f32_16x16x32_bf16 v[56:59], v[174:177], v[198:201], v[56:59]
	v_mfma_f32_16x16x32_bf16 v[52:55], v[166:169], v[206:209], v[52:55]
	v_mfma_f32_16x16x32_bf16 v[44:47], v[174:177], v[206:209], v[44:47]
	v_mfma_f32_16x16x32_bf16 v[36:39], v[166:169], v[214:217], v[36:39]
	v_mfma_f32_16x16x32_bf16 v[28:31], v[174:177], v[214:217], v[28:31]
	v_mfma_f32_16x16x32_bf16 v[20:23], v[166:169], v[222:225], v[20:23]
	v_mfma_f32_16x16x32_bf16 v[12:15], v[174:177], v[222:225], v[12:15]
	s_setprio 0
	s_setprio 1
	v_mfma_f32_16x16x32_bf16 v[48:51], v[178:181], v[194:197], v[48:51]
	v_mfma_f32_16x16x32_bf16 v[40:43], v[186:189], v[194:197], v[40:43]
	v_mfma_f32_16x16x32_bf16 v[32:35], v[178:181], v[202:205], v[32:35]
	v_mfma_f32_16x16x32_bf16 v[24:27], v[186:189], v[202:205], v[24:27]
	v_mfma_f32_16x16x32_bf16 v[16:19], v[178:181], v[210:213], v[16:19]
	v_mfma_f32_16x16x32_bf16 v[8:11], v[186:189], v[210:213], v[8:11]
	v_mfma_f32_16x16x32_bf16 v[4:7], v[178:181], v[218:221], v[4:7]
	v_mfma_f32_16x16x32_bf16 v[0:3], v[186:189], v[218:221], v[0:3]
	v_mfma_f32_16x16x32_bf16 v[48:51], v[182:185], v[198:201], v[48:51]
	v_mfma_f32_16x16x32_bf16 v[40:43], v[190:193], v[198:201], v[40:43]
	v_mfma_f32_16x16x32_bf16 v[32:35], v[182:185], v[206:209], v[32:35]
	v_mfma_f32_16x16x32_bf16 v[24:27], v[190:193], v[206:209], v[24:27]
	v_mfma_f32_16x16x32_bf16 v[16:19], v[182:185], v[214:217], v[16:19]
	v_mfma_f32_16x16x32_bf16 v[8:11], v[190:193], v[214:217], v[8:11]
	v_mfma_f32_16x16x32_bf16 v[4:7], v[182:185], v[222:225], v[4:7]
	v_mfma_f32_16x16x32_bf16 v[0:3], v[190:193], v[222:225], v[0:3]
	s_setprio 0
	s_barrier
	s_add_i32 s78, s78, 2
	s_add_u32 s76, s76, 0x100
	s_addc_u32 s77, s77, 0
	s_add_u32 s34, s34, 0x100
	s_addc_u32 s35, s35, 0
	s_cmp_gt_u32 s78, 13
	s_cbranch_scc1 .Lkexit_0
	.p2alignl 6, 3212836864

; #define PG8_STAGE(bufoff, gbase, voff) do { _Pragma("unroll") for (int _i = 0; _i < 2; ++_i) \
;         __builtin_amdgcn_global_load_lds((const unsigned*)((const char*)(gbase) + (voff)[_i]), (PG8_LAS unsigned*)(lds + (bufoff) + ldsw + _i * 8192), 16, 0, 0); } while (0)
; #define PG8_LDA(dst, b, h) do { _Pragma("unroll") for (int m = 0; m < 4; ++m) _Pragma("unroll") for (int k = 0; k < 2; ++k) dst[m][k] = *(const PG8_LAS bf16x8*)(lds + PG8_SA(b, h) + aoff + m * 2048 + k * 1024); } while (0)
; #define PG8_LDB(dst, b, h) do { _Pragma("unroll") for (int n = 0; n < 2; ++n) _Pragma("unroll") for (int k = 0; k < 2; ++k) dst[n][k] = *(const PG8_LAS bf16x8*)(lds + PG8_SB(b, h) + boff + n * 2048 + k * 1024); } while (0)
; #define PG8_MMA(ai, bj, At, Bt) do { __builtin_amdgcn_s_setprio(1); _Pragma("unroll") for (int m = 0; m < 4; ++m) _Pragma("unroll") for (int n = 0; n < 2; ++n) _Pragma("unroll") for (int k = 0; k < 2; ++k) \
;         acc[ai][bj][m][n] = __builtin_amdgcn_mfma_f32_16x16x32_bf16(Bt[n][k], At[m][k], acc[ai][bj][m][n], 0, 0, 0); __builtin_amdgcn_s_setprio(0); } while (0)
; template <class Epi, class Sched, bool ALIGN_EPI = false, bool SP2 = false>
; __device__ __forceinline__ void gemm_phase(PG8_LAS unsigned char* lds, const Gemm g, const Sched& S, const Epi& E, int wave_in) {
;     ...
;         const char* nA = has_next ? (const char*)g.A + (size_t)(nxt.pm >> g.ash) * g.astride + (size_t)nxt.pm * tstep : cA; const char* nB = has_next ? (const char*)g.Bt + (size_t)(nxt.pm >> g.bsh) * g.bstride + (size_t)nxt.pn * tstep : cB;
;         for (int t = 0; t < nt; t += 2) {
;             const bool last = (t == nt - 2);
;             const char* a1 = cA + (size_t)(t + 1) * kstep;
;             const char* a2 = last ? nA : cA + (size_t)(t + 2) * kstep; const char* b2 = last ? nB : cB + (size_t)(t + 2) * kstep;
;             const char* a3 = a2 + kstep; const char* b3 = b2 + kstep;
;             if (last && has_next) S.a_ready(nxt);
;             if constexpr (SP2) {
;             PG8_LDB(B0, 0, 0); PG8_LDB(B1, 0, 1); PG8_SCHED; PG8_LDA(At, 0, 0); PG8_STAGE(PG8_SA(1, 1), a1 + hstep, voffA);
;             PG8_WAIT_V(8); PG8_WAIT_L(0); PG8_BAR; PG8_MMA(0, 0, At, B0); PG8_MMA(0, 1, At, B1); PG8_BAR; PG8_SCHED;
;             PG8_LDA(At, 0, 1); PG8_STAGE(PG8_SB(0, 0), b2, voffB); PG8_STAGE(PG8_SB(0, 1), b2 + hstep, voffB); PG8_STAGE(PG8_SA(0, 0), a2, voffA);
.LBB0_272:
	s_ashr_i32 s77, s76, 31
	s_lshl_b64 s[8:9], s[76:77], 19
	s_add_u32 s84, s22, s8
	s_addc_u32 s85, s23, s9
	s_and_b64 s[8:9], s[40:41], exec
	s_cselect_b32 s8, s85, s5
	s_cselect_b32 s9, s84, s4
	s_ashr_i32 s95, s94, 31
	s_lshl_b64 s[10:11], s[94:95], 19
	v_readlane_b32 s16, v255, 39
	v_readlane_b32 s17, v255, 40
	s_add_u32 s24, s16, s10
	s_addc_u32 s25, s17, s11
	s_and_b64 s[10:11], s[40:41], exec
	s_cselect_b32 s16, s25, s1
	s_cselect_b32 s17, s24, s0
	s_add_u32 s31, s0, 0x100
	s_addc_u32 s33, s1, 0
	s_add_u32 s0, s4, 0x40080
	s_addc_u32 s1, s5, 0
	s_mov_b32 s34, -2
	s_waitcnt lgkmcnt(0)
	.p2alignl 3, 3212836864
	s_add_u32 s4, s0, 0xfffc0080
	s_addc_u32 s5, s1, -1
	s_add_i32 s42, s35, 0x100
	s_cmp_eq_u32 s34, 12
	s_cselect_b32 s11, s8, s5
	s_cselect_b32 s10, s9, s4
	s_cselect_b32 s5, s16, s33
	s_cselect_b32 s4, s17, s31
	s_add_i32 s44, s90, 0x100
	v_add_u32_e32 v168, s42, v177
	v_add_u32_e32 v188, s44, v177
	ds_read_b128 v[156:159], v168
	ds_read_b128 v[160:163], v168 offset:1024
	ds_read_b128 v[164:167], v168 offset:2048
	ds_read_b128 v[168:171], v168 offset:3072
	ds_read_b128 v[172:175], v188
	ds_read_b128 v[180:183], v188 offset:1024
	ds_read_b128 v[184:187], v188 offset:2048
	ds_read_b128 v[188:191], v188 offset:3072
	v_lshl_add_u64 v[230:231], s[0:1], 0, v[154:155]
	s_add_i32 m0, s67, 0xc000
	ds_read_b128 v[198:201], v179
	ds_read_b128 v[202:205], v179 offset:1024
	ds_read_b128 v[206:209], v179 offset:2048
	ds_read_b128 v[210:213], v179 offset:3072
	ds_read_b128 v[214:217], v179 offset:4096
	ds_read_b128 v[218:221], v179 offset:5120
	ds_read_b128 v[222:225], v179 offset:6144
	ds_read_b128 v[226:229], v179 offset:7168
	global_load_lds_dwordx4 v[230:231], off
	v_lshl_add_u64 v[230:231], s[0:1], 0, v[152:153]
	s_add_i32 m0, s67, 0xe000
	s_nop 0
	global_load_lds_dwordx4 v[230:231], off
	s_waitcnt vmcnt(8)
	s_waitcnt lgkmcnt(0)
	s_barrier
	s_setprio 1
	s_waitcnt lgkmcnt(0)
	v_mfma_f32_16x16x32_bf16 v[124:127], v[156:159], v[198:201], 0
	v_mfma_f32_16x16x32_bf16 v[120:123], v[164:167], v[198:201], 0
	v_mfma_f32_16x16x32_bf16 v[108:111], v[156:159], v[206:209], 0
	v_mfma_f32_16x16x32_bf16 v[104:107], v[164:167], v[206:209], 0
	v_mfma_f32_16x16x32_bf16 v[92:95], v[156:159], v[214:217], 0
	v_mfma_f32_16x16x32_bf16 v[88:91], v[164:167], v[214:217], 0
	v_mfma_f32_16x16x32_bf16 v[76:79], v[156:159], v[222:225], 0
	v_mfma_f32_16x16x32_bf16 v[72:75], v[164:167], v[222:225], 0
	v_mfma_f32_16x16x32_bf16 v[124:127], v[160:163], v[202:205], v[124:127]
	v_mfma_f32_16x16x32_bf16 v[120:123], v[168:171], v[202:205], v[120:123]
	v_mfma_f32_16x16x32_bf16 v[108:111], v[160:163], v[210:213], v[108:111]
	v_mfma_f32_16x16x32_bf16 v[104:107], v[168:171], v[210:213], v[104:107]
	v_mfma_f32_16x16x32_bf16 v[92:95], v[160:163], v[218:221], v[92:95]
	v_mfma_f32_16x16x32_bf16 v[88:91], v[168:171], v[218:221], v[88:91]
	v_mfma_f32_16x16x32_bf16 v[76:79], v[160:163], v[226:229], v[76:79]
	v_mfma_f32_16x16x32_bf16 v[72:75], v[168:171], v[226:229], v[72:75]
	s_setprio 0
	s_setprio 1
	v_mfma_f32_16x16x32_bf16 v[116:119], v[172:175], v[198:201], 0
	v_mfma_f32_16x16x32_bf16 v[112:115], v[184:187], v[198:201], 0
	v_mfma_f32_16x16x32_bf16 v[100:103], v[172:175], v[206:209], 0
	v_mfma_f32_16x16x32_bf16 v[96:99], v[184:187], v[206:209], 0
	v_mfma_f32_16x16x32_bf16 v[84:87], v[172:175], v[214:217], 0
	v_mfma_f32_16x16x32_bf16 v[80:83], v[184:187], v[214:217], 0
	v_mfma_f32_16x16x32_bf16 v[68:71], v[172:175], v[222:225], 0
	v_mfma_f32_16x16x32_bf16 v[64:67], v[184:187], v[222:225], 0
	v_mfma_f32_16x16x32_bf16 v[116:119], v[180:183], v[202:205], v[116:119]
	v_mfma_f32_16x16x32_bf16 v[112:115], v[188:191], v[202:205], v[112:115]
	v_mfma_f32_16x16x32_bf16 v[100:103], v[180:183], v[210:213], v[100:103]
	v_mfma_f32_16x16x32_bf16 v[96:99], v[188:191], v[210:213], v[96:99]
	v_mfma_f32_16x16x32_bf16 v[84:87], v[180:183], v[218:221], v[84:87]
	v_mfma_f32_16x16x32_bf16 v[80:83], v[188:191], v[218:221], v[80:83]
	v_mfma_f32_16x16x32_bf16 v[68:71], v[180:183], v[226:229], v[68:71]
	v_mfma_f32_16x16x32_bf16 v[64:67], v[188:191], v[226:229], v[64:67]
	s_setprio 0
	s_barrier
	s_add_i32 s42, s42, s66
	v_lshl_add_u64 v[230:231], s[4:5], 0, v[132:133]
	s_mov_b32 m0, s42
	ds_read_b128 v[198:201], v179 offset:16384
	ds_read_b128 v[202:205], v179 offset:17408
	ds_read_b128 v[206:209], v179 offset:18432
	ds_read_b128 v[210:213], v179 offset:19456
	ds_read_b128 v[214:217], v179 offset:20480
	ds_read_b128 v[218:221], v179 offset:21504
	ds_read_b128 v[222:225], v179 offset:22528
	ds_read_b128 v[226:229], v179 offset:23552
	global_load_lds_dwordx4 v[230:231], off
	s_add_i32 m0, s42, 0x2000
	s_add_u32 s42, s4, 0x40000
	v_lshl_add_u64 v[232:233], s[4:5], 0, v[128:129]
	s_addc_u32 s43, s5, 0
	s_add_i32 s44, s44, s66
	global_load_lds_dwordx4 v[232:233], off
	v_lshl_add_u64 v[234:235], s[42:43], 0, v[132:133]
	s_mov_b32 m0, s44
	v_lshl_add_u64 v[236:237], s[10:11], 0, v[130:131]
	global_load_lds_dwordx4 v[234:235], off
	v_lshl_add_u64 v[234:235], s[42:43], 0, v[128:129]
	s_add_i32 m0, s44, 0x2000
	s_nop 0
	global_load_lds_dwordx4 v[234:235], off
	v_lshl_add_u64 v[234:235], s[10:11], 0, v[134:135]
	s_mov_b32 m0, s67
	s_nop 0
	global_load_lds_dwordx4 v[234:235], off
	s_mov_b32 m0, s78
	s_nop 0
	global_load_lds_dwordx4 v[236:237], off
	s_waitcnt vmcnt(8)
	s_waitcnt lgkmcnt(0)
	s_barrier
; #define PG8_STAGE(bufoff, gbase, voff) do { _Pragma("unroll") for (int _i = 0; _i < 2; ++_i) \
;         __builtin_amdgcn_global_load_lds((const unsigned*)((const char*)(gbase) + (voff)[_i]), (PG8_LAS unsigned*)(lds + (bufoff) + ldsw + _i * 8192), 16, 0, 0); } while (0)
; #define PG8_LDA(dst, b, h) do { _Pragma("unroll") for (int m = 0; m < 4; ++m) _Pragma("unroll") for (int k = 0; k < 2; ++k) dst[m][k] = *(const PG8_LAS bf16x8*)(lds + PG8_SA(b, h) + aoff + m * 2048 + k * 1024); } while (0)
; #define PG8_LDB(dst, b, h) do { _Pragma("unroll") for (int n = 0; n < 2; ++n) _Pragma("unroll") for (int k = 0; k < 2; ++k) dst[n][k] = *(const PG8_LAS bf16x8*)(lds + PG8_SB(b, h) + boff + n * 2048 + k * 1024); } while (0)
; #define PG8_MMA(ai, bj, At, Bt) do { __builtin_amdgcn_s_setprio(1); _Pragma("unroll") for (int m = 0; m < 4; ++m) _Pragma("unroll") for (int n = 0; n < 2; ++n) _Pragma("unroll") for (int k = 0; k < 2; ++k) \
;         acc[ai][bj][m][n] = __builtin_amdgcn_mfma_f32_16x16x32_bf16(Bt[n][k], At[m][k], acc[ai][bj][m][n], 0, 0, 0); __builtin_amdgcn_s_setprio(0); } while (0)
; #define PG8_WAIT_V(n) asm volatile("s_waitcnt vmcnt(" #n ")" ::: "memory")
; #define PG8_WAIT_L(n) asm volatile("s_waitcnt lgkmcnt(" #n ")" ::: "memory")
; #define PG8_BAR __builtin_amdgcn_s_barrier()
; #define PG8_SCHED __builtin_amdgcn_sched_barrier(0)
; template <class Epi, class Sched, bool ALIGN_EPI = false, bool SP2 = false>
; __device__ __forceinline__ void gemm_phase(PG8_LAS unsigned char* lds, const Gemm g, const Sched& S, const Epi& E, int wave_in) {
;     ...
;             PG8_LDA(At, 0, 1); PG8_STAGE(PG8_SB(0, 0), b2, voffB); PG8_STAGE(PG8_SB(0, 1), b2 + hstep, voffB); PG8_STAGE(PG8_SA(0, 0), a2, voffA);
;             PG8_WAIT_V(8); PG8_WAIT_L(0); PG8_BAR; PG8_MMA(1, 0, At, B0); PG8_MMA(1, 1, At, B1); PG8_BAR; PG8_SCHED;
;             PG8_LDB(B0, 1, 0); PG8_LDB(B1, 1, 1); PG8_SCHED; PG8_LDA(At, 1, 0); PG8_STAGE(PG8_SA(0, 1), a2 + hstep, voffA);
;             PG8_WAIT_V(8); PG8_WAIT_L(0); PG8_BAR; PG8_MMA(0, 0, At, B0); PG8_MMA(0, 1, At, B1); PG8_BAR; PG8_SCHED;
	s_setprio 1
	s_waitcnt lgkmcnt(0)
	v_mfma_f32_16x16x32_bf16 v[60:63], v[156:159], v[198:201], 0
	v_mfma_f32_16x16x32_bf16 v[56:59], v[164:167], v[198:201], 0
	v_mfma_f32_16x16x32_bf16 v[44:47], v[156:159], v[206:209], 0
	v_mfma_f32_16x16x32_bf16 v[40:43], v[164:167], v[206:209], 0
	v_mfma_f32_16x16x32_bf16 v[28:31], v[156:159], v[214:217], 0
	v_mfma_f32_16x16x32_bf16 v[24:27], v[164:167], v[214:217], 0
	v_mfma_f32_16x16x32_bf16 v[12:15], v[156:159], v[222:225], 0
	v_mfma_f32_16x16x32_bf16 v[8:11], v[164:167], v[222:225], 0
	v_mfma_f32_16x16x32_bf16 v[60:63], v[160:163], v[202:205], v[60:63]
	v_mfma_f32_16x16x32_bf16 v[56:59], v[168:171], v[202:205], v[56:59]
	v_mfma_f32_16x16x32_bf16 v[44:47], v[160:163], v[210:213], v[44:47]
	v_mfma_f32_16x16x32_bf16 v[40:43], v[168:171], v[210:213], v[40:43]
	v_mfma_f32_16x16x32_bf16 v[28:31], v[160:163], v[218:221], v[28:31]
	v_mfma_f32_16x16x32_bf16 v[24:27], v[168:171], v[218:221], v[24:27]
	v_mfma_f32_16x16x32_bf16 v[12:15], v[160:163], v[226:229], v[12:15]
	v_mfma_f32_16x16x32_bf16 v[8:11], v[168:171], v[226:229], v[8:11]
	s_setprio 0
	s_setprio 1
	v_mfma_f32_16x16x32_bf16 v[52:55], v[172:175], v[198:201], 0
	v_mfma_f32_16x16x32_bf16 v[48:51], v[184:187], v[198:201], 0
	v_mfma_f32_16x16x32_bf16 v[36:39], v[172:175], v[206:209], 0
	v_mfma_f32_16x16x32_bf16 v[32:35], v[184:187], v[206:209], 0
	v_mfma_f32_16x16x32_bf16 v[20:23], v[172:175], v[214:217], 0
	v_mfma_f32_16x16x32_bf16 v[16:19], v[184:187], v[214:217], 0
	v_mfma_f32_16x16x32_bf16 v[4:7], v[172:175], v[222:225], 0
	v_mfma_f32_16x16x32_bf16 v[0:3], v[184:187], v[222:225], 0
	v_mfma_f32_16x16x32_bf16 v[52:55], v[180:183], v[202:205], v[52:55]
	v_mfma_f32_16x16x32_bf16 v[48:51], v[188:191], v[202:205], v[48:51]
	v_mfma_f32_16x16x32_bf16 v[36:39], v[180:183], v[210:213], v[36:39]
	v_mfma_f32_16x16x32_bf16 v[32:35], v[188:191], v[210:213], v[32:35]
	v_mfma_f32_16x16x32_bf16 v[20:23], v[180:183], v[218:221], v[20:23]
	v_mfma_f32_16x16x32_bf16 v[16:19], v[188:191], v[218:221], v[16:19]
	v_mfma_f32_16x16x32_bf16 v[4:7], v[180:183], v[226:229], v[4:7]
	v_mfma_f32_16x16x32_bf16 v[0:3], v[188:191], v[226:229], v[0:3]
	s_setprio 0
	s_barrier
	s_add_i32 s42, s65, 0x100
	s_add_i32 s43, s52, 0x100
	v_add_u32_e32 v168, s42, v177
	v_add_u32_e32 v188, s43, v177
	ds_read_b128 v[156:159], v168
	ds_read_b128 v[160:163], v168 offset:1024
	ds_read_b128 v[164:167], v168 offset:2048
	ds_read_b128 v[168:171], v168 offset:3072
	ds_read_b128 v[172:175], v188
	ds_read_b128 v[180:183], v188 offset:1024
	ds_read_b128 v[184:187], v188 offset:2048
	ds_read_b128 v[188:191], v188 offset:3072
	s_add_u32 s10, s10, 0x40000
	s_addc_u32 s11, s11, 0
	s_mov_b32 m0, s79
	v_lshl_add_u64 v[238:239], s[10:11], 0, v[134:135]
	ds_read_b128 v[198:201], v179 offset:32768
	ds_read_b128 v[202:205], v179 offset:33792
	ds_read_b128 v[206:209], v179 offset:34816
	ds_read_b128 v[210:213], v179 offset:35840
	ds_read_b128 v[214:217], v179 offset:36864
	ds_read_b128 v[218:221], v179 offset:37888
	ds_read_b128 v[222:225], v179 offset:38912
	ds_read_b128 v[226:229], v179 offset:39936
	global_load_lds_dwordx4 v[238:239], off
	v_lshl_add_u64 v[238:239], s[10:11], 0, v[130:131]
	s_mov_b32 m0, s82
	s_nop 0
	global_load_lds_dwordx4 v[238:239], off
	s_waitcnt vmcnt(8)
	s_waitcnt lgkmcnt(0)
	s_barrier
	s_setprio 1
	s_waitcnt lgkmcnt(0)
	v_mfma_f32_16x16x32_bf16 v[124:127], v[156:159], v[198:201], v[124:127]
	v_mfma_f32_16x16x32_bf16 v[120:123], v[164:167], v[198:201], v[120:123]
	v_mfma_f32_16x16x32_bf16 v[108:111], v[156:159], v[206:209], v[108:111]
	v_mfma_f32_16x16x32_bf16 v[104:107], v[164:167], v[206:209], v[104:107]
	v_mfma_f32_16x16x32_bf16 v[92:95], v[156:159], v[214:217], v[92:95]
	v_mfma_f32_16x16x32_bf16 v[88:91], v[164:167], v[214:217], v[88:91]
	v_mfma_f32_16x16x32_bf16 v[76:79], v[156:159], v[222:225], v[76:79]
	v_mfma_f32_16x16x32_bf16 v[72:75], v[164:167], v[222:225], v[72:75]
	v_mfma_f32_16x16x32_bf16 v[124:127], v[160:163], v[202:205], v[124:127]
	v_mfma_f32_16x16x32_bf16 v[120:123], v[168:171], v[202:205], v[120:123]
	v_mfma_f32_16x16x32_bf16 v[108:111], v[160:163], v[210:213], v[108:111]
	v_mfma_f32_16x16x32_bf16 v[104:107], v[168:171], v[210:213], v[104:107]
	v_mfma_f32_16x16x32_bf16 v[92:95], v[160:163], v[218:221], v[92:95]
	v_mfma_f32_16x16x32_bf16 v[88:91], v[168:171], v[218:221], v[88:91]
	v_mfma_f32_16x16x32_bf16 v[76:79], v[160:163], v[226:229], v[76:79]
	v_mfma_f32_16x16x32_bf16 v[72:75], v[168:171], v[226:229], v[72:75]
	s_setprio 0
	s_setprio 1
	v_mfma_f32_16x16x32_bf16 v[116:119], v[172:175], v[198:201], v[116:119]
	v_mfma_f32_16x16x32_bf16 v[112:115], v[184:187], v[198:201], v[112:115]
	v_mfma_f32_16x16x32_bf16 v[100:103], v[172:175], v[206:209], v[100:103]
	v_mfma_f32_16x16x32_bf16 v[96:99], v[184:187], v[206:209], v[96:99]
	v_mfma_f32_16x16x32_bf16 v[84:87], v[172:175], v[214:217], v[84:87]
	v_mfma_f32_16x16x32_bf16 v[80:83], v[184:187], v[214:217], v[80:83]
	v_mfma_f32_16x16x32_bf16 v[68:71], v[172:175], v[222:225], v[68:71]
	v_mfma_f32_16x16x32_bf16 v[64:67], v[184:187], v[222:225], v[64:67]
	v_mfma_f32_16x16x32_bf16 v[116:119], v[180:183], v[202:205], v[116:119]
	v_mfma_f32_16x16x32_bf16 v[112:115], v[188:191], v[202:205], v[112:115]
	v_mfma_f32_16x16x32_bf16 v[100:103], v[180:183], v[210:213], v[100:103]
	v_mfma_f32_16x16x32_bf16 v[96:99], v[188:191], v[210:213], v[96:99]
	v_mfma_f32_16x16x32_bf16 v[84:87], v[180:183], v[218:221], v[84:87]
	v_mfma_f32_16x16x32_bf16 v[80:83], v[188:191], v[218:221], v[80:83]
	v_mfma_f32_16x16x32_bf16 v[68:71], v[180:183], v[226:229], v[68:71]
	v_mfma_f32_16x16x32_bf16 v[64:67], v[188:191], v[226:229], v[64:67]
	s_setprio 0
	s_barrier
; #define PG8_STAGE(bufoff, gbase, voff) do { _Pragma("unroll") for (int _i = 0; _i < 2; ++_i) \
;         __builtin_amdgcn_global_load_lds((const unsigned*)((const char*)(gbase) + (voff)[_i]), (PG8_LAS unsigned*)(lds + (bufoff) + ldsw + _i * 8192), 16, 0, 0); } while (0)
; #define PG8_LDA(dst, b, h) do { _Pragma("unroll") for (int m = 0; m < 4; ++m) _Pragma("unroll") for (int k = 0; k < 2; ++k) dst[m][k] = *(const PG8_LAS bf16x8*)(lds + PG8_SA(b, h) + aoff + m * 2048 + k * 1024); } while (0)
; #define PG8_MMA(ai, bj, At, Bt) do { __builtin_amdgcn_s_setprio(1); _Pragma("unroll") for (int m = 0; m < 4; ++m) _Pragma("unroll") for (int n = 0; n < 2; ++n) _Pragma("unroll") for (int k = 0; k < 2; ++k) \
;         acc[ai][bj][m][n] = __builtin_amdgcn_mfma_f32_16x16x32_bf16(Bt[n][k], At[m][k], acc[ai][bj][m][n], 0, 0, 0); __builtin_amdgcn_s_setprio(0); } while (0)
; #define PG8_WAIT_V(n) asm volatile("s_waitcnt vmcnt(" #n ")" ::: "memory")
; #define PG8_WAIT_L(n) asm volatile("s_waitcnt lgkmcnt(" #n ")" ::: "memory")
; #define PG8_BAR __builtin_amdgcn_s_barrier()
; #define PG8_SCHED __builtin_amdgcn_sched_barrier(0)
; template <class Epi, class Sched, bool ALIGN_EPI = false, bool SP2 = false>
; __device__ __forceinline__ void gemm_phase(PG8_LAS unsigned char* lds, const Gemm g, const Sched& S, const Epi& E, int wave_in) {
;     ...
;             PG8_WAIT_V(8); PG8_WAIT_L(0); PG8_BAR; PG8_MMA(0, 0, At, B0); PG8_MMA(0, 1, At, B1); PG8_BAR; PG8_SCHED;
;             PG8_LDA(At, 1, 1); PG8_STAGE(PG8_SB(1, 0), b3, voffB); PG8_STAGE(PG8_SB(1, 1), b3 + hstep, voffB); PG8_STAGE(PG8_SA(1, 0), a3, voffA);
;             PG8_WAIT_V(8); PG8_WAIT_L(0); PG8_BAR; PG8_MMA(1, 0, At, B0); PG8_MMA(1, 1, At, B1); PG8_BAR; PG8_SCHED;
	s_add_i32 s10, s42, s66
	v_lshl_add_u64 v[230:231], v[230:231], 0, s[88:89]
	s_mov_b32 m0, s10
	ds_read_b128 v[198:201], v179 offset:49152
	ds_read_b128 v[202:205], v179 offset:50176
	ds_read_b128 v[206:209], v179 offset:51200
	ds_read_b128 v[210:213], v179 offset:52224
	ds_read_b128 v[214:217], v179 offset:53248
	ds_read_b128 v[218:221], v179 offset:54272
	ds_read_b128 v[222:225], v179 offset:55296
	ds_read_b128 v[226:229], v179 offset:56320
	global_load_lds_dwordx4 v[230:231], off
	s_add_i32 m0, s10, 0x2000
	s_add_u32 s4, s4, 0x40080
	v_lshl_add_u64 v[230:231], v[232:233], 0, s[88:89]
	s_addc_u32 s5, s5, 0
	s_add_i32 s10, s43, s66
	global_load_lds_dwordx4 v[230:231], off
	v_lshl_add_u64 v[230:231], s[4:5], 0, v[132:133]
	s_mov_b32 m0, s10
	s_nop 0
	global_load_lds_dwordx4 v[230:231], off
	v_lshl_add_u64 v[230:231], s[4:5], 0, v[128:129]
	s_add_i32 m0, s10, 0x2000
	s_nop 0
	global_load_lds_dwordx4 v[230:231], off
	v_lshl_add_u64 v[230:231], v[234:235], 0, s[88:89]
	s_mov_b32 m0, s72
	s_nop 0
	global_load_lds_dwordx4 v[230:231], off
	v_lshl_add_u64 v[230:231], v[236:237], 0, s[88:89]
	s_mov_b32 m0, s73
	s_nop 0
	global_load_lds_dwordx4 v[230:231], off
	s_waitcnt vmcnt(8)
	s_waitcnt lgkmcnt(0)
	s_barrier
	s_setprio 1
	s_waitcnt lgkmcnt(0)
	v_mfma_f32_16x16x32_bf16 v[60:63], v[156:159], v[198:201], v[60:63]
	v_mfma_f32_16x16x32_bf16 v[56:59], v[164:167], v[198:201], v[56:59]
	v_mfma_f32_16x16x32_bf16 v[44:47], v[156:159], v[206:209], v[44:47]
	v_mfma_f32_16x16x32_bf16 v[40:43], v[164:167], v[206:209], v[40:43]
	v_mfma_f32_16x16x32_bf16 v[28:31], v[156:159], v[214:217], v[28:31]
	v_mfma_f32_16x16x32_bf16 v[24:27], v[164:167], v[214:217], v[24:27]
	v_mfma_f32_16x16x32_bf16 v[12:15], v[156:159], v[222:225], v[12:15]
	v_mfma_f32_16x16x32_bf16 v[8:11], v[164:167], v[222:225], v[8:11]
	v_mfma_f32_16x16x32_bf16 v[60:63], v[160:163], v[202:205], v[60:63]
	v_mfma_f32_16x16x32_bf16 v[56:59], v[168:171], v[202:205], v[56:59]
	v_mfma_f32_16x16x32_bf16 v[44:47], v[160:163], v[210:213], v[44:47]
	v_mfma_f32_16x16x32_bf16 v[40:43], v[168:171], v[210:213], v[40:43]
	v_mfma_f32_16x16x32_bf16 v[28:31], v[160:163], v[218:221], v[28:31]
	v_mfma_f32_16x16x32_bf16 v[24:27], v[168:171], v[218:221], v[24:27]
	v_mfma_f32_16x16x32_bf16 v[12:15], v[160:163], v[226:229], v[12:15]
	v_mfma_f32_16x16x32_bf16 v[8:11], v[168:171], v[226:229], v[8:11]
	s_setprio 0
	s_setprio 1
	v_mfma_f32_16x16x32_bf16 v[52:55], v[172:175], v[198:201], v[52:55]
	v_mfma_f32_16x16x32_bf16 v[48:51], v[184:187], v[198:201], v[48:51]
	v_mfma_f32_16x16x32_bf16 v[36:39], v[172:175], v[206:209], v[36:39]
	v_mfma_f32_16x16x32_bf16 v[32:35], v[184:187], v[206:209], v[32:35]
	v_mfma_f32_16x16x32_bf16 v[20:23], v[172:175], v[214:217], v[20:23]
	v_mfma_f32_16x16x32_bf16 v[16:19], v[184:187], v[214:217], v[16:19]
	v_mfma_f32_16x16x32_bf16 v[4:7], v[172:175], v[222:225], v[4:7]
	v_mfma_f32_16x16x32_bf16 v[0:3], v[184:187], v[222:225], v[0:3]
	v_mfma_f32_16x16x32_bf16 v[52:55], v[180:183], v[202:205], v[52:55]
	v_mfma_f32_16x16x32_bf16 v[48:51], v[188:191], v[202:205], v[48:51]
	v_mfma_f32_16x16x32_bf16 v[36:39], v[180:183], v[210:213], v[36:39]
	v_mfma_f32_16x16x32_bf16 v[32:35], v[188:191], v[210:213], v[32:35]
	v_mfma_f32_16x16x32_bf16 v[20:23], v[180:183], v[218:221], v[20:23]
	v_mfma_f32_16x16x32_bf16 v[16:19], v[188:191], v[218:221], v[16:19]
	v_mfma_f32_16x16x32_bf16 v[4:7], v[180:183], v[226:229], v[4:7]
	v_mfma_f32_16x16x32_bf16 v[0:3], v[188:191], v[226:229], v[0:3]
	s_setprio 0
	s_barrier
	s_add_i32 s34, s34, 2
	s_add_u32 s31, s31, 0x100
	s_addc_u32 s33, s33, 0
	s_add_u32 s0, s0, 0x100
	s_addc_u32 s1, s1, 0
	s_cmp_gt_u32 s34, 13
	s_cbranch_scc1 .Lkexit_1
	.p2alignl 6, 3212836864

; #define PG8_STAGE(bufoff, gbase, voff) do { _Pragma("unroll") for (int _i = 0; _i < 2; ++_i) \
;         __builtin_amdgcn_global_load_lds((const unsigned*)((const char*)(gbase) + (voff)[_i]), (PG8_LAS unsigned*)(lds + (bufoff) + ldsw + _i * 8192), 16, 0, 0); } while (0)
; #define PG8_LDA(dst, b, h) do { _Pragma("unroll") for (int m = 0; m < 4; ++m) _Pragma("unroll") for (int k = 0; k < 2; ++k) dst[m][k] = *(const PG8_LAS bf16x8*)(lds + PG8_SA(b, h) + aoff + m * 2048 + k * 1024); } while (0)
; #define PG8_LDB(dst, b, h) do { _Pragma("unroll") for (int n = 0; n < 2; ++n) _Pragma("unroll") for (int k = 0; k < 2; ++k) dst[n][k] = *(const PG8_LAS bf16x8*)(lds + PG8_SB(b, h) + boff + n * 2048 + k * 1024); } while (0)
; #define PG8_MMA(ai, bj, At, Bt) do { __builtin_amdgcn_s_setprio(1); _Pragma("unroll") for (int m = 0; m < 4; ++m) _Pragma("unroll") for (int n = 0; n < 2; ++n) _Pragma("unroll") for (int k = 0; k < 2; ++k) \
;         acc[ai][bj][m][n] = __builtin_amdgcn_mfma_f32_16x16x32_bf16(Bt[n][k], At[m][k], acc[ai][bj][m][n], 0, 0, 0); __builtin_amdgcn_s_setprio(0); } while (0)
; template <class Epi, class Sched, bool ALIGN_EPI = false, bool SP2 = false>
; __device__ __forceinline__ void gemm_phase(PG8_LAS unsigned char* lds, const Gemm g, const Sched& S, const Epi& E, int wave_in) {
;     ...
;         const char* nA = has_next ? (const char*)g.A + (size_t)(nxt.pm >> g.ash) * g.astride + (size_t)nxt.pm * tstep : cA; const char* nB = has_next ? (const char*)g.Bt + (size_t)(nxt.pm >> g.bsh) * g.bstride + (size_t)nxt.pn * tstep : cB;
;         for (int t = 0; t < nt; t += 2) {
;             const bool last = (t == nt - 2);
;             const char* a1 = cA + (size_t)(t + 1) * kstep;
;             const char* a2 = last ? nA : cA + (size_t)(t + 2) * kstep; const char* b2 = last ? nB : cB + (size_t)(t + 2) * kstep;
;             const char* a3 = a2 + kstep; const char* b3 = b2 + kstep;
;             if (last && has_next) S.a_ready(nxt);
;             if constexpr (SP2) {
;             PG8_LDB(B0, 0, 0); PG8_LDB(B1, 0, 1); PG8_SCHED; PG8_LDA(At, 0, 0); PG8_STAGE(PG8_SA(1, 1), a1 + hstep, voffA);
;             PG8_WAIT_V(8); PG8_WAIT_L(0); PG8_BAR; PG8_MMA(0, 0, At, B0); PG8_MMA(0, 1, At, B1); PG8_BAR; PG8_SCHED;
;             PG8_LDA(At, 0, 1); PG8_STAGE(PG8_SB(0, 0), b2, voffB); PG8_STAGE(PG8_SB(0, 1), b2 + hstep, voffB); PG8_STAGE(PG8_SA(0, 0), a2, voffA);
.LBB0_484:
	s_ashr_i32 s15, s14, 31
	s_lshl_b64 s[16:17], s[14:15], 17
	s_add_u32 s16, s47, s16
	s_addc_u32 s17, s46, s17
	s_and_b64 s[18:19], s[10:11], exec
	s_cselect_b32 s15, s17, s25
	s_cselect_b32 s21, s16, s24
	s_ashr_i32 s13, s12, 31
	s_lshl_b64 s[18:19], s[12:13], 17
	s_add_u32 s18, s63, s18
	s_addc_u32 s19, s62, s19
	s_and_b64 s[38:39], s[10:11], exec
	s_cselect_b32 s13, s19, s23
	s_cselect_b32 s27, s18, s22
	s_mov_b32 s34, 0
	s_mov_b64 s[38:39], -1
	s_mov_b64 s[40:41], 0
	.p2alignl 3, 3212836864
	s_add_u32 s53, s24, s34
	s_addc_u32 s66, s25, 0
	s_add_u32 s44, s53, 0x100
	s_addc_u32 s45, s66, 0
	s_and_b64 s[42:43], s[40:41], exec
	s_cselect_b32 s45, s15, s45
	s_cselect_b32 s44, s21, s44
	s_add_u32 s34, s22, s34
	s_addc_u32 s42, s23, 0
	s_add_u32 s34, s34, 0x100
	s_addc_u32 s42, s42, 0
	s_add_i32 s97, s35, 0x100
	s_and_b64 s[40:41], s[40:41], exec
	s_cselect_b32 s61, s13, s42
	s_cselect_b32 s60, s27, s34
	s_add_i32 s41, s90, 0x100
	s_add_u32 s76, s53, 0x10080
	s_addc_u32 s77, s66, 0
	s_add_i32 s96, s97, s72
	s_add_i32 m0, s75, 0xc000
	s_add_i32 vcc_hi, s75, 0xe000
	s_add_i32 s81, s96, 0x2000
	s_add_u32 s66, s60, 0x10000
	v_add_u32_e32 v166, s97, v152
	v_add_u32_e32 v182, s41, v152
	s_addc_u32 s67, s61, 0
	s_add_i32 s95, s41, s72
	ds_read_b128 v[154:157], v166
	ds_read_b128 v[158:161], v166 offset:1024
	ds_read_b128 v[162:165], v166 offset:2048
	ds_read_b128 v[166:169], v166 offset:3072
	ds_read_b128 v[170:173], v182
	ds_read_b128 v[174:177], v182 offset:1024
	ds_read_b128 v[178:181], v182 offset:2048
	ds_read_b128 v[182:185], v182 offset:3072
	s_add_i32 s94, s95, 0x2000
	s_add_i32 s71, s65, 0x100
	s_add_i32 s69, s52, 0x100
	s_add_u32 s42, s44, 0x10000
	s_addc_u32 s43, s45, 0
	s_add_i32 s53, s71, s72
	s_add_i32 s34, s53, 0x2000
	s_add_u32 s40, s60, 0x10080
	s_addc_u32 s41, s61, 0
	s_add_i32 vcc_lo, s69, s72
	s_add_i32 s97, vcc_lo, 0x2000
	v_lshl_add_u64 v[190:191], s[76:77], 0, v[134:135]
	ds_read_b128 v[186:189], v153
	ds_read_b128 v[198:201], v153 offset:1024
	ds_read_b128 v[202:205], v153 offset:2048
	ds_read_b128 v[206:209], v153 offset:3072
	ds_read_b128 v[210:213], v153 offset:4096
	ds_read_b128 v[214:217], v153 offset:5120
	ds_read_b128 v[218:221], v153 offset:6144
	ds_read_b128 v[222:225], v153 offset:7168
	global_load_lds_dwordx4 v[190:191], off
	v_lshl_add_u64 v[190:191], s[76:77], 0, v[130:131]
	s_mov_b32 m0, vcc_hi
	s_nop 0
	global_load_lds_dwordx4 v[190:191], off
	s_waitcnt vmcnt(8)
	s_waitcnt lgkmcnt(0)
	s_barrier
	s_setprio 1
	s_waitcnt lgkmcnt(0)
	v_mfma_f32_16x16x32_bf16 v[124:127], v[154:157], v[186:189], 0
	v_mfma_f32_16x16x32_bf16 v[120:123], v[162:165], v[186:189], 0
	v_mfma_f32_16x16x32_bf16 v[116:119], v[154:157], v[202:205], 0
	v_mfma_f32_16x16x32_bf16 v[108:111], v[162:165], v[202:205], 0
	v_mfma_f32_16x16x32_bf16 v[100:103], v[154:157], v[210:213], 0
	v_mfma_f32_16x16x32_bf16 v[92:95], v[162:165], v[210:213], 0
	v_mfma_f32_16x16x32_bf16 v[84:87], v[154:157], v[218:221], 0
	v_mfma_f32_16x16x32_bf16 v[76:79], v[162:165], v[218:221], 0
	v_mfma_f32_16x16x32_bf16 v[124:127], v[158:161], v[198:201], v[124:127]
	v_mfma_f32_16x16x32_bf16 v[120:123], v[166:169], v[198:201], v[120:123]
	v_mfma_f32_16x16x32_bf16 v[116:119], v[158:161], v[206:209], v[116:119]
	v_mfma_f32_16x16x32_bf16 v[108:111], v[166:169], v[206:209], v[108:111]
	v_mfma_f32_16x16x32_bf16 v[100:103], v[158:161], v[214:217], v[100:103]
	v_mfma_f32_16x16x32_bf16 v[92:95], v[166:169], v[214:217], v[92:95]
	v_mfma_f32_16x16x32_bf16 v[84:87], v[158:161], v[222:225], v[84:87]
	v_mfma_f32_16x16x32_bf16 v[76:79], v[166:169], v[222:225], v[76:79]
	s_setprio 0
	s_setprio 1
	v_mfma_f32_16x16x32_bf16 v[112:115], v[170:173], v[186:189], 0
	v_mfma_f32_16x16x32_bf16 v[104:107], v[178:181], v[186:189], 0
	v_mfma_f32_16x16x32_bf16 v[96:99], v[170:173], v[202:205], 0
	v_mfma_f32_16x16x32_bf16 v[88:91], v[178:181], v[202:205], 0
	v_mfma_f32_16x16x32_bf16 v[80:83], v[170:173], v[210:213], 0
	v_mfma_f32_16x16x32_bf16 v[72:75], v[178:181], v[210:213], 0
	v_mfma_f32_16x16x32_bf16 v[68:71], v[170:173], v[218:221], 0
	v_mfma_f32_16x16x32_bf16 v[64:67], v[178:181], v[218:221], 0
	v_mfma_f32_16x16x32_bf16 v[112:115], v[174:177], v[198:201], v[112:115]
	v_mfma_f32_16x16x32_bf16 v[104:107], v[182:185], v[198:201], v[104:107]
	v_mfma_f32_16x16x32_bf16 v[96:99], v[174:177], v[206:209], v[96:99]
	v_mfma_f32_16x16x32_bf16 v[88:91], v[182:185], v[206:209], v[88:91]
	v_mfma_f32_16x16x32_bf16 v[80:83], v[174:177], v[214:217], v[80:83]
	v_mfma_f32_16x16x32_bf16 v[72:75], v[182:185], v[214:217], v[72:75]
	v_mfma_f32_16x16x32_bf16 v[68:71], v[174:177], v[222:225], v[68:71]
	v_mfma_f32_16x16x32_bf16 v[64:67], v[182:185], v[222:225], v[64:67]
	s_setprio 0
	s_barrier
	s_mov_b32 m0, s96
	v_lshl_add_u64 v[190:191], s[60:61], 0, v[132:133]
	ds_read_b128 v[186:189], v153 offset:16384
	ds_read_b128 v[198:201], v153 offset:17408
	ds_read_b128 v[202:205], v153 offset:18432
	ds_read_b128 v[206:209], v153 offset:19456
	ds_read_b128 v[210:213], v153 offset:20480
	ds_read_b128 v[214:217], v153 offset:21504
	ds_read_b128 v[218:221], v153 offset:22528
	ds_read_b128 v[222:225], v153 offset:23552
	global_load_lds_dwordx4 v[190:191], off
	v_lshl_add_u64 v[226:227], s[60:61], 0, v[128:129]
	s_mov_b32 m0, s81
	v_lshl_add_u64 v[228:229], s[66:67], 0, v[132:133]
	global_load_lds_dwordx4 v[226:227], off
	s_mov_b32 m0, s95
	v_lshl_add_u64 v[230:231], s[44:45], 0, v[130:131]
	global_load_lds_dwordx4 v[228:229], off
	v_lshl_add_u64 v[228:229], s[66:67], 0, v[128:129]
	s_mov_b32 m0, s94
	s_nop 0
	global_load_lds_dwordx4 v[228:229], off
	v_lshl_add_u64 v[228:229], s[44:45], 0, v[134:135]
	s_mov_b32 m0, s75
	s_nop 0
	global_load_lds_dwordx4 v[228:229], off
	s_mov_b32 m0, s78
	s_nop 0
	global_load_lds_dwordx4 v[230:231], off
	s_waitcnt vmcnt(8)
	s_waitcnt lgkmcnt(0)
	s_barrier
; #define PG8_STAGE(bufoff, gbase, voff) do { _Pragma("unroll") for (int _i = 0; _i < 2; ++_i) \
;         __builtin_amdgcn_global_load_lds((const unsigned*)((const char*)(gbase) + (voff)[_i]), (PG8_LAS unsigned*)(lds + (bufoff) + ldsw + _i * 8192), 16, 0, 0); } while (0)
; #define PG8_LDA(dst, b, h) do { _Pragma("unroll") for (int m = 0; m < 4; ++m) _Pragma("unroll") for (int k = 0; k < 2; ++k) dst[m][k] = *(const PG8_LAS bf16x8*)(lds + PG8_SA(b, h) + aoff + m * 2048 + k * 1024); } while (0)
; #define PG8_LDB(dst, b, h) do { _Pragma("unroll") for (int n = 0; n < 2; ++n) _Pragma("unroll") for (int k = 0; k < 2; ++k) dst[n][k] = *(const PG8_LAS bf16x8*)(lds + PG8_SB(b, h) + boff + n * 2048 + k * 1024); } while (0)
; #define PG8_MMA(ai, bj, At, Bt) do { __builtin_amdgcn_s_setprio(1); _Pragma("unroll") for (int m = 0; m < 4; ++m) _Pragma("unroll") for (int n = 0; n < 2; ++n) _Pragma("unroll") for (int k = 0; k < 2; ++k) \
;         acc[ai][bj][m][n] = __builtin_amdgcn_mfma_f32_16x16x32_bf16(Bt[n][k], At[m][k], acc[ai][bj][m][n], 0, 0, 0); __builtin_amdgcn_s_setprio(0); } while (0)
; #define PG8_WAIT_V(n) asm volatile("s_waitcnt vmcnt(" #n ")" ::: "memory")
; #define PG8_WAIT_L(n) asm volatile("s_waitcnt lgkmcnt(" #n ")" ::: "memory")
; #define PG8_BAR __builtin_amdgcn_s_barrier()
; #define PG8_SCHED __builtin_amdgcn_sched_barrier(0)
; template <class Epi, class Sched, bool ALIGN_EPI = false, bool SP2 = false>
; __device__ __forceinline__ void gemm_phase(PG8_LAS unsigned char* lds, const Gemm g, const Sched& S, const Epi& E, int wave_in) {
;     ...
;             PG8_LDA(At, 0, 1); PG8_STAGE(PG8_SB(0, 0), b2, voffB); PG8_STAGE(PG8_SB(0, 1), b2 + hstep, voffB); PG8_STAGE(PG8_SA(0, 0), a2, voffA);
;             PG8_WAIT_V(8); PG8_WAIT_L(0); PG8_BAR; PG8_MMA(1, 0, At, B0); PG8_MMA(1, 1, At, B1); PG8_BAR; PG8_SCHED;
;             PG8_LDB(B0, 1, 0); PG8_LDB(B1, 1, 1); PG8_SCHED; PG8_LDA(At, 1, 0); PG8_STAGE(PG8_SA(0, 1), a2 + hstep, voffA);
;             PG8_WAIT_V(8); PG8_WAIT_L(0); PG8_BAR; PG8_MMA(0, 0, At, B0); PG8_MMA(0, 1, At, B1); PG8_BAR; PG8_SCHED;
	s_setprio 1
	s_waitcnt lgkmcnt(0)
	v_mfma_f32_16x16x32_bf16 v[60:63], v[154:157], v[186:189], 0
	v_mfma_f32_16x16x32_bf16 v[56:59], v[162:165], v[186:189], 0
	v_mfma_f32_16x16x32_bf16 v[52:55], v[154:157], v[202:205], 0
	v_mfma_f32_16x16x32_bf16 v[44:47], v[162:165], v[202:205], 0
	v_mfma_f32_16x16x32_bf16 v[36:39], v[154:157], v[210:213], 0
	v_mfma_f32_16x16x32_bf16 v[28:31], v[162:165], v[210:213], 0
	v_mfma_f32_16x16x32_bf16 v[20:23], v[154:157], v[218:221], 0
	v_mfma_f32_16x16x32_bf16 v[12:15], v[162:165], v[218:221], 0
	v_mfma_f32_16x16x32_bf16 v[60:63], v[158:161], v[198:201], v[60:63]
	v_mfma_f32_16x16x32_bf16 v[56:59], v[166:169], v[198:201], v[56:59]
	v_mfma_f32_16x16x32_bf16 v[52:55], v[158:161], v[206:209], v[52:55]
	v_mfma_f32_16x16x32_bf16 v[44:47], v[166:169], v[206:209], v[44:47]
	v_mfma_f32_16x16x32_bf16 v[36:39], v[158:161], v[214:217], v[36:39]
	v_mfma_f32_16x16x32_bf16 v[28:31], v[166:169], v[214:217], v[28:31]
	v_mfma_f32_16x16x32_bf16 v[20:23], v[158:161], v[222:225], v[20:23]
	v_mfma_f32_16x16x32_bf16 v[12:15], v[166:169], v[222:225], v[12:15]
	s_setprio 0
	s_setprio 1
	v_mfma_f32_16x16x32_bf16 v[48:51], v[170:173], v[186:189], 0
	v_mfma_f32_16x16x32_bf16 v[40:43], v[178:181], v[186:189], 0
	v_mfma_f32_16x16x32_bf16 v[32:35], v[170:173], v[202:205], 0
	v_mfma_f32_16x16x32_bf16 v[24:27], v[178:181], v[202:205], 0
	v_mfma_f32_16x16x32_bf16 v[16:19], v[170:173], v[210:213], 0
	v_mfma_f32_16x16x32_bf16 v[8:11], v[178:181], v[210:213], 0
	v_mfma_f32_16x16x32_bf16 v[4:7], v[170:173], v[218:221], 0
	v_mfma_f32_16x16x32_bf16 v[0:3], v[178:181], v[218:221], 0
	v_mfma_f32_16x16x32_bf16 v[48:51], v[174:177], v[198:201], v[48:51]
	v_mfma_f32_16x16x32_bf16 v[40:43], v[182:185], v[198:201], v[40:43]
	v_mfma_f32_16x16x32_bf16 v[32:35], v[174:177], v[206:209], v[32:35]
	v_mfma_f32_16x16x32_bf16 v[24:27], v[182:185], v[206:209], v[24:27]
	v_mfma_f32_16x16x32_bf16 v[16:19], v[174:177], v[214:217], v[16:19]
	v_mfma_f32_16x16x32_bf16 v[8:11], v[182:185], v[214:217], v[8:11]
	v_mfma_f32_16x16x32_bf16 v[4:7], v[174:177], v[222:225], v[4:7]
	v_mfma_f32_16x16x32_bf16 v[0:3], v[182:185], v[222:225], v[0:3]
	s_setprio 0
	s_barrier
	v_add_u32_e32 v166, s71, v152
	v_add_u32_e32 v182, s69, v152
	ds_read_b128 v[154:157], v166
	ds_read_b128 v[158:161], v166 offset:1024
	ds_read_b128 v[162:165], v166 offset:2048
	ds_read_b128 v[166:169], v166 offset:3072
	ds_read_b128 v[170:173], v182
	ds_read_b128 v[174:177], v182 offset:1024
	ds_read_b128 v[178:181], v182 offset:2048
	ds_read_b128 v[182:185], v182 offset:3072
	s_mov_b32 m0, s79
	v_lshl_add_u64 v[232:233], s[42:43], 0, v[134:135]
	ds_read_b128 v[186:189], v153 offset:32768
	ds_read_b128 v[198:201], v153 offset:33792
	ds_read_b128 v[202:205], v153 offset:34816
	ds_read_b128 v[206:209], v153 offset:35840
	ds_read_b128 v[210:213], v153 offset:36864
	ds_read_b128 v[214:217], v153 offset:37888
	ds_read_b128 v[218:221], v153 offset:38912
	ds_read_b128 v[222:225], v153 offset:39936
	global_load_lds_dwordx4 v[232:233], off
	v_lshl_add_u64 v[232:233], s[42:43], 0, v[130:131]
	s_mov_b32 m0, s82
	s_nop 0
	global_load_lds_dwordx4 v[232:233], off
	s_waitcnt vmcnt(8)
	s_waitcnt lgkmcnt(0)
	s_barrier
	s_setprio 1
	s_waitcnt lgkmcnt(0)
	v_mfma_f32_16x16x32_bf16 v[124:127], v[154:157], v[186:189], v[124:127]
	v_mfma_f32_16x16x32_bf16 v[120:123], v[162:165], v[186:189], v[120:123]
	v_mfma_f32_16x16x32_bf16 v[116:119], v[154:157], v[202:205], v[116:119]
	v_mfma_f32_16x16x32_bf16 v[108:111], v[162:165], v[202:205], v[108:111]
	v_mfma_f32_16x16x32_bf16 v[100:103], v[154:157], v[210:213], v[100:103]
	v_mfma_f32_16x16x32_bf16 v[92:95], v[162:165], v[210:213], v[92:95]
	v_mfma_f32_16x16x32_bf16 v[84:87], v[154:157], v[218:221], v[84:87]
	v_mfma_f32_16x16x32_bf16 v[76:79], v[162:165], v[218:221], v[76:79]
	v_mfma_f32_16x16x32_bf16 v[124:127], v[158:161], v[198:201], v[124:127]
	v_mfma_f32_16x16x32_bf16 v[120:123], v[166:169], v[198:201], v[120:123]
	v_mfma_f32_16x16x32_bf16 v[116:119], v[158:161], v[206:209], v[116:119]
	v_mfma_f32_16x16x32_bf16 v[108:111], v[166:169], v[206:209], v[108:111]
	v_mfma_f32_16x16x32_bf16 v[100:103], v[158:161], v[214:217], v[100:103]
	v_mfma_f32_16x16x32_bf16 v[92:95], v[166:169], v[214:217], v[92:95]
	v_mfma_f32_16x16x32_bf16 v[84:87], v[158:161], v[222:225], v[84:87]
	v_mfma_f32_16x16x32_bf16 v[76:79], v[166:169], v[222:225], v[76:79]
	s_setprio 0
	s_setprio 1
	v_mfma_f32_16x16x32_bf16 v[112:115], v[170:173], v[186:189], v[112:115]
	v_mfma_f32_16x16x32_bf16 v[104:107], v[178:181], v[186:189], v[104:107]
	v_mfma_f32_16x16x32_bf16 v[96:99], v[170:173], v[202:205], v[96:99]
	v_mfma_f32_16x16x32_bf16 v[88:91], v[178:181], v[202:205], v[88:91]
	v_mfma_f32_16x16x32_bf16 v[80:83], v[170:173], v[210:213], v[80:83]
	v_mfma_f32_16x16x32_bf16 v[72:75], v[178:181], v[210:213], v[72:75]
	v_mfma_f32_16x16x32_bf16 v[68:71], v[170:173], v[218:221], v[68:71]
	v_mfma_f32_16x16x32_bf16 v[64:67], v[178:181], v[218:221], v[64:67]
	v_mfma_f32_16x16x32_bf16 v[112:115], v[174:177], v[198:201], v[112:115]
	v_mfma_f32_16x16x32_bf16 v[104:107], v[182:185], v[198:201], v[104:107]
	v_mfma_f32_16x16x32_bf16 v[96:99], v[174:177], v[206:209], v[96:99]
	v_mfma_f32_16x16x32_bf16 v[88:91], v[182:185], v[206:209], v[88:91]
	v_mfma_f32_16x16x32_bf16 v[80:83], v[174:177], v[214:217], v[80:83]
	v_mfma_f32_16x16x32_bf16 v[72:75], v[182:185], v[214:217], v[72:75]
	v_mfma_f32_16x16x32_bf16 v[68:71], v[174:177], v[222:225], v[68:71]
	v_mfma_f32_16x16x32_bf16 v[64:67], v[182:185], v[222:225], v[64:67]
	s_setprio 0
	s_barrier
; #define PG8_STAGE(bufoff, gbase, voff) do { _Pragma("unroll") for (int _i = 0; _i < 2; ++_i) \
;         __builtin_amdgcn_global_load_lds((const unsigned*)((const char*)(gbase) + (voff)[_i]), (PG8_LAS unsigned*)(lds + (bufoff) + ldsw + _i * 8192), 16, 0, 0); } while (0)
; #define PG8_LDA(dst, b, h) do { _Pragma("unroll") for (int m = 0; m < 4; ++m) _Pragma("unroll") for (int k = 0; k < 2; ++k) dst[m][k] = *(const PG8_LAS bf16x8*)(lds + PG8_SA(b, h) + aoff + m * 2048 + k * 1024); } while (0)
; #define PG8_MMA(ai, bj, At, Bt) do { __builtin_amdgcn_s_setprio(1); _Pragma("unroll") for (int m = 0; m < 4; ++m) _Pragma("unroll") for (int n = 0; n < 2; ++n) _Pragma("unroll") for (int k = 0; k < 2; ++k) \
;         acc[ai][bj][m][n] = __builtin_amdgcn_mfma_f32_16x16x32_bf16(Bt[n][k], At[m][k], acc[ai][bj][m][n], 0, 0, 0); __builtin_amdgcn_s_setprio(0); } while (0)
; #define PG8_WAIT_V(n) asm volatile("s_waitcnt vmcnt(" #n ")" ::: "memory")
; #define PG8_WAIT_L(n) asm volatile("s_waitcnt lgkmcnt(" #n ")" ::: "memory")
; #define PG8_BAR __builtin_amdgcn_s_barrier()
; #define PG8_SCHED __builtin_amdgcn_sched_barrier(0)
; template <class Epi, class Sched, bool ALIGN_EPI = false, bool SP2 = false>
; __device__ __forceinline__ void gemm_phase(PG8_LAS unsigned char* lds, const Gemm g, const Sched& S, const Epi& E, int wave_in) {
;     ...
;             PG8_WAIT_V(8); PG8_WAIT_L(0); PG8_BAR; PG8_MMA(0, 0, At, B0); PG8_MMA(0, 1, At, B1); PG8_BAR; PG8_SCHED;
;             PG8_LDA(At, 1, 1); PG8_STAGE(PG8_SB(1, 0), b3, voffB); PG8_STAGE(PG8_SB(1, 1), b3 + hstep, voffB); PG8_STAGE(PG8_SA(1, 0), a3, voffA);
;             PG8_WAIT_V(8); PG8_WAIT_L(0); PG8_BAR; PG8_MMA(1, 0, At, B0); PG8_MMA(1, 1, At, B1); PG8_BAR; PG8_SCHED;
	s_mov_b32 m0, s53
	v_lshl_add_u64 v[190:191], v[190:191], 0, s[88:89]
	ds_read_b128 v[186:189], v153 offset:49152
	ds_read_b128 v[198:201], v153 offset:50176
	ds_read_b128 v[202:205], v153 offset:51200
	ds_read_b128 v[206:209], v153 offset:52224
	ds_read_b128 v[210:213], v153 offset:53248
	ds_read_b128 v[214:217], v153 offset:54272
	ds_read_b128 v[218:221], v153 offset:55296
	ds_read_b128 v[222:225], v153 offset:56320
	global_load_lds_dwordx4 v[190:191], off
	v_lshl_add_u64 v[190:191], v[226:227], 0, s[88:89]
	s_mov_b32 m0, s34
	s_nop 0
	global_load_lds_dwordx4 v[190:191], off
	v_lshl_add_u64 v[190:191], s[40:41], 0, v[132:133]
	s_mov_b32 m0, vcc_lo
	s_nop 0
	global_load_lds_dwordx4 v[190:191], off
	v_lshl_add_u64 v[190:191], s[40:41], 0, v[128:129]
	s_mov_b32 m0, s97
	s_nop 0
	global_load_lds_dwordx4 v[190:191], off
	v_lshl_add_u64 v[190:191], v[228:229], 0, s[88:89]
	s_mov_b32 m0, s85
	s_nop 0
	global_load_lds_dwordx4 v[190:191], off
	v_lshl_add_u64 v[190:191], v[230:231], 0, s[88:89]
	s_mov_b32 m0, s92
	s_nop 0
	global_load_lds_dwordx4 v[190:191], off
	s_waitcnt vmcnt(8)
	s_waitcnt lgkmcnt(0)
	s_barrier
	s_setprio 1
	s_waitcnt lgkmcnt(0)
	v_mfma_f32_16x16x32_bf16 v[60:63], v[154:157], v[186:189], v[60:63]
	v_mfma_f32_16x16x32_bf16 v[56:59], v[162:165], v[186:189], v[56:59]
	v_mfma_f32_16x16x32_bf16 v[52:55], v[154:157], v[202:205], v[52:55]
	v_mfma_f32_16x16x32_bf16 v[44:47], v[162:165], v[202:205], v[44:47]
	v_mfma_f32_16x16x32_bf16 v[36:39], v[154:157], v[210:213], v[36:39]
	v_mfma_f32_16x16x32_bf16 v[28:31], v[162:165], v[210:213], v[28:31]
	v_mfma_f32_16x16x32_bf16 v[20:23], v[154:157], v[218:221], v[20:23]
	v_mfma_f32_16x16x32_bf16 v[12:15], v[162:165], v[218:221], v[12:15]
	v_mfma_f32_16x16x32_bf16 v[60:63], v[158:161], v[198:201], v[60:63]
	v_mfma_f32_16x16x32_bf16 v[56:59], v[166:169], v[198:201], v[56:59]
	v_mfma_f32_16x16x32_bf16 v[52:55], v[158:161], v[206:209], v[52:55]
	v_mfma_f32_16x16x32_bf16 v[44:47], v[166:169], v[206:209], v[44:47]
	v_mfma_f32_16x16x32_bf16 v[36:39], v[158:161], v[214:217], v[36:39]
	v_mfma_f32_16x16x32_bf16 v[28:31], v[166:169], v[214:217], v[28:31]
	v_mfma_f32_16x16x32_bf16 v[20:23], v[158:161], v[222:225], v[20:23]
	v_mfma_f32_16x16x32_bf16 v[12:15], v[166:169], v[222:225], v[12:15]
	s_setprio 0
	s_setprio 1
	v_mfma_f32_16x16x32_bf16 v[48:51], v[170:173], v[186:189], v[48:51]
	v_mfma_f32_16x16x32_bf16 v[40:43], v[178:181], v[186:189], v[40:43]
	v_mfma_f32_16x16x32_bf16 v[32:35], v[170:173], v[202:205], v[32:35]
	v_mfma_f32_16x16x32_bf16 v[24:27], v[178:181], v[202:205], v[24:27]
	v_mfma_f32_16x16x32_bf16 v[16:19], v[170:173], v[210:213], v[16:19]
	v_mfma_f32_16x16x32_bf16 v[8:11], v[178:181], v[210:213], v[8:11]
	v_mfma_f32_16x16x32_bf16 v[4:7], v[170:173], v[218:221], v[4:7]
	v_mfma_f32_16x16x32_bf16 v[0:3], v[178:181], v[218:221], v[0:3]
	v_mfma_f32_16x16x32_bf16 v[48:51], v[174:177], v[198:201], v[48:51]
	v_mfma_f32_16x16x32_bf16 v[40:43], v[182:185], v[198:201], v[40:43]
	v_mfma_f32_16x16x32_bf16 v[32:35], v[174:177], v[206:209], v[32:35]
	v_mfma_f32_16x16x32_bf16 v[24:27], v[182:185], v[206:209], v[24:27]
	v_mfma_f32_16x16x32_bf16 v[16:19], v[174:177], v[214:217], v[16:19]
	v_mfma_f32_16x16x32_bf16 v[8:11], v[182:185], v[214:217], v[8:11]
	v_mfma_f32_16x16x32_bf16 v[4:7], v[174:177], v[222:225], v[4:7]
	v_mfma_f32_16x16x32_bf16 v[0:3], v[182:185], v[222:225], v[0:3]
	s_setprio 0
	s_barrier
	s_movk_i32 s34, 0x100
	s_andn2_b64 vcc, exec, s[38:39]
	s_mov_b64 s[40:41], -1
	s_mov_b64 s[38:39], 0
	s_cbranch_vccnz .Lkexit_2
	.p2alignl 6, 3212836864

; #define PG8_STAGE(bufoff, gbase, voff) do { _Pragma("unroll") for (int _i = 0; _i < 2; ++_i) \
;         __builtin_amdgcn_global_load_lds((const unsigned*)((const char*)(gbase) + (voff)[_i]), (PG8_LAS unsigned*)(lds + (bufoff) + ldsw + _i * 8192), 16, 0, 0); } while (0)
; #define PG8_LDA(dst, b, h) do { _Pragma("unroll") for (int m = 0; m < 4; ++m) _Pragma("unroll") for (int k = 0; k < 2; ++k) dst[m][k] = *(const PG8_LAS bf16x8*)(lds + PG8_SA(b, h) + aoff + m * 2048 + k * 1024); } while (0)
; #define PG8_LDB(dst, b, h) do { _Pragma("unroll") for (int n = 0; n < 2; ++n) _Pragma("unroll") for (int k = 0; k < 2; ++k) dst[n][k] = *(const PG8_LAS bf16x8*)(lds + PG8_SB(b, h) + boff + n * 2048 + k * 1024); } while (0)
; #define PG8_MMA(ai, bj, At, Bt) do { __builtin_amdgcn_s_setprio(1); _Pragma("unroll") for (int m = 0; m < 4; ++m) _Pragma("unroll") for (int n = 0; n < 2; ++n) _Pragma("unroll") for (int k = 0; k < 2; ++k) \
;         acc[ai][bj][m][n] = __builtin_amdgcn_mfma_f32_16x16x32_bf16(Bt[n][k], At[m][k], acc[ai][bj][m][n], 0, 0, 0); __builtin_amdgcn_s_setprio(0); } while (0)
; template <class Epi, class Sched, bool ALIGN_EPI = false, bool SP2 = false>
; __device__ __forceinline__ void gemm_phase(PG8_LAS unsigned char* lds, const Gemm g, const Sched& S, const Epi& E, int wave_in) {
;     ...
;         const char* nA = has_next ? (const char*)g.A + (size_t)(nxt.pm >> g.ash) * g.astride + (size_t)nxt.pm * tstep : cA; const char* nB = has_next ? (const char*)g.Bt + (size_t)(nxt.pm >> g.bsh) * g.bstride + (size_t)nxt.pn * tstep : cB;
;         for (int t = 0; t < nt; t += 2) {
;             const bool last = (t == nt - 2);
;             const char* a1 = cA + (size_t)(t + 1) * kstep;
;             const char* a2 = last ? nA : cA + (size_t)(t + 2) * kstep; const char* b2 = last ? nB : cB + (size_t)(t + 2) * kstep;
;             const char* a3 = a2 + kstep; const char* b3 = b2 + kstep;
;             if (last && has_next) S.a_ready(nxt);
;             if constexpr (SP2) {
;             PG8_LDB(B0, 0, 0); PG8_LDB(B1, 0, 1); PG8_SCHED; PG8_LDA(At, 0, 0); PG8_STAGE(PG8_SA(1, 1), a1 + hstep, voffA);
;             PG8_WAIT_V(8); PG8_WAIT_L(0); PG8_BAR; PG8_MMA(0, 0, At, B0); PG8_MMA(0, 1, At, B1); PG8_BAR; PG8_SCHED;
;             PG8_LDA(At, 0, 1); PG8_STAGE(PG8_SB(0, 0), b2, voffB); PG8_STAGE(PG8_SB(0, 1), b2 + hstep, voffB); PG8_STAGE(PG8_SA(0, 0), a2, voffA);
.LBB0_589:
	s_ashr_i32 s15, s14, 31
	s_lshl_b64 s[20:21], s[14:15], 19
	s_add_u32 s20, s31, s20
	s_addc_u32 s21, s33, s21
	s_and_b64 s[26:27], s[44:45], exec
	s_cselect_b32 s15, s21, s23
	s_cselect_b32 s17, s20, s22
	s_add_u32 s34, s22, 0x100
	s_addc_u32 s44, s23, 0
	s_add_u32 s22, s24, 0x40080
	s_addc_u32 s23, s25, 0
	s_mov_b32 s45, -2
	.p2alignl 3, 3212836864
	s_add_u32 s24, s22, 0xfffc0080
	s_addc_u32 s25, s23, -1
	s_add_i32 s53, s35, 0x100
	s_cmp_eq_u32 s45, 12
	s_cselect_b32 s27, s19, s25
	s_cselect_b32 s26, s18, s24
	s_cselect_b32 s25, s15, s44
	s_cselect_b32 s24, s17, s34
	s_add_i32 s69, s90, 0x100
	v_add_u32_e32 v128, s53, v249
	v_add_u32_e32 v156, s69, v249
	ds_read_b128 v[112:115], v128
	ds_read_b128 v[120:123], v128 offset:1024
	ds_read_b128 v[124:127], v128 offset:2048
	ds_read_b128 v[128:131], v128 offset:3072
	ds_read_b128 v[136:139], v156
	ds_read_b128 v[140:143], v156 offset:1024
	ds_read_b128 v[144:147], v156 offset:2048
	ds_read_b128 v[156:159], v156 offset:3072
	v_lshl_add_u64 v[208:209], s[22:23], 0, v[206:207]
	s_add_i32 m0, s39, 0xc000
	ds_read_b128 v[160:163], v251
	ds_read_b128 v[164:167], v251 offset:1024
	ds_read_b128 v[168:171], v251 offset:2048
	ds_read_b128 v[172:175], v251 offset:3072
	ds_read_b128 v[176:179], v251 offset:4096
	ds_read_b128 v[180:183], v251 offset:5120
	ds_read_b128 v[184:187], v251 offset:6144
	ds_read_b128 v[188:191], v251 offset:7168
	global_load_lds_dwordx4 v[208:209], off
	v_lshl_add_u64 v[208:209], s[22:23], 0, v[204:205]
	s_add_i32 m0, s39, 0xe000
	s_nop 0
	global_load_lds_dwordx4 v[208:209], off
	s_waitcnt vmcnt(8)
	s_waitcnt lgkmcnt(0)
	s_barrier
	s_setprio 1
	s_waitcnt lgkmcnt(0)
	v_mfma_f32_16x16x32_bf16 v[152:155], v[112:115], v[160:163], 0
	v_mfma_f32_16x16x32_bf16 v[148:151], v[124:127], v[160:163], 0
	v_mfma_f32_16x16x32_bf16 v[108:111], v[112:115], v[168:171], 0
	v_mfma_f32_16x16x32_bf16 v[104:107], v[124:127], v[168:171], 0
	v_mfma_f32_16x16x32_bf16 v[92:95], v[112:115], v[176:179], 0
	v_mfma_f32_16x16x32_bf16 v[88:91], v[124:127], v[176:179], 0
	v_mfma_f32_16x16x32_bf16 v[76:79], v[112:115], v[184:187], 0
	v_mfma_f32_16x16x32_bf16 v[72:75], v[124:127], v[184:187], 0
	v_mfma_f32_16x16x32_bf16 v[152:155], v[120:123], v[164:167], v[152:155]
	v_mfma_f32_16x16x32_bf16 v[148:151], v[128:131], v[164:167], v[148:151]
	v_mfma_f32_16x16x32_bf16 v[108:111], v[120:123], v[172:175], v[108:111]
	v_mfma_f32_16x16x32_bf16 v[104:107], v[128:131], v[172:175], v[104:107]
	v_mfma_f32_16x16x32_bf16 v[92:95], v[120:123], v[180:183], v[92:95]
	v_mfma_f32_16x16x32_bf16 v[88:91], v[128:131], v[180:183], v[88:91]
	v_mfma_f32_16x16x32_bf16 v[76:79], v[120:123], v[188:191], v[76:79]
	v_mfma_f32_16x16x32_bf16 v[72:75], v[128:131], v[188:191], v[72:75]
	s_setprio 0
	s_setprio 1
	v_mfma_f32_16x16x32_bf16 v[132:135], v[136:139], v[160:163], 0
	v_mfma_f32_16x16x32_bf16 v[116:119], v[144:147], v[160:163], 0
	v_mfma_f32_16x16x32_bf16 v[100:103], v[136:139], v[168:171], 0
	v_mfma_f32_16x16x32_bf16 v[96:99], v[144:147], v[168:171], 0
	v_mfma_f32_16x16x32_bf16 v[84:87], v[136:139], v[176:179], 0
	v_mfma_f32_16x16x32_bf16 v[80:83], v[144:147], v[176:179], 0
	v_mfma_f32_16x16x32_bf16 v[68:71], v[136:139], v[184:187], 0
	v_mfma_f32_16x16x32_bf16 v[64:67], v[144:147], v[184:187], 0
	v_mfma_f32_16x16x32_bf16 v[132:135], v[140:143], v[164:167], v[132:135]
	v_mfma_f32_16x16x32_bf16 v[116:119], v[156:159], v[164:167], v[116:119]
	v_mfma_f32_16x16x32_bf16 v[100:103], v[140:143], v[172:175], v[100:103]
	v_mfma_f32_16x16x32_bf16 v[96:99], v[156:159], v[172:175], v[96:99]
	v_mfma_f32_16x16x32_bf16 v[84:87], v[140:143], v[180:183], v[84:87]
	v_mfma_f32_16x16x32_bf16 v[80:83], v[156:159], v[180:183], v[80:83]
	v_mfma_f32_16x16x32_bf16 v[68:71], v[140:143], v[188:191], v[68:71]
	v_mfma_f32_16x16x32_bf16 v[64:67], v[156:159], v[188:191], v[64:67]
	s_setprio 0
	s_barrier
	s_add_i32 s53, s53, s38
	v_lshl_add_u64 v[208:209], s[24:25], 0, v[192:193]
	s_mov_b32 m0, s53
	ds_read_b128 v[160:163], v251 offset:16384
	ds_read_b128 v[164:167], v251 offset:17408
	ds_read_b128 v[168:171], v251 offset:18432
	ds_read_b128 v[172:175], v251 offset:19456
	ds_read_b128 v[176:179], v251 offset:20480
	ds_read_b128 v[180:183], v251 offset:21504
	ds_read_b128 v[184:187], v251 offset:22528
	ds_read_b128 v[188:191], v251 offset:23552
	global_load_lds_dwordx4 v[208:209], off
	s_add_i32 m0, s53, 0x2000
	s_add_u32 s72, s24, 0x40000
	v_lshl_add_u64 v[210:211], s[24:25], 0, v[198:199]
	s_addc_u32 s73, s25, 0
	s_add_i32 s53, s69, s38
	global_load_lds_dwordx4 v[210:211], off
	v_lshl_add_u64 v[212:213], s[72:73], 0, v[192:193]
	s_mov_b32 m0, s53
	v_lshl_add_u64 v[214:215], s[26:27], 0, v[200:201]
	global_load_lds_dwordx4 v[212:213], off
	v_lshl_add_u64 v[212:213], s[72:73], 0, v[198:199]
	s_add_i32 m0, s53, 0x2000
	s_nop 0
	global_load_lds_dwordx4 v[212:213], off
	v_lshl_add_u64 v[212:213], s[26:27], 0, v[202:203]
	s_mov_b32 m0, s39
	s_nop 0
	global_load_lds_dwordx4 v[212:213], off
	s_mov_b32 m0, s46
	s_nop 0
	global_load_lds_dwordx4 v[214:215], off
	s_waitcnt vmcnt(8)
	s_waitcnt lgkmcnt(0)
	s_barrier
; #define PG8_STAGE(bufoff, gbase, voff) do { _Pragma("unroll") for (int _i = 0; _i < 2; ++_i) \
;         __builtin_amdgcn_global_load_lds((const unsigned*)((const char*)(gbase) + (voff)[_i]), (PG8_LAS unsigned*)(lds + (bufoff) + ldsw + _i * 8192), 16, 0, 0); } while (0)
; #define PG8_LDA(dst, b, h) do { _Pragma("unroll") for (int m = 0; m < 4; ++m) _Pragma("unroll") for (int k = 0; k < 2; ++k) dst[m][k] = *(const PG8_LAS bf16x8*)(lds + PG8_SA(b, h) + aoff + m * 2048 + k * 1024); } while (0)
; #define PG8_LDB(dst, b, h) do { _Pragma("unroll") for (int n = 0; n < 2; ++n) _Pragma("unroll") for (int k = 0; k < 2; ++k) dst[n][k] = *(const PG8_LAS bf16x8*)(lds + PG8_SB(b, h) + boff + n * 2048 + k * 1024); } while (0)
; #define PG8_MMA(ai, bj, At, Bt) do { __builtin_amdgcn_s_setprio(1); _Pragma("unroll") for (int m = 0; m < 4; ++m) _Pragma("unroll") for (int n = 0; n < 2; ++n) _Pragma("unroll") for (int k = 0; k < 2; ++k) \
;         acc[ai][bj][m][n] = __builtin_amdgcn_mfma_f32_16x16x32_bf16(Bt[n][k], At[m][k], acc[ai][bj][m][n], 0, 0, 0); __builtin_amdgcn_s_setprio(0); } while (0)
; #define PG8_WAIT_V(n) asm volatile("s_waitcnt vmcnt(" #n ")" ::: "memory")
; #define PG8_WAIT_L(n) asm volatile("s_waitcnt lgkmcnt(" #n ")" ::: "memory")
; #define PG8_BAR __builtin_amdgcn_s_barrier()
; #define PG8_SCHED __builtin_amdgcn_sched_barrier(0)
; template <class Epi, class Sched, bool ALIGN_EPI = false, bool SP2 = false>
; __device__ __forceinline__ void gemm_phase(PG8_LAS unsigned char* lds, const Gemm g, const Sched& S, const Epi& E, int wave_in) {
;     ...
;             PG8_LDA(At, 0, 1); PG8_STAGE(PG8_SB(0, 0), b2, voffB); PG8_STAGE(PG8_SB(0, 1), b2 + hstep, voffB); PG8_STAGE(PG8_SA(0, 0), a2, voffA);
;             PG8_WAIT_V(8); PG8_WAIT_L(0); PG8_BAR; PG8_MMA(1, 0, At, B0); PG8_MMA(1, 1, At, B1); PG8_BAR; PG8_SCHED;
;             PG8_LDB(B0, 1, 0); PG8_LDB(B1, 1, 1); PG8_SCHED; PG8_LDA(At, 1, 0); PG8_STAGE(PG8_SA(0, 1), a2 + hstep, voffA);
;             PG8_WAIT_V(8); PG8_WAIT_L(0); PG8_BAR; PG8_MMA(0, 0, At, B0); PG8_MMA(0, 1, At, B1); PG8_BAR; PG8_SCHED;
	s_setprio 1
	s_waitcnt lgkmcnt(0)
	v_mfma_f32_16x16x32_bf16 v[60:63], v[112:115], v[160:163], 0
	v_mfma_f32_16x16x32_bf16 v[56:59], v[124:127], v[160:163], 0
	v_mfma_f32_16x16x32_bf16 v[44:47], v[112:115], v[168:171], 0
	v_mfma_f32_16x16x32_bf16 v[40:43], v[124:127], v[168:171], 0
	v_mfma_f32_16x16x32_bf16 v[28:31], v[112:115], v[176:179], 0
	v_mfma_f32_16x16x32_bf16 v[24:27], v[124:127], v[176:179], 0
	v_mfma_f32_16x16x32_bf16 v[12:15], v[112:115], v[184:187], 0
	v_mfma_f32_16x16x32_bf16 v[8:11], v[124:127], v[184:187], 0
	v_mfma_f32_16x16x32_bf16 v[60:63], v[120:123], v[164:167], v[60:63]
	v_mfma_f32_16x16x32_bf16 v[56:59], v[128:131], v[164:167], v[56:59]
	v_mfma_f32_16x16x32_bf16 v[44:47], v[120:123], v[172:175], v[44:47]
	v_mfma_f32_16x16x32_bf16 v[40:43], v[128:131], v[172:175], v[40:43]
	v_mfma_f32_16x16x32_bf16 v[28:31], v[120:123], v[180:183], v[28:31]
	v_mfma_f32_16x16x32_bf16 v[24:27], v[128:131], v[180:183], v[24:27]
	v_mfma_f32_16x16x32_bf16 v[12:15], v[120:123], v[188:191], v[12:15]
	v_mfma_f32_16x16x32_bf16 v[8:11], v[128:131], v[188:191], v[8:11]
	s_setprio 0
	s_setprio 1
	v_mfma_f32_16x16x32_bf16 v[52:55], v[136:139], v[160:163], 0
	v_mfma_f32_16x16x32_bf16 v[48:51], v[144:147], v[160:163], 0
	v_mfma_f32_16x16x32_bf16 v[36:39], v[136:139], v[168:171], 0
	v_mfma_f32_16x16x32_bf16 v[32:35], v[144:147], v[168:171], 0
	v_mfma_f32_16x16x32_bf16 v[20:23], v[136:139], v[176:179], 0
	v_mfma_f32_16x16x32_bf16 v[16:19], v[144:147], v[176:179], 0
	v_mfma_f32_16x16x32_bf16 v[4:7], v[136:139], v[184:187], 0
	v_mfma_f32_16x16x32_bf16 v[0:3], v[144:147], v[184:187], 0
	v_mfma_f32_16x16x32_bf16 v[52:55], v[140:143], v[164:167], v[52:55]
	v_mfma_f32_16x16x32_bf16 v[48:51], v[156:159], v[164:167], v[48:51]
	v_mfma_f32_16x16x32_bf16 v[36:39], v[140:143], v[172:175], v[36:39]
	v_mfma_f32_16x16x32_bf16 v[32:35], v[156:159], v[172:175], v[32:35]
	v_mfma_f32_16x16x32_bf16 v[20:23], v[140:143], v[180:183], v[20:23]
	v_mfma_f32_16x16x32_bf16 v[16:19], v[156:159], v[180:183], v[16:19]
	v_mfma_f32_16x16x32_bf16 v[4:7], v[140:143], v[188:191], v[4:7]
	v_mfma_f32_16x16x32_bf16 v[0:3], v[156:159], v[188:191], v[0:3]
	s_setprio 0
	s_barrier
	s_add_i32 s53, s65, 0x100
	s_add_i32 s69, s52, 0x100
	v_add_u32_e32 v128, s53, v249
	v_add_u32_e32 v156, s69, v249
	ds_read_b128 v[112:115], v128
	ds_read_b128 v[120:123], v128 offset:1024
	ds_read_b128 v[124:127], v128 offset:2048
	ds_read_b128 v[128:131], v128 offset:3072
	ds_read_b128 v[136:139], v156
	ds_read_b128 v[140:143], v156 offset:1024
	ds_read_b128 v[144:147], v156 offset:2048
	ds_read_b128 v[156:159], v156 offset:3072
	s_add_u32 s26, s26, 0x40000
	s_addc_u32 s27, s27, 0
	s_mov_b32 m0, s47
	v_lshl_add_u64 v[216:217], s[26:27], 0, v[202:203]
	ds_read_b128 v[160:163], v251 offset:32768
	ds_read_b128 v[164:167], v251 offset:33792
	ds_read_b128 v[168:171], v251 offset:34816
	ds_read_b128 v[172:175], v251 offset:35840
	ds_read_b128 v[176:179], v251 offset:36864
	ds_read_b128 v[180:183], v251 offset:37888
	ds_read_b128 v[184:187], v251 offset:38912
	ds_read_b128 v[188:191], v251 offset:39936
	global_load_lds_dwordx4 v[216:217], off
	v_lshl_add_u64 v[216:217], s[26:27], 0, v[200:201]
	s_mov_b32 m0, s60
	s_nop 0
	global_load_lds_dwordx4 v[216:217], off
	s_waitcnt vmcnt(8)
	s_waitcnt lgkmcnt(0)
	s_barrier
	s_setprio 1
	s_waitcnt lgkmcnt(0)
	v_mfma_f32_16x16x32_bf16 v[152:155], v[112:115], v[160:163], v[152:155]
	v_mfma_f32_16x16x32_bf16 v[148:151], v[124:127], v[160:163], v[148:151]
	v_mfma_f32_16x16x32_bf16 v[108:111], v[112:115], v[168:171], v[108:111]
	v_mfma_f32_16x16x32_bf16 v[104:107], v[124:127], v[168:171], v[104:107]
	v_mfma_f32_16x16x32_bf16 v[92:95], v[112:115], v[176:179], v[92:95]
	v_mfma_f32_16x16x32_bf16 v[88:91], v[124:127], v[176:179], v[88:91]
	v_mfma_f32_16x16x32_bf16 v[76:79], v[112:115], v[184:187], v[76:79]
	v_mfma_f32_16x16x32_bf16 v[72:75], v[124:127], v[184:187], v[72:75]
	v_mfma_f32_16x16x32_bf16 v[152:155], v[120:123], v[164:167], v[152:155]
	v_mfma_f32_16x16x32_bf16 v[148:151], v[128:131], v[164:167], v[148:151]
	v_mfma_f32_16x16x32_bf16 v[108:111], v[120:123], v[172:175], v[108:111]
	v_mfma_f32_16x16x32_bf16 v[104:107], v[128:131], v[172:175], v[104:107]
	v_mfma_f32_16x16x32_bf16 v[92:95], v[120:123], v[180:183], v[92:95]
	v_mfma_f32_16x16x32_bf16 v[88:91], v[128:131], v[180:183], v[88:91]
	v_mfma_f32_16x16x32_bf16 v[76:79], v[120:123], v[188:191], v[76:79]
	v_mfma_f32_16x16x32_bf16 v[72:75], v[128:131], v[188:191], v[72:75]
	s_setprio 0
	s_setprio 1
	v_mfma_f32_16x16x32_bf16 v[132:135], v[136:139], v[160:163], v[132:135]
	v_mfma_f32_16x16x32_bf16 v[116:119], v[144:147], v[160:163], v[116:119]
	v_mfma_f32_16x16x32_bf16 v[100:103], v[136:139], v[168:171], v[100:103]
	v_mfma_f32_16x16x32_bf16 v[96:99], v[144:147], v[168:171], v[96:99]
	v_mfma_f32_16x16x32_bf16 v[84:87], v[136:139], v[176:179], v[84:87]
	v_mfma_f32_16x16x32_bf16 v[80:83], v[144:147], v[176:179], v[80:83]
	v_mfma_f32_16x16x32_bf16 v[68:71], v[136:139], v[184:187], v[68:71]
	v_mfma_f32_16x16x32_bf16 v[64:67], v[144:147], v[184:187], v[64:67]
	v_mfma_f32_16x16x32_bf16 v[132:135], v[140:143], v[164:167], v[132:135]
	v_mfma_f32_16x16x32_bf16 v[116:119], v[156:159], v[164:167], v[116:119]
	v_mfma_f32_16x16x32_bf16 v[100:103], v[140:143], v[172:175], v[100:103]
	v_mfma_f32_16x16x32_bf16 v[96:99], v[156:159], v[172:175], v[96:99]
	v_mfma_f32_16x16x32_bf16 v[84:87], v[140:143], v[180:183], v[84:87]
	v_mfma_f32_16x16x32_bf16 v[80:83], v[156:159], v[180:183], v[80:83]
	v_mfma_f32_16x16x32_bf16 v[68:71], v[140:143], v[188:191], v[68:71]
	v_mfma_f32_16x16x32_bf16 v[64:67], v[156:159], v[188:191], v[64:67]
	s_setprio 0
	s_barrier
; #define PG8_STAGE(bufoff, gbase, voff) do { _Pragma("unroll") for (int _i = 0; _i < 2; ++_i) \
;         __builtin_amdgcn_global_load_lds((const unsigned*)((const char*)(gbase) + (voff)[_i]), (PG8_LAS unsigned*)(lds + (bufoff) + ldsw + _i * 8192), 16, 0, 0); } while (0)
; #define PG8_LDA(dst, b, h) do { _Pragma("unroll") for (int m = 0; m < 4; ++m) _Pragma("unroll") for (int k = 0; k < 2; ++k) dst[m][k] = *(const PG8_LAS bf16x8*)(lds + PG8_SA(b, h) + aoff + m * 2048 + k * 1024); } while (0)
; #define PG8_MMA(ai, bj, At, Bt) do { __builtin_amdgcn_s_setprio(1); _Pragma("unroll") for (int m = 0; m < 4; ++m) _Pragma("unroll") for (int n = 0; n < 2; ++n) _Pragma("unroll") for (int k = 0; k < 2; ++k) \
;         acc[ai][bj][m][n] = __builtin_amdgcn_mfma_f32_16x16x32_bf16(Bt[n][k], At[m][k], acc[ai][bj][m][n], 0, 0, 0); __builtin_amdgcn_s_setprio(0); } while (0)
; #define PG8_WAIT_V(n) asm volatile("s_waitcnt vmcnt(" #n ")" ::: "memory")
; #define PG8_WAIT_L(n) asm volatile("s_waitcnt lgkmcnt(" #n ")" ::: "memory")
; #define PG8_BAR __builtin_amdgcn_s_barrier()
; #define PG8_SCHED __builtin_amdgcn_sched_barrier(0)
; template <class Epi, class Sched, bool ALIGN_EPI = false, bool SP2 = false>
; __device__ __forceinline__ void gemm_phase(PG8_LAS unsigned char* lds, const Gemm g, const Sched& S, const Epi& E, int wave_in) {
;     ...
;             PG8_WAIT_V(8); PG8_WAIT_L(0); PG8_BAR; PG8_MMA(0, 0, At, B0); PG8_MMA(0, 1, At, B1); PG8_BAR; PG8_SCHED;
;             PG8_LDA(At, 1, 1); PG8_STAGE(PG8_SB(1, 0), b3, voffB); PG8_STAGE(PG8_SB(1, 1), b3 + hstep, voffB); PG8_STAGE(PG8_SA(1, 0), a3, voffA);
;             PG8_WAIT_V(8); PG8_WAIT_L(0); PG8_BAR; PG8_MMA(1, 0, At, B0); PG8_MMA(1, 1, At, B1); PG8_BAR; PG8_SCHED;
	s_add_i32 s26, s53, s38
	v_lshl_add_u64 v[208:209], v[208:209], 0, s[88:89]
	s_mov_b32 m0, s26
	ds_read_b128 v[160:163], v251 offset:49152
	ds_read_b128 v[164:167], v251 offset:50176
	ds_read_b128 v[168:171], v251 offset:51200
	ds_read_b128 v[172:175], v251 offset:52224
	ds_read_b128 v[176:179], v251 offset:53248
	ds_read_b128 v[180:183], v251 offset:54272
	ds_read_b128 v[184:187], v251 offset:55296
	ds_read_b128 v[188:191], v251 offset:56320
	global_load_lds_dwordx4 v[208:209], off
	s_add_i32 m0, s26, 0x2000
	s_add_u32 s24, s24, 0x40080
	v_lshl_add_u64 v[208:209], v[210:211], 0, s[88:89]
	s_addc_u32 s25, s25, 0
	s_add_i32 s26, s69, s38
	global_load_lds_dwordx4 v[208:209], off
	v_lshl_add_u64 v[208:209], s[24:25], 0, v[192:193]
	s_mov_b32 m0, s26
	s_nop 0
	global_load_lds_dwordx4 v[208:209], off
	v_lshl_add_u64 v[208:209], s[24:25], 0, v[198:199]
	s_add_i32 m0, s26, 0x2000
	s_nop 0
	global_load_lds_dwordx4 v[208:209], off
	v_lshl_add_u64 v[208:209], v[212:213], 0, s[88:89]
	s_mov_b32 m0, s62
	s_nop 0
	global_load_lds_dwordx4 v[208:209], off
	v_lshl_add_u64 v[208:209], v[214:215], 0, s[88:89]
	s_mov_b32 m0, s63
	s_nop 0
	global_load_lds_dwordx4 v[208:209], off
	s_waitcnt vmcnt(8)
	s_waitcnt lgkmcnt(0)
	s_barrier
	s_setprio 1
	s_waitcnt lgkmcnt(0)
	v_mfma_f32_16x16x32_bf16 v[60:63], v[112:115], v[160:163], v[60:63]
	v_mfma_f32_16x16x32_bf16 v[56:59], v[124:127], v[160:163], v[56:59]
	v_mfma_f32_16x16x32_bf16 v[44:47], v[112:115], v[168:171], v[44:47]
	v_mfma_f32_16x16x32_bf16 v[40:43], v[124:127], v[168:171], v[40:43]
	v_mfma_f32_16x16x32_bf16 v[28:31], v[112:115], v[176:179], v[28:31]
	v_mfma_f32_16x16x32_bf16 v[24:27], v[124:127], v[176:179], v[24:27]
	v_mfma_f32_16x16x32_bf16 v[12:15], v[112:115], v[184:187], v[12:15]
	v_mfma_f32_16x16x32_bf16 v[8:11], v[124:127], v[184:187], v[8:11]
	v_mfma_f32_16x16x32_bf16 v[60:63], v[120:123], v[164:167], v[60:63]
	v_mfma_f32_16x16x32_bf16 v[56:59], v[128:131], v[164:167], v[56:59]
	v_mfma_f32_16x16x32_bf16 v[44:47], v[120:123], v[172:175], v[44:47]
	v_mfma_f32_16x16x32_bf16 v[40:43], v[128:131], v[172:175], v[40:43]
	v_mfma_f32_16x16x32_bf16 v[28:31], v[120:123], v[180:183], v[28:31]
	v_mfma_f32_16x16x32_bf16 v[24:27], v[128:131], v[180:183], v[24:27]
	v_mfma_f32_16x16x32_bf16 v[12:15], v[120:123], v[188:191], v[12:15]
	v_mfma_f32_16x16x32_bf16 v[8:11], v[128:131], v[188:191], v[8:11]
	s_setprio 0
	s_setprio 1
	v_mfma_f32_16x16x32_bf16 v[52:55], v[136:139], v[160:163], v[52:55]
	v_mfma_f32_16x16x32_bf16 v[48:51], v[144:147], v[160:163], v[48:51]
	v_mfma_f32_16x16x32_bf16 v[36:39], v[136:139], v[168:171], v[36:39]
	v_mfma_f32_16x16x32_bf16 v[32:35], v[144:147], v[168:171], v[32:35]
	v_mfma_f32_16x16x32_bf16 v[20:23], v[136:139], v[176:179], v[20:23]
	v_mfma_f32_16x16x32_bf16 v[16:19], v[144:147], v[176:179], v[16:19]
	v_mfma_f32_16x16x32_bf16 v[4:7], v[136:139], v[184:187], v[4:7]
	v_mfma_f32_16x16x32_bf16 v[0:3], v[144:147], v[184:187], v[0:3]
	v_mfma_f32_16x16x32_bf16 v[52:55], v[140:143], v[164:167], v[52:55]
	v_mfma_f32_16x16x32_bf16 v[48:51], v[156:159], v[164:167], v[48:51]
	v_mfma_f32_16x16x32_bf16 v[36:39], v[140:143], v[172:175], v[36:39]
	v_mfma_f32_16x16x32_bf16 v[32:35], v[156:159], v[172:175], v[32:35]
	v_mfma_f32_16x16x32_bf16 v[20:23], v[140:143], v[180:183], v[20:23]
	v_mfma_f32_16x16x32_bf16 v[16:19], v[156:159], v[180:183], v[16:19]
	v_mfma_f32_16x16x32_bf16 v[4:7], v[140:143], v[188:191], v[4:7]
	v_mfma_f32_16x16x32_bf16 v[0:3], v[156:159], v[188:191], v[0:3]
	s_setprio 0
	s_barrier
	s_add_i32 s45, s45, 2
	s_add_u32 s34, s34, 0x100
	s_addc_u32 s44, s44, 0
	s_add_u32 s22, s22, 0x100
	s_addc_u32 s23, s23, 0
	s_cmp_gt_u32 s45, 13
	s_cbranch_scc1 .Lkexit_3
	.p2alignl 6, 3212836864

; #define PG8_STAGE(bufoff, gbase, voff) do { _Pragma("unroll") for (int _i = 0; _i < 2; ++_i) \
;         __builtin_amdgcn_global_load_lds((const unsigned*)((const char*)(gbase) + (voff)[_i]), (PG8_LAS unsigned*)(lds + (bufoff) + ldsw + _i * 8192), 16, 0, 0); } while (0)
; #define PG8_LDA(dst, b, h) do { _Pragma("unroll") for (int m = 0; m < 4; ++m) _Pragma("unroll") for (int k = 0; k < 2; ++k) dst[m][k] = *(const PG8_LAS bf16x8*)(lds + PG8_SA(b, h) + aoff + m * 2048 + k * 1024); } while (0)
; #define PG8_LDB(dst, b, h) do { _Pragma("unroll") for (int n = 0; n < 2; ++n) _Pragma("unroll") for (int k = 0; k < 2; ++k) dst[n][k] = *(const PG8_LAS bf16x8*)(lds + PG8_SB(b, h) + boff + n * 2048 + k * 1024); } while (0)
; #define PG8_MMA(ai, bj, At, Bt) do { __builtin_amdgcn_s_setprio(1); _Pragma("unroll") for (int m = 0; m < 4; ++m) _Pragma("unroll") for (int n = 0; n < 2; ++n) _Pragma("unroll") for (int k = 0; k < 2; ++k) \
;         acc[ai][bj][m][n] = __builtin_amdgcn_mfma_f32_16x16x32_bf16(Bt[n][k], At[m][k], acc[ai][bj][m][n], 0, 0, 0); __builtin_amdgcn_s_setprio(0); } while (0)
; template <class Epi, class Sched, bool ALIGN_EPI = false, bool SP2 = false>
; __device__ __forceinline__ void gemm_phase(PG8_LAS unsigned char* lds, const Gemm g, const Sched& S, const Epi& E, int wave_in) {
;     ...
;         const char* nA = has_next ? (const char*)g.A + (size_t)(nxt.pm >> g.ash) * g.astride + (size_t)nxt.pm * tstep : cA; const char* nB = has_next ? (const char*)g.Bt + (size_t)(nxt.pm >> g.bsh) * g.bstride + (size_t)nxt.pn * tstep : cB;
;         for (int t = 0; t < nt; t += 2) {
;             const bool last = (t == nt - 2);
;             const char* a1 = cA + (size_t)(t + 1) * kstep;
;             const char* a2 = last ? nA : cA + (size_t)(t + 2) * kstep; const char* b2 = last ? nB : cB + (size_t)(t + 2) * kstep;
;             const char* a3 = a2 + kstep; const char* b3 = b2 + kstep;
;             if (last && has_next) S.a_ready(nxt);
;             if constexpr (SP2) {
;             PG8_LDB(B0, 0, 0); PG8_LDB(B1, 0, 1); PG8_SCHED; PG8_LDA(At, 0, 0); PG8_STAGE(PG8_SA(1, 1), a1 + hstep, voffA);
;             PG8_WAIT_V(8); PG8_WAIT_L(0); PG8_BAR; PG8_MMA(0, 0, At, B0); PG8_MMA(0, 1, At, B1); PG8_BAR; PG8_SCHED;
;             PG8_LDA(At, 0, 1); PG8_STAGE(PG8_SB(0, 0), b2, voffB); PG8_STAGE(PG8_SB(0, 1), b2 + hstep, voffB); PG8_STAGE(PG8_SA(0, 0), a2, voffA);
.LBB0_686:
	s_ashr_i32 s17, s16, 31
	s_lshl_b64 s[18:19], s[16:17], 19
	s_add_u32 s18, s8, s18
	s_addc_u32 s19, s9, s19
	s_and_b64 s[20:21], s[42:43], exec
	s_cselect_b32 s17, s19, s25
	s_cselect_b32 s69, s18, s24
	s_ashr_i32 s20, s16, 5
	s_ashr_i32 s21, s20, 31
	s_lshl_b64 s[20:21], s[20:21], 21
	s_add_u32 s26, s31, s20
	s_addc_u32 s27, s33, s21
	s_ashr_i32 s13, s12, 31
	s_lshl_b64 s[20:21], s[12:13], 19
	s_add_u32 s20, s26, s20
	s_addc_u32 s21, s27, s21
	s_and_b64 s[26:27], s[42:43], exec
	s_cselect_b32 s13, s21, s23
	s_cselect_b32 s34, s20, s22
	s_add_u32 s53, s22, 0x100
	s_addc_u32 s71, s23, 0
	s_add_u32 s22, s24, 0x40080
	s_addc_u32 s23, s25, 0
	s_mov_b32 s72, -2
	.p2alignl 3, 3212836864
	s_add_u32 s24, s22, 0xfffc0080
	s_addc_u32 s25, s23, -1
	s_add_i32 s73, s35, 0x100
	s_cmp_eq_u32 s72, 12
	s_cselect_b32 s27, s17, s25
	s_cselect_b32 s26, s69, s24
	s_cselect_b32 s25, s13, s71
	s_cselect_b32 s24, s34, s53
	s_add_i32 s76, s90, 0x100
	v_add_u32_e32 v140, s73, v212
	v_add_u32_e32 v168, s76, v212
	ds_read_b128 v[128:131], v140
	ds_read_b128 v[132:135], v140 offset:1024
	ds_read_b128 v[136:139], v140 offset:2048
	ds_read_b128 v[140:143], v140 offset:3072
	ds_read_b128 v[156:159], v168
	ds_read_b128 v[160:163], v168 offset:1024
	ds_read_b128 v[164:167], v168 offset:2048
	ds_read_b128 v[168:171], v168 offset:3072
	v_lshl_add_u64 v[194:195], s[22:23], 0, v[154:155]
	s_add_i32 m0, s39, 0xc000
	ds_read_b128 v[172:175], v227
	ds_read_b128 v[176:179], v227 offset:1024
	ds_read_b128 v[180:183], v227 offset:2048
	ds_read_b128 v[184:187], v227 offset:3072
	ds_read_b128 v[188:191], v227 offset:4096
	ds_read_b128 v[198:201], v227 offset:5120
	ds_read_b128 v[202:205], v227 offset:6144
	ds_read_b128 v[206:209], v227 offset:7168
	global_load_lds_dwordx4 v[194:195], off
	v_lshl_add_u64 v[194:195], s[22:23], 0, v[152:153]
	s_add_i32 m0, s39, 0xe000
	s_nop 0
	global_load_lds_dwordx4 v[194:195], off
	s_waitcnt vmcnt(8)
	s_waitcnt lgkmcnt(0)
	s_barrier
	s_setprio 1
	s_waitcnt lgkmcnt(0)
	v_mfma_f32_16x16x32_bf16 v[124:127], v[128:131], v[172:175], 0
	v_mfma_f32_16x16x32_bf16 v[120:123], v[136:139], v[172:175], 0
	v_mfma_f32_16x16x32_bf16 v[108:111], v[128:131], v[180:183], 0
	v_mfma_f32_16x16x32_bf16 v[104:107], v[136:139], v[180:183], 0
	v_mfma_f32_16x16x32_bf16 v[96:99], v[128:131], v[188:191], 0
	v_mfma_f32_16x16x32_bf16 v[88:91], v[136:139], v[188:191], 0
	v_mfma_f32_16x16x32_bf16 v[80:83], v[128:131], v[202:205], 0
	v_mfma_f32_16x16x32_bf16 v[72:75], v[136:139], v[202:205], 0
	v_mfma_f32_16x16x32_bf16 v[124:127], v[132:135], v[176:179], v[124:127]
	v_mfma_f32_16x16x32_bf16 v[120:123], v[140:143], v[176:179], v[120:123]
	v_mfma_f32_16x16x32_bf16 v[108:111], v[132:135], v[184:187], v[108:111]
	v_mfma_f32_16x16x32_bf16 v[104:107], v[140:143], v[184:187], v[104:107]
	v_mfma_f32_16x16x32_bf16 v[96:99], v[132:135], v[198:201], v[96:99]
	v_mfma_f32_16x16x32_bf16 v[88:91], v[140:143], v[198:201], v[88:91]
	v_mfma_f32_16x16x32_bf16 v[80:83], v[132:135], v[206:209], v[80:83]
	v_mfma_f32_16x16x32_bf16 v[72:75], v[140:143], v[206:209], v[72:75]
	s_setprio 0
	s_setprio 1
	v_mfma_f32_16x16x32_bf16 v[116:119], v[156:159], v[172:175], 0
	v_mfma_f32_16x16x32_bf16 v[112:115], v[164:167], v[172:175], 0
	v_mfma_f32_16x16x32_bf16 v[100:103], v[156:159], v[180:183], 0
	v_mfma_f32_16x16x32_bf16 v[92:95], v[164:167], v[180:183], 0
	v_mfma_f32_16x16x32_bf16 v[84:87], v[156:159], v[188:191], 0
	v_mfma_f32_16x16x32_bf16 v[76:79], v[164:167], v[188:191], 0
	v_mfma_f32_16x16x32_bf16 v[68:71], v[156:159], v[202:205], 0
	v_mfma_f32_16x16x32_bf16 v[64:67], v[164:167], v[202:205], 0
	v_mfma_f32_16x16x32_bf16 v[116:119], v[160:163], v[176:179], v[116:119]
	v_mfma_f32_16x16x32_bf16 v[112:115], v[168:171], v[176:179], v[112:115]
	v_mfma_f32_16x16x32_bf16 v[100:103], v[160:163], v[184:187], v[100:103]
	v_mfma_f32_16x16x32_bf16 v[92:95], v[168:171], v[184:187], v[92:95]
	v_mfma_f32_16x16x32_bf16 v[84:87], v[160:163], v[198:201], v[84:87]
	v_mfma_f32_16x16x32_bf16 v[76:79], v[168:171], v[198:201], v[76:79]
	v_mfma_f32_16x16x32_bf16 v[68:71], v[160:163], v[206:209], v[68:71]
	v_mfma_f32_16x16x32_bf16 v[64:67], v[168:171], v[206:209], v[64:67]
	s_setprio 0
	s_barrier
	s_add_i32 s73, s73, s38
	v_lshl_add_u64 v[194:195], s[24:25], 0, v[148:149]
	s_mov_b32 m0, s73
	ds_read_b128 v[172:175], v227 offset:16384
	ds_read_b128 v[176:179], v227 offset:17408
	ds_read_b128 v[180:183], v227 offset:18432
	ds_read_b128 v[184:187], v227 offset:19456
	ds_read_b128 v[188:191], v227 offset:20480
	ds_read_b128 v[198:201], v227 offset:21504
	ds_read_b128 v[202:205], v227 offset:22528
	ds_read_b128 v[206:209], v227 offset:23552
	global_load_lds_dwordx4 v[194:195], off
	s_add_i32 m0, s73, 0x2000
	s_add_u32 s74, s24, 0x40000
	v_lshl_add_u64 v[196:197], s[24:25], 0, v[144:145]
	s_addc_u32 s75, s25, 0
	s_add_i32 s73, s76, s38
	global_load_lds_dwordx4 v[196:197], off
	v_lshl_add_u64 v[234:235], s[74:75], 0, v[148:149]
	s_mov_b32 m0, s73
	v_lshl_add_u64 v[236:237], s[26:27], 0, v[146:147]
	global_load_lds_dwordx4 v[234:235], off
	v_lshl_add_u64 v[234:235], s[74:75], 0, v[144:145]
	s_add_i32 m0, s73, 0x2000
	s_nop 0
	global_load_lds_dwordx4 v[234:235], off
	v_lshl_add_u64 v[234:235], s[26:27], 0, v[150:151]
	s_mov_b32 m0, s39
	s_nop 0
	global_load_lds_dwordx4 v[234:235], off
	s_mov_b32 m0, s44
	s_nop 0
	global_load_lds_dwordx4 v[236:237], off
	s_waitcnt vmcnt(8)
	s_waitcnt lgkmcnt(0)
	s_barrier
; #define PG8_STAGE(bufoff, gbase, voff) do { _Pragma("unroll") for (int _i = 0; _i < 2; ++_i) \
;         __builtin_amdgcn_global_load_lds((const unsigned*)((const char*)(gbase) + (voff)[_i]), (PG8_LAS unsigned*)(lds + (bufoff) + ldsw + _i * 8192), 16, 0, 0); } while (0)
; #define PG8_LDA(dst, b, h) do { _Pragma("unroll") for (int m = 0; m < 4; ++m) _Pragma("unroll") for (int k = 0; k < 2; ++k) dst[m][k] = *(const PG8_LAS bf16x8*)(lds + PG8_SA(b, h) + aoff + m * 2048 + k * 1024); } while (0)
; #define PG8_LDB(dst, b, h) do { _Pragma("unroll") for (int n = 0; n < 2; ++n) _Pragma("unroll") for (int k = 0; k < 2; ++k) dst[n][k] = *(const PG8_LAS bf16x8*)(lds + PG8_SB(b, h) + boff + n * 2048 + k * 1024); } while (0)
; #define PG8_MMA(ai, bj, At, Bt) do { __builtin_amdgcn_s_setprio(1); _Pragma("unroll") for (int m = 0; m < 4; ++m) _Pragma("unroll") for (int n = 0; n < 2; ++n) _Pragma("unroll") for (int k = 0; k < 2; ++k) \
;         acc[ai][bj][m][n] = __builtin_amdgcn_mfma_f32_16x16x32_bf16(Bt[n][k], At[m][k], acc[ai][bj][m][n], 0, 0, 0); __builtin_amdgcn_s_setprio(0); } while (0)
; #define PG8_WAIT_V(n) asm volatile("s_waitcnt vmcnt(" #n ")" ::: "memory")
; #define PG8_WAIT_L(n) asm volatile("s_waitcnt lgkmcnt(" #n ")" ::: "memory")
; #define PG8_BAR __builtin_amdgcn_s_barrier()
; #define PG8_SCHED __builtin_amdgcn_sched_barrier(0)
; template <class Epi, class Sched, bool ALIGN_EPI = false, bool SP2 = false>
; __device__ __forceinline__ void gemm_phase(PG8_LAS unsigned char* lds, const Gemm g, const Sched& S, const Epi& E, int wave_in) {
;     ...
;             PG8_LDA(At, 0, 1); PG8_STAGE(PG8_SB(0, 0), b2, voffB); PG8_STAGE(PG8_SB(0, 1), b2 + hstep, voffB); PG8_STAGE(PG8_SA(0, 0), a2, voffA);
;             PG8_WAIT_V(8); PG8_WAIT_L(0); PG8_BAR; PG8_MMA(1, 0, At, B0); PG8_MMA(1, 1, At, B1); PG8_BAR; PG8_SCHED;
;             PG8_LDB(B0, 1, 0); PG8_LDB(B1, 1, 1); PG8_SCHED; PG8_LDA(At, 1, 0); PG8_STAGE(PG8_SA(0, 1), a2 + hstep, voffA);
;             PG8_WAIT_V(8); PG8_WAIT_L(0); PG8_BAR; PG8_MMA(0, 0, At, B0); PG8_MMA(0, 1, At, B1); PG8_BAR; PG8_SCHED;
	s_setprio 1
	s_waitcnt lgkmcnt(0)
	v_mfma_f32_16x16x32_bf16 v[60:63], v[128:131], v[172:175], 0
	v_mfma_f32_16x16x32_bf16 v[56:59], v[136:139], v[172:175], 0
	v_mfma_f32_16x16x32_bf16 v[48:51], v[128:131], v[180:183], 0
	v_mfma_f32_16x16x32_bf16 v[40:43], v[136:139], v[180:183], 0
	v_mfma_f32_16x16x32_bf16 v[32:35], v[128:131], v[188:191], 0
	v_mfma_f32_16x16x32_bf16 v[24:27], v[136:139], v[188:191], 0
	v_mfma_f32_16x16x32_bf16 v[16:19], v[128:131], v[202:205], 0
	v_mfma_f32_16x16x32_bf16 v[8:11], v[136:139], v[202:205], 0
	v_mfma_f32_16x16x32_bf16 v[60:63], v[132:135], v[176:179], v[60:63]
	v_mfma_f32_16x16x32_bf16 v[56:59], v[140:143], v[176:179], v[56:59]
	v_mfma_f32_16x16x32_bf16 v[48:51], v[132:135], v[184:187], v[48:51]
	v_mfma_f32_16x16x32_bf16 v[40:43], v[140:143], v[184:187], v[40:43]
	v_mfma_f32_16x16x32_bf16 v[32:35], v[132:135], v[198:201], v[32:35]
	v_mfma_f32_16x16x32_bf16 v[24:27], v[140:143], v[198:201], v[24:27]
	v_mfma_f32_16x16x32_bf16 v[16:19], v[132:135], v[206:209], v[16:19]
	v_mfma_f32_16x16x32_bf16 v[8:11], v[140:143], v[206:209], v[8:11]
	s_setprio 0
	s_setprio 1
	v_mfma_f32_16x16x32_bf16 v[52:55], v[156:159], v[172:175], 0
	v_mfma_f32_16x16x32_bf16 v[44:47], v[164:167], v[172:175], 0
	v_mfma_f32_16x16x32_bf16 v[36:39], v[156:159], v[180:183], 0
	v_mfma_f32_16x16x32_bf16 v[28:31], v[164:167], v[180:183], 0
	v_mfma_f32_16x16x32_bf16 v[20:23], v[156:159], v[188:191], 0
	v_mfma_f32_16x16x32_bf16 v[12:15], v[164:167], v[188:191], 0
	v_mfma_f32_16x16x32_bf16 v[4:7], v[156:159], v[202:205], 0
	v_mfma_f32_16x16x32_bf16 v[0:3], v[164:167], v[202:205], 0
	v_mfma_f32_16x16x32_bf16 v[52:55], v[160:163], v[176:179], v[52:55]
	v_mfma_f32_16x16x32_bf16 v[44:47], v[168:171], v[176:179], v[44:47]
	v_mfma_f32_16x16x32_bf16 v[36:39], v[160:163], v[184:187], v[36:39]
	v_mfma_f32_16x16x32_bf16 v[28:31], v[168:171], v[184:187], v[28:31]
	v_mfma_f32_16x16x32_bf16 v[20:23], v[160:163], v[198:201], v[20:23]
	v_mfma_f32_16x16x32_bf16 v[12:15], v[168:171], v[198:201], v[12:15]
	v_mfma_f32_16x16x32_bf16 v[4:7], v[160:163], v[206:209], v[4:7]
	v_mfma_f32_16x16x32_bf16 v[0:3], v[168:171], v[206:209], v[0:3]
	s_setprio 0
	s_barrier
	s_add_i32 s73, s65, 0x100
	s_add_i32 s74, s52, 0x100
	v_add_u32_e32 v140, s73, v212
	v_add_u32_e32 v168, s74, v212
	ds_read_b128 v[128:131], v140
	ds_read_b128 v[132:135], v140 offset:1024
	ds_read_b128 v[136:139], v140 offset:2048
	ds_read_b128 v[140:143], v140 offset:3072
	ds_read_b128 v[156:159], v168
	ds_read_b128 v[160:163], v168 offset:1024
	ds_read_b128 v[164:167], v168 offset:2048
	ds_read_b128 v[168:171], v168 offset:3072
	s_add_u32 s26, s26, 0x40000
	s_addc_u32 s27, s27, 0
	s_mov_b32 m0, s45
	v_lshl_add_u64 v[238:239], s[26:27], 0, v[150:151]
	ds_read_b128 v[172:175], v227 offset:32768
	ds_read_b128 v[176:179], v227 offset:33792
	ds_read_b128 v[180:183], v227 offset:34816
	ds_read_b128 v[184:187], v227 offset:35840
	ds_read_b128 v[188:191], v227 offset:36864
	ds_read_b128 v[198:201], v227 offset:37888
	ds_read_b128 v[202:205], v227 offset:38912
	ds_read_b128 v[206:209], v227 offset:39936
	global_load_lds_dwordx4 v[238:239], off
	v_lshl_add_u64 v[238:239], s[26:27], 0, v[146:147]
	s_mov_b32 m0, s46
	s_nop 0
	global_load_lds_dwordx4 v[238:239], off
	s_waitcnt vmcnt(8)
	s_waitcnt lgkmcnt(0)
	s_barrier
	s_setprio 1
	s_waitcnt lgkmcnt(0)
	v_mfma_f32_16x16x32_bf16 v[124:127], v[128:131], v[172:175], v[124:127]
	v_mfma_f32_16x16x32_bf16 v[120:123], v[136:139], v[172:175], v[120:123]
	v_mfma_f32_16x16x32_bf16 v[108:111], v[128:131], v[180:183], v[108:111]
	v_mfma_f32_16x16x32_bf16 v[104:107], v[136:139], v[180:183], v[104:107]
	v_mfma_f32_16x16x32_bf16 v[96:99], v[128:131], v[188:191], v[96:99]
	v_mfma_f32_16x16x32_bf16 v[88:91], v[136:139], v[188:191], v[88:91]
	v_mfma_f32_16x16x32_bf16 v[80:83], v[128:131], v[202:205], v[80:83]
	v_mfma_f32_16x16x32_bf16 v[72:75], v[136:139], v[202:205], v[72:75]
	v_mfma_f32_16x16x32_bf16 v[124:127], v[132:135], v[176:179], v[124:127]
	v_mfma_f32_16x16x32_bf16 v[120:123], v[140:143], v[176:179], v[120:123]
	v_mfma_f32_16x16x32_bf16 v[108:111], v[132:135], v[184:187], v[108:111]
	v_mfma_f32_16x16x32_bf16 v[104:107], v[140:143], v[184:187], v[104:107]
	v_mfma_f32_16x16x32_bf16 v[96:99], v[132:135], v[198:201], v[96:99]
	v_mfma_f32_16x16x32_bf16 v[88:91], v[140:143], v[198:201], v[88:91]
	v_mfma_f32_16x16x32_bf16 v[80:83], v[132:135], v[206:209], v[80:83]
	v_mfma_f32_16x16x32_bf16 v[72:75], v[140:143], v[206:209], v[72:75]
	s_setprio 0
	s_setprio 1
	v_mfma_f32_16x16x32_bf16 v[116:119], v[156:159], v[172:175], v[116:119]
	v_mfma_f32_16x16x32_bf16 v[112:115], v[164:167], v[172:175], v[112:115]
	v_mfma_f32_16x16x32_bf16 v[100:103], v[156:159], v[180:183], v[100:103]
	v_mfma_f32_16x16x32_bf16 v[92:95], v[164:167], v[180:183], v[92:95]
	v_mfma_f32_16x16x32_bf16 v[84:87], v[156:159], v[188:191], v[84:87]
	v_mfma_f32_16x16x32_bf16 v[76:79], v[164:167], v[188:191], v[76:79]
	v_mfma_f32_16x16x32_bf16 v[68:71], v[156:159], v[202:205], v[68:71]
	v_mfma_f32_16x16x32_bf16 v[64:67], v[164:167], v[202:205], v[64:67]
	v_mfma_f32_16x16x32_bf16 v[116:119], v[160:163], v[176:179], v[116:119]
	v_mfma_f32_16x16x32_bf16 v[112:115], v[168:171], v[176:179], v[112:115]
	v_mfma_f32_16x16x32_bf16 v[100:103], v[160:163], v[184:187], v[100:103]
	v_mfma_f32_16x16x32_bf16 v[92:95], v[168:171], v[184:187], v[92:95]
	v_mfma_f32_16x16x32_bf16 v[84:87], v[160:163], v[198:201], v[84:87]
	v_mfma_f32_16x16x32_bf16 v[76:79], v[168:171], v[198:201], v[76:79]
	v_mfma_f32_16x16x32_bf16 v[68:71], v[160:163], v[206:209], v[68:71]
	v_mfma_f32_16x16x32_bf16 v[64:67], v[168:171], v[206:209], v[64:67]
	s_setprio 0
	s_barrier
; #define PG8_STAGE(bufoff, gbase, voff) do { _Pragma("unroll") for (int _i = 0; _i < 2; ++_i) \
;         __builtin_amdgcn_global_load_lds((const unsigned*)((const char*)(gbase) + (voff)[_i]), (PG8_LAS unsigned*)(lds + (bufoff) + ldsw + _i * 8192), 16, 0, 0); } while (0)
; #define PG8_LDA(dst, b, h) do { _Pragma("unroll") for (int m = 0; m < 4; ++m) _Pragma("unroll") for (int k = 0; k < 2; ++k) dst[m][k] = *(const PG8_LAS bf16x8*)(lds + PG8_SA(b, h) + aoff + m * 2048 + k * 1024); } while (0)
; #define PG8_MMA(ai, bj, At, Bt) do { __builtin_amdgcn_s_setprio(1); _Pragma("unroll") for (int m = 0; m < 4; ++m) _Pragma("unroll") for (int n = 0; n < 2; ++n) _Pragma("unroll") for (int k = 0; k < 2; ++k) \
;         acc[ai][bj][m][n] = __builtin_amdgcn_mfma_f32_16x16x32_bf16(Bt[n][k], At[m][k], acc[ai][bj][m][n], 0, 0, 0); __builtin_amdgcn_s_setprio(0); } while (0)
; #define PG8_WAIT_V(n) asm volatile("s_waitcnt vmcnt(" #n ")" ::: "memory")
; #define PG8_WAIT_L(n) asm volatile("s_waitcnt lgkmcnt(" #n ")" ::: "memory")
; #define PG8_BAR __builtin_amdgcn_s_barrier()
; #define PG8_SCHED __builtin_amdgcn_sched_barrier(0)
; template <class Epi, class Sched, bool ALIGN_EPI = false, bool SP2 = false>
; __device__ __forceinline__ void gemm_phase(PG8_LAS unsigned char* lds, const Gemm g, const Sched& S, const Epi& E, int wave_in) {
;     ...
;             PG8_WAIT_V(8); PG8_WAIT_L(0); PG8_BAR; PG8_MMA(0, 0, At, B0); PG8_MMA(0, 1, At, B1); PG8_BAR; PG8_SCHED;
;             PG8_LDA(At, 1, 1); PG8_STAGE(PG8_SB(1, 0), b3, voffB); PG8_STAGE(PG8_SB(1, 1), b3 + hstep, voffB); PG8_STAGE(PG8_SA(1, 0), a3, voffA);
;             PG8_WAIT_V(8); PG8_WAIT_L(0); PG8_BAR; PG8_MMA(1, 0, At, B0); PG8_MMA(1, 1, At, B1); PG8_BAR; PG8_SCHED;
	s_add_i32 s26, s73, s38
	v_lshl_add_u64 v[194:195], v[194:195], 0, s[88:89]
	s_mov_b32 m0, s26
	ds_read_b128 v[172:175], v227 offset:49152
	ds_read_b128 v[176:179], v227 offset:50176
	ds_read_b128 v[180:183], v227 offset:51200
	ds_read_b128 v[184:187], v227 offset:52224
	ds_read_b128 v[188:191], v227 offset:53248
	ds_read_b128 v[198:201], v227 offset:54272
	ds_read_b128 v[202:205], v227 offset:55296
	ds_read_b128 v[206:209], v227 offset:56320
	global_load_lds_dwordx4 v[194:195], off
	s_add_i32 m0, s26, 0x2000
	s_add_u32 s24, s24, 0x40080
	v_lshl_add_u64 v[194:195], v[196:197], 0, s[88:89]
	s_addc_u32 s25, s25, 0
	s_add_i32 s26, s74, s38
	global_load_lds_dwordx4 v[194:195], off
	v_lshl_add_u64 v[194:195], s[24:25], 0, v[148:149]
	s_mov_b32 m0, s26
	s_nop 0
	global_load_lds_dwordx4 v[194:195], off
	v_lshl_add_u64 v[194:195], s[24:25], 0, v[144:145]
	s_add_i32 m0, s26, 0x2000
	s_nop 0
	global_load_lds_dwordx4 v[194:195], off
	v_lshl_add_u64 v[194:195], v[234:235], 0, s[88:89]
	s_mov_b32 m0, s61
	s_nop 0
	global_load_lds_dwordx4 v[194:195], off
	v_lshl_add_u64 v[194:195], v[236:237], 0, s[88:89]
	s_mov_b32 m0, s62
	s_nop 0
	global_load_lds_dwordx4 v[194:195], off
	s_waitcnt vmcnt(8)
	s_waitcnt lgkmcnt(0)
	s_barrier
	s_setprio 1
	s_waitcnt lgkmcnt(0)
	v_mfma_f32_16x16x32_bf16 v[60:63], v[128:131], v[172:175], v[60:63]
	v_mfma_f32_16x16x32_bf16 v[56:59], v[136:139], v[172:175], v[56:59]
	v_mfma_f32_16x16x32_bf16 v[48:51], v[128:131], v[180:183], v[48:51]
	v_mfma_f32_16x16x32_bf16 v[40:43], v[136:139], v[180:183], v[40:43]
	v_mfma_f32_16x16x32_bf16 v[32:35], v[128:131], v[188:191], v[32:35]
	v_mfma_f32_16x16x32_bf16 v[24:27], v[136:139], v[188:191], v[24:27]
	v_mfma_f32_16x16x32_bf16 v[16:19], v[128:131], v[202:205], v[16:19]
	v_mfma_f32_16x16x32_bf16 v[8:11], v[136:139], v[202:205], v[8:11]
	v_mfma_f32_16x16x32_bf16 v[60:63], v[132:135], v[176:179], v[60:63]
	v_mfma_f32_16x16x32_bf16 v[56:59], v[140:143], v[176:179], v[56:59]
	v_mfma_f32_16x16x32_bf16 v[48:51], v[132:135], v[184:187], v[48:51]
	v_mfma_f32_16x16x32_bf16 v[40:43], v[140:143], v[184:187], v[40:43]
	v_mfma_f32_16x16x32_bf16 v[32:35], v[132:135], v[198:201], v[32:35]
	v_mfma_f32_16x16x32_bf16 v[24:27], v[140:143], v[198:201], v[24:27]
	v_mfma_f32_16x16x32_bf16 v[16:19], v[132:135], v[206:209], v[16:19]
	v_mfma_f32_16x16x32_bf16 v[8:11], v[140:143], v[206:209], v[8:11]
	s_setprio 0
	s_setprio 1
	v_mfma_f32_16x16x32_bf16 v[52:55], v[156:159], v[172:175], v[52:55]
	v_mfma_f32_16x16x32_bf16 v[44:47], v[164:167], v[172:175], v[44:47]
	v_mfma_f32_16x16x32_bf16 v[36:39], v[156:159], v[180:183], v[36:39]
	v_mfma_f32_16x16x32_bf16 v[28:31], v[164:167], v[180:183], v[28:31]
	v_mfma_f32_16x16x32_bf16 v[20:23], v[156:159], v[188:191], v[20:23]
	v_mfma_f32_16x16x32_bf16 v[12:15], v[164:167], v[188:191], v[12:15]
	v_mfma_f32_16x16x32_bf16 v[4:7], v[156:159], v[202:205], v[4:7]
	v_mfma_f32_16x16x32_bf16 v[0:3], v[164:167], v[202:205], v[0:3]
	v_mfma_f32_16x16x32_bf16 v[52:55], v[160:163], v[176:179], v[52:55]
	v_mfma_f32_16x16x32_bf16 v[44:47], v[168:171], v[176:179], v[44:47]
	v_mfma_f32_16x16x32_bf16 v[36:39], v[160:163], v[184:187], v[36:39]
	v_mfma_f32_16x16x32_bf16 v[28:31], v[168:171], v[184:187], v[28:31]
	v_mfma_f32_16x16x32_bf16 v[20:23], v[160:163], v[198:201], v[20:23]
	v_mfma_f32_16x16x32_bf16 v[12:15], v[168:171], v[198:201], v[12:15]
	v_mfma_f32_16x16x32_bf16 v[4:7], v[160:163], v[206:209], v[4:7]
	v_mfma_f32_16x16x32_bf16 v[0:3], v[168:171], v[206:209], v[0:3]
	s_setprio 0
	s_barrier
	s_add_i32 s72, s72, 2
	s_add_u32 s53, s53, 0x100
	s_addc_u32 s71, s71, 0
	s_add_u32 s22, s22, 0x100
	s_addc_u32 s23, s23, 0
	s_cmp_gt_u32 s72, 13
	s_cbranch_scc1 .Lkexit_4
	.p2alignl 6, 3212836864

; #define PG8_STAGE(bufoff, gbase, voff) do { _Pragma("unroll") for (int _i = 0; _i < 2; ++_i) \
;         __builtin_amdgcn_global_load_lds((const unsigned*)((const char*)(gbase) + (voff)[_i]), (PG8_LAS unsigned*)(lds + (bufoff) + ldsw + _i * 8192), 16, 0, 0); } while (0)
; #define PG8_LDA(dst, b, h) do { _Pragma("unroll") for (int m = 0; m < 4; ++m) _Pragma("unroll") for (int k = 0; k < 2; ++k) dst[m][k] = *(const PG8_LAS bf16x8*)(lds + PG8_SA(b, h) + aoff + m * 2048 + k * 1024); } while (0)
; #define PG8_LDB(dst, b, h) do { _Pragma("unroll") for (int n = 0; n < 2; ++n) _Pragma("unroll") for (int k = 0; k < 2; ++k) dst[n][k] = *(const PG8_LAS bf16x8*)(lds + PG8_SB(b, h) + boff + n * 2048 + k * 1024); } while (0)
; #define PG8_MMA(ai, bj, At, Bt) do { __builtin_amdgcn_s_setprio(1); _Pragma("unroll") for (int m = 0; m < 4; ++m) _Pragma("unroll") for (int n = 0; n < 2; ++n) _Pragma("unroll") for (int k = 0; k < 2; ++k) \
;         acc[ai][bj][m][n] = __builtin_amdgcn_mfma_f32_16x16x32_bf16(Bt[n][k], At[m][k], acc[ai][bj][m][n], 0, 0, 0); __builtin_amdgcn_s_setprio(0); } while (0)
; #define PG8_WAIT_V(n) asm volatile("s_waitcnt vmcnt(" #n ")" ::: "memory")
; #define PG8_WAIT_L(n) asm volatile("s_waitcnt lgkmcnt(" #n ")" ::: "memory")
; #define PG8_BAR __builtin_amdgcn_s_barrier()
; #define PG8_SCHED __builtin_amdgcn_sched_barrier(0)
; template <class Epi, class Sched, bool ALIGN_EPI = false, bool SP2 = false>
; __device__ __forceinline__ void gemm_phase(PG8_LAS unsigned char* lds, const Gemm g, const Sched& S, const Epi& E, int wave_in) {
;     ...
;         for (int t = 0; t < nt; t += 2) {
;             const bool last = (t == nt - 2);
;             const char* a1 = cA + (size_t)(t + 1) * kstep;
;             const char* a2 = last ? nA : cA + (size_t)(t + 2) * kstep; const char* b2 = last ? nB : cB + (size_t)(t + 2) * kstep;
;             const char* a3 = a2 + kstep; const char* b3 = b2 + kstep;
;             if (last && has_next) S.a_ready(nxt);
;             if constexpr (SP2) {
;             PG8_LDB(B0, 0, 0); PG8_LDB(B1, 0, 1); PG8_SCHED; PG8_LDA(At, 0, 0); PG8_STAGE(PG8_SA(1, 1), a1 + hstep, voffA);
;             PG8_WAIT_V(8); PG8_WAIT_L(0); PG8_BAR; PG8_MMA(0, 0, At, B0); PG8_MMA(0, 1, At, B1); PG8_BAR; PG8_SCHED;
;             PG8_LDA(At, 0, 1); PG8_STAGE(PG8_SB(0, 0), b2, voffB); PG8_STAGE(PG8_SB(0, 1), b2 + hstep, voffB); PG8_STAGE(PG8_SA(0, 0), a2, voffA);
.LBB0_803:
	s_add_u32 s15, s22, 0x100
	s_addc_u32 s17, s23, 0
	s_add_u32 s22, s24, 0x40080
	s_addc_u32 s23, s25, 0
	s_mov_b32 s34, -2
	.p2alignl 3, 3212836864
	s_add_u32 s24, s22, 0xfffc0080
	s_addc_u32 s25, s23, -1
	s_add_i32 s44, s35, 0x100
	s_cmp_eq_u32 s34, 12
	s_cselect_b32 s27, s19, s25
	s_cselect_b32 s26, s18, s24
	s_cselect_b32 s25, s21, s17
	s_cselect_b32 s24, s20, s15
	s_add_i32 s53, s90, 0x100
	v_add_u32_e32 v128, s44, v249
	v_add_u32_e32 v156, s53, v249
	ds_read_b128 v[112:115], v128
	ds_read_b128 v[120:123], v128 offset:1024
	ds_read_b128 v[124:127], v128 offset:2048
	ds_read_b128 v[128:131], v128 offset:3072
	ds_read_b128 v[136:139], v156
	ds_read_b128 v[140:143], v156 offset:1024
	ds_read_b128 v[144:147], v156 offset:2048
	ds_read_b128 v[156:159], v156 offset:3072
	v_lshl_add_u64 v[194:195], s[22:23], 0, v[206:207]
	s_add_i32 m0, s39, 0xc000
	ds_read_b128 v[160:163], v251
	ds_read_b128 v[164:167], v251 offset:1024
	ds_read_b128 v[168:171], v251 offset:2048
	ds_read_b128 v[172:175], v251 offset:3072
	ds_read_b128 v[176:179], v251 offset:4096
	ds_read_b128 v[180:183], v251 offset:5120
	ds_read_b128 v[184:187], v251 offset:6144
	ds_read_b128 v[188:191], v251 offset:7168
	global_load_lds_dwordx4 v[194:195], off
	v_lshl_add_u64 v[194:195], s[22:23], 0, v[204:205]
	s_add_i32 m0, s39, 0xe000
	s_nop 0
	global_load_lds_dwordx4 v[194:195], off
	s_waitcnt vmcnt(8)
	s_waitcnt lgkmcnt(0)
	s_barrier
	s_setprio 1
	s_waitcnt lgkmcnt(0)
	v_mfma_f32_16x16x32_bf16 v[152:155], v[112:115], v[160:163], 0
	v_mfma_f32_16x16x32_bf16 v[148:151], v[124:127], v[160:163], 0
	v_mfma_f32_16x16x32_bf16 v[108:111], v[112:115], v[168:171], 0
	v_mfma_f32_16x16x32_bf16 v[104:107], v[124:127], v[168:171], 0
	v_mfma_f32_16x16x32_bf16 v[92:95], v[112:115], v[176:179], 0
	v_mfma_f32_16x16x32_bf16 v[88:91], v[124:127], v[176:179], 0
	v_mfma_f32_16x16x32_bf16 v[76:79], v[112:115], v[184:187], 0
	v_mfma_f32_16x16x32_bf16 v[72:75], v[124:127], v[184:187], 0
	v_mfma_f32_16x16x32_bf16 v[152:155], v[120:123], v[164:167], v[152:155]
	v_mfma_f32_16x16x32_bf16 v[148:151], v[128:131], v[164:167], v[148:151]
	v_mfma_f32_16x16x32_bf16 v[108:111], v[120:123], v[172:175], v[108:111]
	v_mfma_f32_16x16x32_bf16 v[104:107], v[128:131], v[172:175], v[104:107]
	v_mfma_f32_16x16x32_bf16 v[92:95], v[120:123], v[180:183], v[92:95]
	v_mfma_f32_16x16x32_bf16 v[88:91], v[128:131], v[180:183], v[88:91]
	v_mfma_f32_16x16x32_bf16 v[76:79], v[120:123], v[188:191], v[76:79]
	v_mfma_f32_16x16x32_bf16 v[72:75], v[128:131], v[188:191], v[72:75]
	s_setprio 0
	s_setprio 1
	v_mfma_f32_16x16x32_bf16 v[132:135], v[136:139], v[160:163], 0
	v_mfma_f32_16x16x32_bf16 v[116:119], v[144:147], v[160:163], 0
	v_mfma_f32_16x16x32_bf16 v[100:103], v[136:139], v[168:171], 0
	v_mfma_f32_16x16x32_bf16 v[96:99], v[144:147], v[168:171], 0
	v_mfma_f32_16x16x32_bf16 v[84:87], v[136:139], v[176:179], 0
	v_mfma_f32_16x16x32_bf16 v[80:83], v[144:147], v[176:179], 0
	v_mfma_f32_16x16x32_bf16 v[68:71], v[136:139], v[184:187], 0
	v_mfma_f32_16x16x32_bf16 v[64:67], v[144:147], v[184:187], 0
	v_mfma_f32_16x16x32_bf16 v[132:135], v[140:143], v[164:167], v[132:135]
	v_mfma_f32_16x16x32_bf16 v[116:119], v[156:159], v[164:167], v[116:119]
	v_mfma_f32_16x16x32_bf16 v[100:103], v[140:143], v[172:175], v[100:103]
	v_mfma_f32_16x16x32_bf16 v[96:99], v[156:159], v[172:175], v[96:99]
	v_mfma_f32_16x16x32_bf16 v[84:87], v[140:143], v[180:183], v[84:87]
	v_mfma_f32_16x16x32_bf16 v[80:83], v[156:159], v[180:183], v[80:83]
	v_mfma_f32_16x16x32_bf16 v[68:71], v[140:143], v[188:191], v[68:71]
	v_mfma_f32_16x16x32_bf16 v[64:67], v[156:159], v[188:191], v[64:67]
	s_setprio 0
	s_barrier
	s_add_i32 s44, s44, s38
	v_lshl_add_u64 v[194:195], s[24:25], 0, v[192:193]
	s_mov_b32 m0, s44
	ds_read_b128 v[160:163], v251 offset:16384
	ds_read_b128 v[164:167], v251 offset:17408
	ds_read_b128 v[168:171], v251 offset:18432
	ds_read_b128 v[172:175], v251 offset:19456
	ds_read_b128 v[176:179], v251 offset:20480
	ds_read_b128 v[180:183], v251 offset:21504
	ds_read_b128 v[184:187], v251 offset:22528
	ds_read_b128 v[188:191], v251 offset:23552
	global_load_lds_dwordx4 v[194:195], off
	s_add_i32 m0, s44, 0x2000
	s_add_u32 s44, s24, 0x40000
	v_lshl_add_u64 v[196:197], s[24:25], 0, v[198:199]
	s_addc_u32 s45, s25, 0
	s_add_i32 s53, s53, s38
	global_load_lds_dwordx4 v[196:197], off
	v_lshl_add_u64 v[208:209], s[44:45], 0, v[192:193]
	s_mov_b32 m0, s53
	v_lshl_add_u64 v[210:211], s[26:27], 0, v[200:201]
	global_load_lds_dwordx4 v[208:209], off
	v_lshl_add_u64 v[208:209], s[44:45], 0, v[198:199]
	s_add_i32 m0, s53, 0x2000
	s_nop 0
	global_load_lds_dwordx4 v[208:209], off
	v_lshl_add_u64 v[208:209], s[26:27], 0, v[202:203]
	s_mov_b32 m0, s39
	s_nop 0
	global_load_lds_dwordx4 v[208:209], off
	s_mov_b32 m0, s46
	s_nop 0
	global_load_lds_dwordx4 v[210:211], off
	s_waitcnt vmcnt(8)
	s_waitcnt lgkmcnt(0)
	s_barrier
; #define PG8_STAGE(bufoff, gbase, voff) do { _Pragma("unroll") for (int _i = 0; _i < 2; ++_i) \
;         __builtin_amdgcn_global_load_lds((const unsigned*)((const char*)(gbase) + (voff)[_i]), (PG8_LAS unsigned*)(lds + (bufoff) + ldsw + _i * 8192), 16, 0, 0); } while (0)
; #define PG8_LDA(dst, b, h) do { _Pragma("unroll") for (int m = 0; m < 4; ++m) _Pragma("unroll") for (int k = 0; k < 2; ++k) dst[m][k] = *(const PG8_LAS bf16x8*)(lds + PG8_SA(b, h) + aoff + m * 2048 + k * 1024); } while (0)
; #define PG8_LDB(dst, b, h) do { _Pragma("unroll") for (int n = 0; n < 2; ++n) _Pragma("unroll") for (int k = 0; k < 2; ++k) dst[n][k] = *(const PG8_LAS bf16x8*)(lds + PG8_SB(b, h) + boff + n * 2048 + k * 1024); } while (0)
; #define PG8_MMA(ai, bj, At, Bt) do { __builtin_amdgcn_s_setprio(1); _Pragma("unroll") for (int m = 0; m < 4; ++m) _Pragma("unroll") for (int n = 0; n < 2; ++n) _Pragma("unroll") for (int k = 0; k < 2; ++k) \
;         acc[ai][bj][m][n] = __builtin_amdgcn_mfma_f32_16x16x32_bf16(Bt[n][k], At[m][k], acc[ai][bj][m][n], 0, 0, 0); __builtin_amdgcn_s_setprio(0); } while (0)
; #define PG8_WAIT_V(n) asm volatile("s_waitcnt vmcnt(" #n ")" ::: "memory")
; #define PG8_WAIT_L(n) asm volatile("s_waitcnt lgkmcnt(" #n ")" ::: "memory")
; #define PG8_BAR __builtin_amdgcn_s_barrier()
; #define PG8_SCHED __builtin_amdgcn_sched_barrier(0)
; template <class Epi, class Sched, bool ALIGN_EPI = false, bool SP2 = false>
; __device__ __forceinline__ void gemm_phase(PG8_LAS unsigned char* lds, const Gemm g, const Sched& S, const Epi& E, int wave_in) {
;     ...
;             PG8_LDA(At, 0, 1); PG8_STAGE(PG8_SB(0, 0), b2, voffB); PG8_STAGE(PG8_SB(0, 1), b2 + hstep, voffB); PG8_STAGE(PG8_SA(0, 0), a2, voffA);
;             PG8_WAIT_V(8); PG8_WAIT_L(0); PG8_BAR; PG8_MMA(1, 0, At, B0); PG8_MMA(1, 1, At, B1); PG8_BAR; PG8_SCHED;
;             PG8_LDB(B0, 1, 0); PG8_LDB(B1, 1, 1); PG8_SCHED; PG8_LDA(At, 1, 0); PG8_STAGE(PG8_SA(0, 1), a2 + hstep, voffA);
;             PG8_WAIT_V(8); PG8_WAIT_L(0); PG8_BAR; PG8_MMA(0, 0, At, B0); PG8_MMA(0, 1, At, B1); PG8_BAR; PG8_SCHED;
	s_setprio 1
	s_waitcnt lgkmcnt(0)
	v_mfma_f32_16x16x32_bf16 v[60:63], v[112:115], v[160:163], 0
	v_mfma_f32_16x16x32_bf16 v[56:59], v[124:127], v[160:163], 0
	v_mfma_f32_16x16x32_bf16 v[44:47], v[112:115], v[168:171], 0
	v_mfma_f32_16x16x32_bf16 v[40:43], v[124:127], v[168:171], 0
	v_mfma_f32_16x16x32_bf16 v[28:31], v[112:115], v[176:179], 0
	v_mfma_f32_16x16x32_bf16 v[24:27], v[124:127], v[176:179], 0
	v_mfma_f32_16x16x32_bf16 v[12:15], v[112:115], v[184:187], 0
	v_mfma_f32_16x16x32_bf16 v[8:11], v[124:127], v[184:187], 0
	v_mfma_f32_16x16x32_bf16 v[60:63], v[120:123], v[164:167], v[60:63]
	v_mfma_f32_16x16x32_bf16 v[56:59], v[128:131], v[164:167], v[56:59]
	v_mfma_f32_16x16x32_bf16 v[44:47], v[120:123], v[172:175], v[44:47]
	v_mfma_f32_16x16x32_bf16 v[40:43], v[128:131], v[172:175], v[40:43]
	v_mfma_f32_16x16x32_bf16 v[28:31], v[120:123], v[180:183], v[28:31]
	v_mfma_f32_16x16x32_bf16 v[24:27], v[128:131], v[180:183], v[24:27]
	v_mfma_f32_16x16x32_bf16 v[12:15], v[120:123], v[188:191], v[12:15]
	v_mfma_f32_16x16x32_bf16 v[8:11], v[128:131], v[188:191], v[8:11]
	s_setprio 0
	s_setprio 1
	v_mfma_f32_16x16x32_bf16 v[52:55], v[136:139], v[160:163], 0
	v_mfma_f32_16x16x32_bf16 v[48:51], v[144:147], v[160:163], 0
	v_mfma_f32_16x16x32_bf16 v[36:39], v[136:139], v[168:171], 0
	v_mfma_f32_16x16x32_bf16 v[32:35], v[144:147], v[168:171], 0
	v_mfma_f32_16x16x32_bf16 v[20:23], v[136:139], v[176:179], 0
	v_mfma_f32_16x16x32_bf16 v[16:19], v[144:147], v[176:179], 0
	v_mfma_f32_16x16x32_bf16 v[4:7], v[136:139], v[184:187], 0
	v_mfma_f32_16x16x32_bf16 v[0:3], v[144:147], v[184:187], 0
	v_mfma_f32_16x16x32_bf16 v[52:55], v[140:143], v[164:167], v[52:55]
	v_mfma_f32_16x16x32_bf16 v[48:51], v[156:159], v[164:167], v[48:51]
	v_mfma_f32_16x16x32_bf16 v[36:39], v[140:143], v[172:175], v[36:39]
	v_mfma_f32_16x16x32_bf16 v[32:35], v[156:159], v[172:175], v[32:35]
	v_mfma_f32_16x16x32_bf16 v[20:23], v[140:143], v[180:183], v[20:23]
	v_mfma_f32_16x16x32_bf16 v[16:19], v[156:159], v[180:183], v[16:19]
	v_mfma_f32_16x16x32_bf16 v[4:7], v[140:143], v[188:191], v[4:7]
	v_mfma_f32_16x16x32_bf16 v[0:3], v[156:159], v[188:191], v[0:3]
	s_setprio 0
	s_barrier
	s_add_i32 s44, s65, 0x100
	s_add_i32 s45, s52, 0x100
	v_add_u32_e32 v128, s44, v249
	v_add_u32_e32 v156, s45, v249
	ds_read_b128 v[112:115], v128
	ds_read_b128 v[120:123], v128 offset:1024
	ds_read_b128 v[124:127], v128 offset:2048
	ds_read_b128 v[128:131], v128 offset:3072
	ds_read_b128 v[136:139], v156
	ds_read_b128 v[140:143], v156 offset:1024
	ds_read_b128 v[144:147], v156 offset:2048
	ds_read_b128 v[156:159], v156 offset:3072
	s_add_u32 s26, s26, 0x40000
	s_addc_u32 s27, s27, 0
	s_mov_b32 m0, s47
	v_lshl_add_u64 v[212:213], s[26:27], 0, v[202:203]
	ds_read_b128 v[160:163], v251 offset:32768
	ds_read_b128 v[164:167], v251 offset:33792
	ds_read_b128 v[168:171], v251 offset:34816
	ds_read_b128 v[172:175], v251 offset:35840
	ds_read_b128 v[176:179], v251 offset:36864
	ds_read_b128 v[180:183], v251 offset:37888
	ds_read_b128 v[184:187], v251 offset:38912
	ds_read_b128 v[188:191], v251 offset:39936
	global_load_lds_dwordx4 v[212:213], off
	v_lshl_add_u64 v[212:213], s[26:27], 0, v[200:201]
	s_mov_b32 m0, s60
	s_nop 0
	global_load_lds_dwordx4 v[212:213], off
	s_waitcnt vmcnt(8)
	s_waitcnt lgkmcnt(0)
	s_barrier
	s_setprio 1
	s_waitcnt lgkmcnt(0)
	v_mfma_f32_16x16x32_bf16 v[152:155], v[112:115], v[160:163], v[152:155]
	v_mfma_f32_16x16x32_bf16 v[148:151], v[124:127], v[160:163], v[148:151]
	v_mfma_f32_16x16x32_bf16 v[108:111], v[112:115], v[168:171], v[108:111]
	v_mfma_f32_16x16x32_bf16 v[104:107], v[124:127], v[168:171], v[104:107]
	v_mfma_f32_16x16x32_bf16 v[92:95], v[112:115], v[176:179], v[92:95]
	v_mfma_f32_16x16x32_bf16 v[88:91], v[124:127], v[176:179], v[88:91]
	v_mfma_f32_16x16x32_bf16 v[76:79], v[112:115], v[184:187], v[76:79]
	v_mfma_f32_16x16x32_bf16 v[72:75], v[124:127], v[184:187], v[72:75]
	v_mfma_f32_16x16x32_bf16 v[152:155], v[120:123], v[164:167], v[152:155]
	v_mfma_f32_16x16x32_bf16 v[148:151], v[128:131], v[164:167], v[148:151]
	v_mfma_f32_16x16x32_bf16 v[108:111], v[120:123], v[172:175], v[108:111]
	v_mfma_f32_16x16x32_bf16 v[104:107], v[128:131], v[172:175], v[104:107]
	v_mfma_f32_16x16x32_bf16 v[92:95], v[120:123], v[180:183], v[92:95]
	v_mfma_f32_16x16x32_bf16 v[88:91], v[128:131], v[180:183], v[88:91]
	v_mfma_f32_16x16x32_bf16 v[76:79], v[120:123], v[188:191], v[76:79]
	v_mfma_f32_16x16x32_bf16 v[72:75], v[128:131], v[188:191], v[72:75]
	s_setprio 0
	s_setprio 1
	v_mfma_f32_16x16x32_bf16 v[132:135], v[136:139], v[160:163], v[132:135]
	v_mfma_f32_16x16x32_bf16 v[116:119], v[144:147], v[160:163], v[116:119]
	v_mfma_f32_16x16x32_bf16 v[100:103], v[136:139], v[168:171], v[100:103]
	v_mfma_f32_16x16x32_bf16 v[96:99], v[144:147], v[168:171], v[96:99]
	v_mfma_f32_16x16x32_bf16 v[84:87], v[136:139], v[176:179], v[84:87]
	v_mfma_f32_16x16x32_bf16 v[80:83], v[144:147], v[176:179], v[80:83]
	v_mfma_f32_16x16x32_bf16 v[68:71], v[136:139], v[184:187], v[68:71]
	v_mfma_f32_16x16x32_bf16 v[64:67], v[144:147], v[184:187], v[64:67]
	v_mfma_f32_16x16x32_bf16 v[132:135], v[140:143], v[164:167], v[132:135]
	v_mfma_f32_16x16x32_bf16 v[116:119], v[156:159], v[164:167], v[116:119]
	v_mfma_f32_16x16x32_bf16 v[100:103], v[140:143], v[172:175], v[100:103]
	v_mfma_f32_16x16x32_bf16 v[96:99], v[156:159], v[172:175], v[96:99]
	v_mfma_f32_16x16x32_bf16 v[84:87], v[140:143], v[180:183], v[84:87]
	v_mfma_f32_16x16x32_bf16 v[80:83], v[156:159], v[180:183], v[80:83]
	v_mfma_f32_16x16x32_bf16 v[68:71], v[140:143], v[188:191], v[68:71]
	v_mfma_f32_16x16x32_bf16 v[64:67], v[156:159], v[188:191], v[64:67]
	s_setprio 0
	s_barrier
; #define PG8_STAGE(bufoff, gbase, voff) do { _Pragma("unroll") for (int _i = 0; _i < 2; ++_i) \
;         __builtin_amdgcn_global_load_lds((const unsigned*)((const char*)(gbase) + (voff)[_i]), (PG8_LAS unsigned*)(lds + (bufoff) + ldsw + _i * 8192), 16, 0, 0); } while (0)
; #define PG8_LDA(dst, b, h) do { _Pragma("unroll") for (int m = 0; m < 4; ++m) _Pragma("unroll") for (int k = 0; k < 2; ++k) dst[m][k] = *(const PG8_LAS bf16x8*)(lds + PG8_SA(b, h) + aoff + m * 2048 + k * 1024); } while (0)
; #define PG8_MMA(ai, bj, At, Bt) do { __builtin_amdgcn_s_setprio(1); _Pragma("unroll") for (int m = 0; m < 4; ++m) _Pragma("unroll") for (int n = 0; n < 2; ++n) _Pragma("unroll") for (int k = 0; k < 2; ++k) \
;         acc[ai][bj][m][n] = __builtin_amdgcn_mfma_f32_16x16x32_bf16(Bt[n][k], At[m][k], acc[ai][bj][m][n], 0, 0, 0); __builtin_amdgcn_s_setprio(0); } while (0)
; #define PG8_WAIT_V(n) asm volatile("s_waitcnt vmcnt(" #n ")" ::: "memory")
; #define PG8_WAIT_L(n) asm volatile("s_waitcnt lgkmcnt(" #n ")" ::: "memory")
; #define PG8_BAR __builtin_amdgcn_s_barrier()
; #define PG8_SCHED __builtin_amdgcn_sched_barrier(0)
; template <class Epi, class Sched, bool ALIGN_EPI = false, bool SP2 = false>
; __device__ __forceinline__ void gemm_phase(PG8_LAS unsigned char* lds, const Gemm g, const Sched& S, const Epi& E, int wave_in) {
;     ...
;         for (int t = 0; t < nt; t += 2) {
;             const bool last = (t == nt - 2);
;     ...
;             PG8_LDA(At, 1, 1); PG8_STAGE(PG8_SB(1, 0), b3, voffB); PG8_STAGE(PG8_SB(1, 1), b3 + hstep, voffB); PG8_STAGE(PG8_SA(1, 0), a3, voffA);
;             PG8_WAIT_V(8); PG8_WAIT_L(0); PG8_BAR; PG8_MMA(1, 0, At, B0); PG8_MMA(1, 1, At, B1); PG8_BAR; PG8_SCHED;
	s_add_i32 s26, s44, s38
	v_lshl_add_u64 v[194:195], v[194:195], 0, s[88:89]
	s_mov_b32 m0, s26
	ds_read_b128 v[160:163], v251 offset:49152
	ds_read_b128 v[164:167], v251 offset:50176
	ds_read_b128 v[168:171], v251 offset:51200
	ds_read_b128 v[172:175], v251 offset:52224
	ds_read_b128 v[176:179], v251 offset:53248
	ds_read_b128 v[180:183], v251 offset:54272
	ds_read_b128 v[184:187], v251 offset:55296
	ds_read_b128 v[188:191], v251 offset:56320
	global_load_lds_dwordx4 v[194:195], off
	s_add_i32 m0, s26, 0x2000
	s_add_u32 s24, s24, 0x40080
	v_lshl_add_u64 v[194:195], v[196:197], 0, s[88:89]
	s_addc_u32 s25, s25, 0
	s_add_i32 s26, s45, s38
	global_load_lds_dwordx4 v[194:195], off
	v_lshl_add_u64 v[194:195], s[24:25], 0, v[192:193]
	s_mov_b32 m0, s26
	s_nop 0
	global_load_lds_dwordx4 v[194:195], off
	v_lshl_add_u64 v[194:195], s[24:25], 0, v[198:199]
	s_add_i32 m0, s26, 0x2000
	s_nop 0
	global_load_lds_dwordx4 v[194:195], off
	v_lshl_add_u64 v[194:195], v[208:209], 0, s[88:89]
	s_mov_b32 m0, s62
	s_nop 0
	global_load_lds_dwordx4 v[194:195], off
	v_lshl_add_u64 v[194:195], v[210:211], 0, s[88:89]
	s_mov_b32 m0, s63
	s_nop 0
	global_load_lds_dwordx4 v[194:195], off
	s_waitcnt vmcnt(8)
	s_waitcnt lgkmcnt(0)
	s_barrier
	s_setprio 1
	s_waitcnt lgkmcnt(0)
	v_mfma_f32_16x16x32_bf16 v[60:63], v[112:115], v[160:163], v[60:63]
	v_mfma_f32_16x16x32_bf16 v[56:59], v[124:127], v[160:163], v[56:59]
	v_mfma_f32_16x16x32_bf16 v[44:47], v[112:115], v[168:171], v[44:47]
	v_mfma_f32_16x16x32_bf16 v[40:43], v[124:127], v[168:171], v[40:43]
	v_mfma_f32_16x16x32_bf16 v[28:31], v[112:115], v[176:179], v[28:31]
	v_mfma_f32_16x16x32_bf16 v[24:27], v[124:127], v[176:179], v[24:27]
	v_mfma_f32_16x16x32_bf16 v[12:15], v[112:115], v[184:187], v[12:15]
	v_mfma_f32_16x16x32_bf16 v[8:11], v[124:127], v[184:187], v[8:11]
	v_mfma_f32_16x16x32_bf16 v[60:63], v[120:123], v[164:167], v[60:63]
	v_mfma_f32_16x16x32_bf16 v[56:59], v[128:131], v[164:167], v[56:59]
	v_mfma_f32_16x16x32_bf16 v[44:47], v[120:123], v[172:175], v[44:47]
	v_mfma_f32_16x16x32_bf16 v[40:43], v[128:131], v[172:175], v[40:43]
	v_mfma_f32_16x16x32_bf16 v[28:31], v[120:123], v[180:183], v[28:31]
	v_mfma_f32_16x16x32_bf16 v[24:27], v[128:131], v[180:183], v[24:27]
	v_mfma_f32_16x16x32_bf16 v[12:15], v[120:123], v[188:191], v[12:15]
	v_mfma_f32_16x16x32_bf16 v[8:11], v[128:131], v[188:191], v[8:11]
	s_setprio 0
	s_setprio 1
	v_mfma_f32_16x16x32_bf16 v[52:55], v[136:139], v[160:163], v[52:55]
	v_mfma_f32_16x16x32_bf16 v[48:51], v[144:147], v[160:163], v[48:51]
	v_mfma_f32_16x16x32_bf16 v[36:39], v[136:139], v[168:171], v[36:39]
	v_mfma_f32_16x16x32_bf16 v[32:35], v[144:147], v[168:171], v[32:35]
	v_mfma_f32_16x16x32_bf16 v[20:23], v[136:139], v[176:179], v[20:23]
	v_mfma_f32_16x16x32_bf16 v[16:19], v[144:147], v[176:179], v[16:19]
	v_mfma_f32_16x16x32_bf16 v[4:7], v[136:139], v[184:187], v[4:7]
	v_mfma_f32_16x16x32_bf16 v[0:3], v[144:147], v[184:187], v[0:3]
	v_mfma_f32_16x16x32_bf16 v[52:55], v[140:143], v[164:167], v[52:55]
	v_mfma_f32_16x16x32_bf16 v[48:51], v[156:159], v[164:167], v[48:51]
	v_mfma_f32_16x16x32_bf16 v[36:39], v[140:143], v[172:175], v[36:39]
	v_mfma_f32_16x16x32_bf16 v[32:35], v[156:159], v[172:175], v[32:35]
	v_mfma_f32_16x16x32_bf16 v[20:23], v[140:143], v[180:183], v[20:23]
	v_mfma_f32_16x16x32_bf16 v[16:19], v[156:159], v[180:183], v[16:19]
	v_mfma_f32_16x16x32_bf16 v[4:7], v[140:143], v[188:191], v[4:7]
	v_mfma_f32_16x16x32_bf16 v[0:3], v[156:159], v[188:191], v[0:3]
	s_setprio 0
	s_barrier
	s_add_i32 s34, s34, 2
	s_add_u32 s15, s15, 0x100
	s_addc_u32 s17, s17, 0
	s_add_u32 s22, s22, 0x100
	s_addc_u32 s23, s23, 0
	s_cmp_gt_u32 s34, 13
	s_cbranch_scc1 .Lkexit_5
	.p2alignl 6, 3212836864

; #define PG8_STAGE(bufoff, gbase, voff) do { _Pragma("unroll") for (int _i = 0; _i < 2; ++_i) \
;         __builtin_amdgcn_global_load_lds((const unsigned*)((const char*)(gbase) + (voff)[_i]), (PG8_LAS unsigned*)(lds + (bufoff) + ldsw + _i * 8192), 16, 0, 0); } while (0)
; #define PG8_LDA(dst, b, h) do { _Pragma("unroll") for (int m = 0; m < 4; ++m) _Pragma("unroll") for (int k = 0; k < 2; ++k) dst[m][k] = *(const PG8_LAS bf16x8*)(lds + PG8_SA(b, h) + aoff + m * 2048 + k * 1024); } while (0)
; #define PG8_LDB(dst, b, h) do { _Pragma("unroll") for (int n = 0; n < 2; ++n) _Pragma("unroll") for (int k = 0; k < 2; ++k) dst[n][k] = *(const PG8_LAS bf16x8*)(lds + PG8_SB(b, h) + boff + n * 2048 + k * 1024); } while (0)
; #define PG8_MMA(ai, bj, At, Bt) do { __builtin_amdgcn_s_setprio(1); _Pragma("unroll") for (int m = 0; m < 4; ++m) _Pragma("unroll") for (int n = 0; n < 2; ++n) _Pragma("unroll") for (int k = 0; k < 2; ++k) \
;         acc[ai][bj][m][n] = __builtin_amdgcn_mfma_f32_16x16x32_bf16(Bt[n][k], At[m][k], acc[ai][bj][m][n], 0, 0, 0); __builtin_amdgcn_s_setprio(0); } while (0)
; template <class Epi, class Sched, bool ALIGN_EPI = false, bool SP2 = false>
; __device__ __forceinline__ void gemm_phase(PG8_LAS unsigned char* lds, const Gemm g, const Sched& S, const Epi& E, int wave_in) {
;     ...
;         const char* nA = has_next ? (const char*)g.A + (size_t)(nxt.pm >> g.ash) * g.astride + (size_t)nxt.pm * tstep : cA; const char* nB = has_next ? (const char*)g.Bt + (size_t)(nxt.pm >> g.bsh) * g.bstride + (size_t)nxt.pn * tstep : cB;
;         for (int t = 0; t < nt; t += 2) {
;             const bool last = (t == nt - 2);
;             const char* a1 = cA + (size_t)(t + 1) * kstep;
;             const char* a2 = last ? nA : cA + (size_t)(t + 2) * kstep; const char* b2 = last ? nB : cB + (size_t)(t + 2) * kstep;
;             const char* a3 = a2 + kstep; const char* b3 = b2 + kstep;
;             if (last && has_next) S.a_ready(nxt);
;             if constexpr (SP2) {
;             PG8_LDB(B0, 0, 0); PG8_LDB(B1, 0, 1); PG8_SCHED; PG8_LDA(At, 0, 0); PG8_STAGE(PG8_SA(1, 1), a1 + hstep, voffA);
;             PG8_WAIT_V(8); PG8_WAIT_L(0); PG8_BAR; PG8_MMA(0, 0, At, B0); PG8_MMA(0, 1, At, B1); PG8_BAR; PG8_SCHED;
;             PG8_LDA(At, 0, 1); PG8_STAGE(PG8_SB(0, 0), b2, voffB); PG8_STAGE(PG8_SB(0, 1), b2 + hstep, voffB); PG8_STAGE(PG8_SA(0, 0), a2, voffA);
.LBB0_896:
	s_ashr_i32 s11, s10, 31
	s_lshl_b64 s[18:19], s[10:11], 19
	s_add_u32 s66, s6, s18
	s_addc_u32 s67, s72, s19
	s_and_b64 s[18:19], s[46:47], exec
	s_cselect_b32 s11, s67, s1
	s_cselect_b32 s34, s66, s0
	s_ashr_i32 s5, s4, 31
	s_lshl_b64 s[18:19], s[4:5], 19
	s_add_u32 s38, s73, s18
	s_addc_u32 s39, s74, s19
	s_and_b64 s[18:19], s[46:47], exec
	s_cselect_b32 s5, s39, s79
	s_cselect_b32 s53, s38, s78
	s_add_u32 s81, s78, 0x100
	s_addc_u32 s18, s79, 0
	s_add_u32 vcc_lo, s0, 0x40080
	s_addc_u32 vcc_hi, s1, 0
	s_mov_b32 s19, -2
	.p2alignl 3, 3212836864
	s_add_u32 s0, vcc_lo, 0xfffc0080
	s_addc_u32 s1, vcc_hi, -1
	s_add_i32 s76, s35, 0x100
	s_cmp_eq_u32 s19, 12
	s_cselect_b32 s79, s11, s1
	s_cselect_b32 s78, s34, s0
	s_cselect_b32 s1, s5, s18
	s_cselect_b32 s0, s53, s81
	s_add_i32 s29, s90, 0x100
	v_add_u32_e32 v140, s76, v207
	v_add_u32_e32 v156, s29, v207
	ds_read_b128 v[128:131], v140
	ds_read_b128 v[132:135], v140 offset:1024
	ds_read_b128 v[136:139], v140 offset:2048
	ds_read_b128 v[140:143], v140 offset:3072
	ds_read_b128 v[144:147], v156
	ds_read_b128 v[148:151], v156 offset:1024
	ds_read_b128 v[152:155], v156 offset:2048
	ds_read_b128 v[156:159], v156 offset:3072
	v_lshl_add_u64 v[190:191], vcc, 0, v[176:177]
	s_add_i32 m0, s33, 0xc000
	ds_read_b128 v[160:163], v219
	ds_read_b128 v[164:167], v219 offset:1024
	ds_read_b128 v[178:181], v219 offset:2048
	ds_read_b128 v[182:185], v219 offset:3072
	ds_read_b128 v[186:189], v219 offset:4096
	ds_read_b128 v[198:201], v219 offset:5120
	ds_read_b128 v[202:205], v219 offset:6144
	ds_read_b128 v[220:223], v219 offset:7168
	global_load_lds_dwordx4 v[190:191], off
	v_lshl_add_u64 v[190:191], vcc, 0, v[174:175]
	s_add_i32 m0, s33, 0xe000
	s_nop 0
	global_load_lds_dwordx4 v[190:191], off
	s_waitcnt vmcnt(8)
	s_waitcnt lgkmcnt(0)
	s_barrier
	s_setprio 1
	s_waitcnt lgkmcnt(0)
	v_mfma_f32_16x16x32_bf16 v[124:127], v[128:131], v[160:163], 0
	v_mfma_f32_16x16x32_bf16 v[60:63], v[136:139], v[160:163], 0
	v_mfma_f32_16x16x32_bf16 v[116:119], v[128:131], v[178:181], 0
	v_mfma_f32_16x16x32_bf16 v[52:55], v[136:139], v[178:181], 0
	v_mfma_f32_16x16x32_bf16 v[108:111], v[128:131], v[186:189], 0
	v_mfma_f32_16x16x32_bf16 v[44:47], v[136:139], v[186:189], 0
	v_mfma_f32_16x16x32_bf16 v[100:103], v[128:131], v[202:205], 0
	v_mfma_f32_16x16x32_bf16 v[36:39], v[136:139], v[202:205], 0
	v_mfma_f32_16x16x32_bf16 v[124:127], v[132:135], v[164:167], v[124:127]
	v_mfma_f32_16x16x32_bf16 v[60:63], v[140:143], v[164:167], v[60:63]
	v_mfma_f32_16x16x32_bf16 v[116:119], v[132:135], v[182:185], v[116:119]
	v_mfma_f32_16x16x32_bf16 v[52:55], v[140:143], v[182:185], v[52:55]
	v_mfma_f32_16x16x32_bf16 v[108:111], v[132:135], v[198:201], v[108:111]
	v_mfma_f32_16x16x32_bf16 v[44:47], v[140:143], v[198:201], v[44:47]
	v_mfma_f32_16x16x32_bf16 v[100:103], v[132:135], v[220:223], v[100:103]
	v_mfma_f32_16x16x32_bf16 v[36:39], v[140:143], v[220:223], v[36:39]
	s_setprio 0
	s_setprio 1
	v_mfma_f32_16x16x32_bf16 v[120:123], v[144:147], v[160:163], 0
	v_mfma_f32_16x16x32_bf16 v[56:59], v[152:155], v[160:163], 0
	v_mfma_f32_16x16x32_bf16 v[112:115], v[144:147], v[178:181], 0
	v_mfma_f32_16x16x32_bf16 v[48:51], v[152:155], v[178:181], 0
	v_mfma_f32_16x16x32_bf16 v[104:107], v[144:147], v[186:189], 0
	v_mfma_f32_16x16x32_bf16 v[40:43], v[152:155], v[186:189], 0
	v_mfma_f32_16x16x32_bf16 v[96:99], v[144:147], v[202:205], 0
	v_mfma_f32_16x16x32_bf16 v[32:35], v[152:155], v[202:205], 0
	v_mfma_f32_16x16x32_bf16 v[120:123], v[148:151], v[164:167], v[120:123]
	v_mfma_f32_16x16x32_bf16 v[56:59], v[156:159], v[164:167], v[56:59]
	v_mfma_f32_16x16x32_bf16 v[112:115], v[148:151], v[182:185], v[112:115]
	v_mfma_f32_16x16x32_bf16 v[48:51], v[156:159], v[182:185], v[48:51]
	v_mfma_f32_16x16x32_bf16 v[104:107], v[148:151], v[198:201], v[104:107]
	v_mfma_f32_16x16x32_bf16 v[40:43], v[156:159], v[198:201], v[40:43]
	v_mfma_f32_16x16x32_bf16 v[96:99], v[148:151], v[220:223], v[96:99]
	v_mfma_f32_16x16x32_bf16 v[32:35], v[156:159], v[220:223], v[32:35]
	s_setprio 0
	s_barrier
	s_add_i32 s76, s76, s75
	v_lshl_add_u64 v[190:191], s[0:1], 0, v[192:193]
	s_mov_b32 m0, s76
	ds_read_b128 v[160:163], v219 offset:16384
	ds_read_b128 v[164:167], v219 offset:17408
	ds_read_b128 v[178:181], v219 offset:18432
	ds_read_b128 v[182:185], v219 offset:19456
	ds_read_b128 v[186:189], v219 offset:20480
	ds_read_b128 v[198:201], v219 offset:21504
	ds_read_b128 v[202:205], v219 offset:22528
	ds_read_b128 v[220:223], v219 offset:23552
	global_load_lds_dwordx4 v[190:191], off
	s_add_i32 m0, s76, 0x2000
	s_add_u32 s76, s0, 0x40000
	v_lshl_add_u64 v[194:195], s[0:1], 0, v[168:169]
	s_addc_u32 s77, s1, 0
	s_add_i32 s29, s29, s75
	global_load_lds_dwordx4 v[194:195], off
	v_lshl_add_u64 v[196:197], s[76:77], 0, v[192:193]
	s_mov_b32 m0, s29
	v_lshl_add_u64 v[224:225], s[78:79], 0, v[170:171]
	global_load_lds_dwordx4 v[196:197], off
	v_lshl_add_u64 v[196:197], s[76:77], 0, v[168:169]
	s_add_i32 m0, s29, 0x2000
	s_nop 0
	global_load_lds_dwordx4 v[196:197], off
	v_lshl_add_u64 v[196:197], s[78:79], 0, v[172:173]
	s_mov_b32 m0, s33
	s_nop 0
	global_load_lds_dwordx4 v[196:197], off
	s_mov_b32 m0, s62
	s_nop 0
	global_load_lds_dwordx4 v[224:225], off
	s_waitcnt vmcnt(8)
	s_waitcnt lgkmcnt(0)
	s_barrier
; #define PG8_STAGE(bufoff, gbase, voff) do { _Pragma("unroll") for (int _i = 0; _i < 2; ++_i) \
;         __builtin_amdgcn_global_load_lds((const unsigned*)((const char*)(gbase) + (voff)[_i]), (PG8_LAS unsigned*)(lds + (bufoff) + ldsw + _i * 8192), 16, 0, 0); } while (0)
; #define PG8_LDA(dst, b, h) do { _Pragma("unroll") for (int m = 0; m < 4; ++m) _Pragma("unroll") for (int k = 0; k < 2; ++k) dst[m][k] = *(const PG8_LAS bf16x8*)(lds + PG8_SA(b, h) + aoff + m * 2048 + k * 1024); } while (0)
; #define PG8_LDB(dst, b, h) do { _Pragma("unroll") for (int n = 0; n < 2; ++n) _Pragma("unroll") for (int k = 0; k < 2; ++k) dst[n][k] = *(const PG8_LAS bf16x8*)(lds + PG8_SB(b, h) + boff + n * 2048 + k * 1024); } while (0)
; #define PG8_MMA(ai, bj, At, Bt) do { __builtin_amdgcn_s_setprio(1); _Pragma("unroll") for (int m = 0; m < 4; ++m) _Pragma("unroll") for (int n = 0; n < 2; ++n) _Pragma("unroll") for (int k = 0; k < 2; ++k) \
;         acc[ai][bj][m][n] = __builtin_amdgcn_mfma_f32_16x16x32_bf16(Bt[n][k], At[m][k], acc[ai][bj][m][n], 0, 0, 0); __builtin_amdgcn_s_setprio(0); } while (0)
; #define PG8_WAIT_V(n) asm volatile("s_waitcnt vmcnt(" #n ")" ::: "memory")
; #define PG8_WAIT_L(n) asm volatile("s_waitcnt lgkmcnt(" #n ")" ::: "memory")
; #define PG8_BAR __builtin_amdgcn_s_barrier()
; #define PG8_SCHED __builtin_amdgcn_sched_barrier(0)
; template <class Epi, class Sched, bool ALIGN_EPI = false, bool SP2 = false>
; __device__ __forceinline__ void gemm_phase(PG8_LAS unsigned char* lds, const Gemm g, const Sched& S, const Epi& E, int wave_in) {
;     ...
;             PG8_WAIT_V(8); PG8_WAIT_L(0); PG8_BAR; PG8_MMA(1, 0, At, B0); PG8_MMA(1, 1, At, B1); PG8_BAR; PG8_SCHED;
;             PG8_LDB(B0, 1, 0); PG8_LDB(B1, 1, 1); PG8_SCHED; PG8_LDA(At, 1, 0); PG8_STAGE(PG8_SA(0, 1), a2 + hstep, voffA);
;             PG8_WAIT_V(8); PG8_WAIT_L(0); PG8_BAR; PG8_MMA(0, 0, At, B0); PG8_MMA(0, 1, At, B1); PG8_BAR; PG8_SCHED;
	s_setprio 1
	s_waitcnt lgkmcnt(0)
	v_mfma_f32_16x16x32_bf16 v[92:95], v[128:131], v[160:163], 0
	v_mfma_f32_16x16x32_bf16 v[28:31], v[136:139], v[160:163], 0
	v_mfma_f32_16x16x32_bf16 v[84:87], v[128:131], v[178:181], 0
	v_mfma_f32_16x16x32_bf16 v[20:23], v[136:139], v[178:181], 0
	v_mfma_f32_16x16x32_bf16 v[76:79], v[128:131], v[186:189], 0
	v_mfma_f32_16x16x32_bf16 v[12:15], v[136:139], v[186:189], 0
	v_mfma_f32_16x16x32_bf16 v[68:71], v[128:131], v[202:205], 0
	v_mfma_f32_16x16x32_bf16 v[4:7], v[136:139], v[202:205], 0
	v_mfma_f32_16x16x32_bf16 v[92:95], v[132:135], v[164:167], v[92:95]
	v_mfma_f32_16x16x32_bf16 v[28:31], v[140:143], v[164:167], v[28:31]
	v_mfma_f32_16x16x32_bf16 v[84:87], v[132:135], v[182:185], v[84:87]
	v_mfma_f32_16x16x32_bf16 v[20:23], v[140:143], v[182:185], v[20:23]
	v_mfma_f32_16x16x32_bf16 v[76:79], v[132:135], v[198:201], v[76:79]
	v_mfma_f32_16x16x32_bf16 v[12:15], v[140:143], v[198:201], v[12:15]
	v_mfma_f32_16x16x32_bf16 v[68:71], v[132:135], v[220:223], v[68:71]
	v_mfma_f32_16x16x32_bf16 v[4:7], v[140:143], v[220:223], v[4:7]
	s_setprio 0
	s_setprio 1
	v_mfma_f32_16x16x32_bf16 v[88:91], v[144:147], v[160:163], 0
	v_mfma_f32_16x16x32_bf16 v[24:27], v[152:155], v[160:163], 0
	v_mfma_f32_16x16x32_bf16 v[80:83], v[144:147], v[178:181], 0
	v_mfma_f32_16x16x32_bf16 v[16:19], v[152:155], v[178:181], 0
	v_mfma_f32_16x16x32_bf16 v[72:75], v[144:147], v[186:189], 0
	v_mfma_f32_16x16x32_bf16 v[8:11], v[152:155], v[186:189], 0
	v_mfma_f32_16x16x32_bf16 v[64:67], v[144:147], v[202:205], 0
	v_mfma_f32_16x16x32_bf16 v[0:3], v[152:155], v[202:205], 0
	v_mfma_f32_16x16x32_bf16 v[88:91], v[148:151], v[164:167], v[88:91]
	v_mfma_f32_16x16x32_bf16 v[24:27], v[156:159], v[164:167], v[24:27]
	v_mfma_f32_16x16x32_bf16 v[80:83], v[148:151], v[182:185], v[80:83]
	v_mfma_f32_16x16x32_bf16 v[16:19], v[156:159], v[182:185], v[16:19]
	v_mfma_f32_16x16x32_bf16 v[72:75], v[148:151], v[198:201], v[72:75]
	v_mfma_f32_16x16x32_bf16 v[8:11], v[156:159], v[198:201], v[8:11]
	v_mfma_f32_16x16x32_bf16 v[64:67], v[148:151], v[220:223], v[64:67]
	v_mfma_f32_16x16x32_bf16 v[0:3], v[156:159], v[220:223], v[0:3]
	s_setprio 0
	s_barrier
	s_add_i32 s29, s65, 0x100
	s_add_i32 s2, s52, 0x100
	v_add_u32_e32 v140, s29, v207
	v_add_u32_e32 v156, s2, v207
	ds_read_b128 v[128:131], v140
	ds_read_b128 v[132:135], v140 offset:1024
	ds_read_b128 v[136:139], v140 offset:2048
	ds_read_b128 v[140:143], v140 offset:3072
	ds_read_b128 v[144:147], v156
	ds_read_b128 v[148:151], v156 offset:1024
	ds_read_b128 v[152:155], v156 offset:2048
	ds_read_b128 v[156:159], v156 offset:3072
	s_add_u32 s76, s78, 0x40000
	s_addc_u32 s77, s79, 0
	s_mov_b32 m0, s63
	v_lshl_add_u64 v[226:227], s[76:77], 0, v[172:173]
	ds_read_b128 v[160:163], v219 offset:32768
	ds_read_b128 v[164:167], v219 offset:33792
	ds_read_b128 v[178:181], v219 offset:34816
	ds_read_b128 v[182:185], v219 offset:35840
	ds_read_b128 v[186:189], v219 offset:36864
	ds_read_b128 v[198:201], v219 offset:37888
	ds_read_b128 v[202:205], v219 offset:38912
	ds_read_b128 v[220:223], v219 offset:39936
	global_load_lds_dwordx4 v[226:227], off
	v_lshl_add_u64 v[226:227], s[76:77], 0, v[170:171]
	s_mov_b32 m0, s31
	s_nop 0
	global_load_lds_dwordx4 v[226:227], off
	s_waitcnt vmcnt(8)
	s_waitcnt lgkmcnt(0)
	s_barrier
	s_setprio 1
	s_waitcnt lgkmcnt(0)
	v_mfma_f32_16x16x32_bf16 v[124:127], v[128:131], v[160:163], v[124:127]
	v_mfma_f32_16x16x32_bf16 v[60:63], v[136:139], v[160:163], v[60:63]
	v_mfma_f32_16x16x32_bf16 v[116:119], v[128:131], v[178:181], v[116:119]
	v_mfma_f32_16x16x32_bf16 v[52:55], v[136:139], v[178:181], v[52:55]
	v_mfma_f32_16x16x32_bf16 v[108:111], v[128:131], v[186:189], v[108:111]
	v_mfma_f32_16x16x32_bf16 v[44:47], v[136:139], v[186:189], v[44:47]
	v_mfma_f32_16x16x32_bf16 v[100:103], v[128:131], v[202:205], v[100:103]
	v_mfma_f32_16x16x32_bf16 v[36:39], v[136:139], v[202:205], v[36:39]
	v_mfma_f32_16x16x32_bf16 v[124:127], v[132:135], v[164:167], v[124:127]
	v_mfma_f32_16x16x32_bf16 v[60:63], v[140:143], v[164:167], v[60:63]
	v_mfma_f32_16x16x32_bf16 v[116:119], v[132:135], v[182:185], v[116:119]
	v_mfma_f32_16x16x32_bf16 v[52:55], v[140:143], v[182:185], v[52:55]
	v_mfma_f32_16x16x32_bf16 v[108:111], v[132:135], v[198:201], v[108:111]
	v_mfma_f32_16x16x32_bf16 v[44:47], v[140:143], v[198:201], v[44:47]
	v_mfma_f32_16x16x32_bf16 v[100:103], v[132:135], v[220:223], v[100:103]
	v_mfma_f32_16x16x32_bf16 v[36:39], v[140:143], v[220:223], v[36:39]
	s_setprio 0
	s_setprio 1
	v_mfma_f32_16x16x32_bf16 v[120:123], v[144:147], v[160:163], v[120:123]
	v_mfma_f32_16x16x32_bf16 v[56:59], v[152:155], v[160:163], v[56:59]
	v_mfma_f32_16x16x32_bf16 v[112:115], v[144:147], v[178:181], v[112:115]
	v_mfma_f32_16x16x32_bf16 v[48:51], v[152:155], v[178:181], v[48:51]
	v_mfma_f32_16x16x32_bf16 v[104:107], v[144:147], v[186:189], v[104:107]
	v_mfma_f32_16x16x32_bf16 v[40:43], v[152:155], v[186:189], v[40:43]
	v_mfma_f32_16x16x32_bf16 v[96:99], v[144:147], v[202:205], v[96:99]
	v_mfma_f32_16x16x32_bf16 v[32:35], v[152:155], v[202:205], v[32:35]
	v_mfma_f32_16x16x32_bf16 v[120:123], v[148:151], v[164:167], v[120:123]
	v_mfma_f32_16x16x32_bf16 v[56:59], v[156:159], v[164:167], v[56:59]
	v_mfma_f32_16x16x32_bf16 v[112:115], v[148:151], v[182:185], v[112:115]
	v_mfma_f32_16x16x32_bf16 v[48:51], v[156:159], v[182:185], v[48:51]
	v_mfma_f32_16x16x32_bf16 v[104:107], v[148:151], v[198:201], v[104:107]
	v_mfma_f32_16x16x32_bf16 v[40:43], v[156:159], v[198:201], v[40:43]
	v_mfma_f32_16x16x32_bf16 v[96:99], v[148:151], v[220:223], v[96:99]
	v_mfma_f32_16x16x32_bf16 v[32:35], v[156:159], v[220:223], v[32:35]
	s_setprio 0
	s_barrier
; #define PG8_STAGE(bufoff, gbase, voff) do { _Pragma("unroll") for (int _i = 0; _i < 2; ++_i) \
;         __builtin_amdgcn_global_load_lds((const unsigned*)((const char*)(gbase) + (voff)[_i]), (PG8_LAS unsigned*)(lds + (bufoff) + ldsw + _i * 8192), 16, 0, 0); } while (0)
; #define PG8_LDA(dst, b, h) do { _Pragma("unroll") for (int m = 0; m < 4; ++m) _Pragma("unroll") for (int k = 0; k < 2; ++k) dst[m][k] = *(const PG8_LAS bf16x8*)(lds + PG8_SA(b, h) + aoff + m * 2048 + k * 1024); } while (0)
; #define PG8_MMA(ai, bj, At, Bt) do { __builtin_amdgcn_s_setprio(1); _Pragma("unroll") for (int m = 0; m < 4; ++m) _Pragma("unroll") for (int n = 0; n < 2; ++n) _Pragma("unroll") for (int k = 0; k < 2; ++k) \
;         acc[ai][bj][m][n] = __builtin_amdgcn_mfma_f32_16x16x32_bf16(Bt[n][k], At[m][k], acc[ai][bj][m][n], 0, 0, 0); __builtin_amdgcn_s_setprio(0); } while (0)
; #define PG8_WAIT_V(n) asm volatile("s_waitcnt vmcnt(" #n ")" ::: "memory")
; #define PG8_WAIT_L(n) asm volatile("s_waitcnt lgkmcnt(" #n ")" ::: "memory")
; #define PG8_BAR __builtin_amdgcn_s_barrier()
; #define PG8_SCHED __builtin_amdgcn_sched_barrier(0)
; template <class Epi, class Sched, bool ALIGN_EPI = false, bool SP2 = false>
; __device__ __forceinline__ void gemm_phase(PG8_LAS unsigned char* lds, const Gemm g, const Sched& S, const Epi& E, int wave_in) {
;     ...
;         for (int t = 0; t < nt; t += 2) {
;             const bool last = (t == nt - 2);
;     ...
;             PG8_LDA(At, 1, 1); PG8_STAGE(PG8_SB(1, 0), b3, voffB); PG8_STAGE(PG8_SB(1, 1), b3 + hstep, voffB); PG8_STAGE(PG8_SA(1, 0), a3, voffA);
;             PG8_WAIT_V(8); PG8_WAIT_L(0); PG8_BAR; PG8_MMA(1, 0, At, B0); PG8_MMA(1, 1, At, B1); PG8_BAR; PG8_SCHED;
	s_add_i32 s29, s29, s75
	v_lshl_add_u64 v[190:191], v[190:191], 0, s[88:89]
	s_mov_b32 m0, s29
	ds_read_b128 v[160:163], v219 offset:49152
	ds_read_b128 v[164:167], v219 offset:50176
	ds_read_b128 v[178:181], v219 offset:51200
	ds_read_b128 v[182:185], v219 offset:52224
	ds_read_b128 v[186:189], v219 offset:53248
	ds_read_b128 v[198:201], v219 offset:54272
	ds_read_b128 v[202:205], v219 offset:55296
	ds_read_b128 v[220:223], v219 offset:56320
	global_load_lds_dwordx4 v[190:191], off
	s_add_i32 m0, s29, 0x2000
	s_add_u32 s0, s0, 0x40080
	v_lshl_add_u64 v[190:191], v[194:195], 0, s[88:89]
	s_addc_u32 s1, s1, 0
	s_add_i32 s2, s2, s75
	global_load_lds_dwordx4 v[190:191], off
	v_lshl_add_u64 v[190:191], s[0:1], 0, v[192:193]
	s_mov_b32 m0, s2
	s_nop 0
	global_load_lds_dwordx4 v[190:191], off
	v_lshl_add_u64 v[190:191], s[0:1], 0, v[168:169]
	s_add_i32 m0, s2, 0x2000
	s_nop 0
	global_load_lds_dwordx4 v[190:191], off
	v_lshl_add_u64 v[190:191], v[196:197], 0, s[88:89]
	s_mov_b32 m0, s9
	s_nop 0
	global_load_lds_dwordx4 v[190:191], off
	v_lshl_add_u64 v[190:191], v[224:225], 0, s[88:89]
	s_mov_b32 m0, s96
	s_nop 0
	global_load_lds_dwordx4 v[190:191], off
	s_waitcnt vmcnt(8)
	s_waitcnt lgkmcnt(0)
	s_barrier
	s_setprio 1
	s_waitcnt lgkmcnt(0)
	v_mfma_f32_16x16x32_bf16 v[92:95], v[128:131], v[160:163], v[92:95]
	v_mfma_f32_16x16x32_bf16 v[28:31], v[136:139], v[160:163], v[28:31]
	v_mfma_f32_16x16x32_bf16 v[84:87], v[128:131], v[178:181], v[84:87]
	v_mfma_f32_16x16x32_bf16 v[20:23], v[136:139], v[178:181], v[20:23]
	v_mfma_f32_16x16x32_bf16 v[76:79], v[128:131], v[186:189], v[76:79]
	v_mfma_f32_16x16x32_bf16 v[12:15], v[136:139], v[186:189], v[12:15]
	v_mfma_f32_16x16x32_bf16 v[68:71], v[128:131], v[202:205], v[68:71]
	v_mfma_f32_16x16x32_bf16 v[4:7], v[136:139], v[202:205], v[4:7]
	v_mfma_f32_16x16x32_bf16 v[92:95], v[132:135], v[164:167], v[92:95]
	v_mfma_f32_16x16x32_bf16 v[28:31], v[140:143], v[164:167], v[28:31]
	v_mfma_f32_16x16x32_bf16 v[84:87], v[132:135], v[182:185], v[84:87]
	v_mfma_f32_16x16x32_bf16 v[20:23], v[140:143], v[182:185], v[20:23]
	v_mfma_f32_16x16x32_bf16 v[76:79], v[132:135], v[198:201], v[76:79]
	v_mfma_f32_16x16x32_bf16 v[12:15], v[140:143], v[198:201], v[12:15]
	v_mfma_f32_16x16x32_bf16 v[68:71], v[132:135], v[220:223], v[68:71]
	v_mfma_f32_16x16x32_bf16 v[4:7], v[140:143], v[220:223], v[4:7]
	s_setprio 0
	s_setprio 1
	v_mfma_f32_16x16x32_bf16 v[88:91], v[144:147], v[160:163], v[88:91]
	v_mfma_f32_16x16x32_bf16 v[24:27], v[152:155], v[160:163], v[24:27]
	v_mfma_f32_16x16x32_bf16 v[80:83], v[144:147], v[178:181], v[80:83]
	v_mfma_f32_16x16x32_bf16 v[16:19], v[152:155], v[178:181], v[16:19]
	v_mfma_f32_16x16x32_bf16 v[72:75], v[144:147], v[186:189], v[72:75]
	v_mfma_f32_16x16x32_bf16 v[8:11], v[152:155], v[186:189], v[8:11]
	v_mfma_f32_16x16x32_bf16 v[64:67], v[144:147], v[202:205], v[64:67]
	v_mfma_f32_16x16x32_bf16 v[0:3], v[152:155], v[202:205], v[0:3]
	v_mfma_f32_16x16x32_bf16 v[88:91], v[148:151], v[164:167], v[88:91]
	v_mfma_f32_16x16x32_bf16 v[24:27], v[156:159], v[164:167], v[24:27]
	v_mfma_f32_16x16x32_bf16 v[80:83], v[148:151], v[182:185], v[80:83]
	v_mfma_f32_16x16x32_bf16 v[16:19], v[156:159], v[182:185], v[16:19]
	v_mfma_f32_16x16x32_bf16 v[72:75], v[148:151], v[198:201], v[72:75]
	v_mfma_f32_16x16x32_bf16 v[8:11], v[156:159], v[198:201], v[8:11]
	v_mfma_f32_16x16x32_bf16 v[64:67], v[148:151], v[220:223], v[64:67]
	v_mfma_f32_16x16x32_bf16 v[0:3], v[156:159], v[220:223], v[0:3]
	s_setprio 0
	s_barrier
	s_add_i32 s19, s19, 2
	s_add_u32 s81, s81, 0x100
	s_addc_u32 s18, s18, 0
	s_add_u32 vcc_lo, vcc_lo, 0x100
	s_addc_u32 vcc_hi, vcc_hi, 0
	s_cmp_gt_u32 s19, 13
	s_cbranch_scc1 .Lkexit_6
	.p2alignl 6, 3212836864

; #define PG8_STAGE(bufoff, gbase, voff) do { _Pragma("unroll") for (int _i = 0; _i < 2; ++_i) \
;         __builtin_amdgcn_global_load_lds((const unsigned*)((const char*)(gbase) + (voff)[_i]), (PG8_LAS unsigned*)(lds + (bufoff) + ldsw + _i * 8192), 16, 0, 0); } while (0)
; #define PG8_LDA(dst, b, h) do { _Pragma("unroll") for (int m = 0; m < 4; ++m) _Pragma("unroll") for (int k = 0; k < 2; ++k) dst[m][k] = *(const PG8_LAS bf16x8*)(lds + PG8_SA(b, h) + aoff + m * 2048 + k * 1024); } while (0)
; #define PG8_LDB(dst, b, h) do { _Pragma("unroll") for (int n = 0; n < 2; ++n) _Pragma("unroll") for (int k = 0; k < 2; ++k) dst[n][k] = *(const PG8_LAS bf16x8*)(lds + PG8_SB(b, h) + boff + n * 2048 + k * 1024); } while (0)
; #define PG8_MMA(ai, bj, At, Bt) do { __builtin_amdgcn_s_setprio(1); _Pragma("unroll") for (int m = 0; m < 4; ++m) _Pragma("unroll") for (int n = 0; n < 2; ++n) _Pragma("unroll") for (int k = 0; k < 2; ++k) \
;         acc[ai][bj][m][n] = __builtin_amdgcn_mfma_f32_16x16x32_bf16(Bt[n][k], At[m][k], acc[ai][bj][m][n], 0, 0, 0); __builtin_amdgcn_s_setprio(0); } while (0)
; template <class Epi, class Sched, bool ALIGN_EPI = false, bool SP2 = false>
; __device__ __forceinline__ void gemm_phase(PG8_LAS unsigned char* lds, const Gemm g, const Sched& S, const Epi& E, int wave_in) {
;     ...
;         const char* nA = has_next ? (const char*)g.A + (size_t)(nxt.pm >> g.ash) * g.astride + (size_t)nxt.pm * tstep : cA; const char* nB = has_next ? (const char*)g.Bt + (size_t)(nxt.pm >> g.bsh) * g.bstride + (size_t)nxt.pn * tstep : cB;
;         for (int t = 0; t < nt; t += 2) {
;             const bool last = (t == nt - 2);
;             const char* a1 = cA + (size_t)(t + 1) * kstep;
;             const char* a2 = last ? nA : cA + (size_t)(t + 2) * kstep; const char* b2 = last ? nB : cB + (size_t)(t + 2) * kstep;
;             const char* a3 = a2 + kstep; const char* b3 = b2 + kstep;
;             if (last && has_next) S.a_ready(nxt);
;             if constexpr (SP2) {
;             PG8_LDB(B0, 0, 0); PG8_LDB(B1, 0, 1); PG8_SCHED; PG8_LDA(At, 0, 0); PG8_STAGE(PG8_SA(1, 1), a1 + hstep, voffA);
;             PG8_WAIT_V(8); PG8_WAIT_L(0); PG8_BAR; PG8_MMA(0, 0, At, B0); PG8_MMA(0, 1, At, B1); PG8_BAR; PG8_SCHED;
;             PG8_LDA(At, 0, 1); PG8_STAGE(PG8_SB(0, 0), b2, voffB); PG8_STAGE(PG8_SB(0, 1), b2 + hstep, voffB); PG8_STAGE(PG8_SA(0, 0), a2, voffA);
.LBB0_1030:
	s_add_u32 s34, s20, 0x100
	s_addc_u32 s42, s21, 0
	s_mov_b32 s43, -2
	.p2alignl 3, 3212836864
	s_add_u32 s20, s16, 0x100
	s_addc_u32 s21, s17, 0
	s_add_i32 s2, s35, 0x100
	s_cmp_eq_u32 s43, 40
	s_cselect_b32 s25, s13, s21
	s_cselect_b32 s24, s12, s20
	s_cselect_b32 s23, s15, s42
	s_cselect_b32 s22, s14, s34
	s_add_i32 s29, s90, 0x100
	v_add_u32_e32 v128, s2, v249
	v_add_u32_e32 v156, s29, v249
	ds_read_b128 v[112:115], v128
	ds_read_b128 v[120:123], v128 offset:1024
	ds_read_b128 v[124:127], v128 offset:2048
	ds_read_b128 v[128:131], v128 offset:3072
	ds_read_b128 v[136:139], v156
	ds_read_b128 v[140:143], v156 offset:1024
	ds_read_b128 v[144:147], v156 offset:2048
	ds_read_b128 v[156:159], v156 offset:3072
	v_lshl_add_u64 v[194:195], s[16:17], 0, v[206:207]
	s_add_i32 m0, s45, 0xc000
	ds_read_b128 v[160:163], v251
	ds_read_b128 v[164:167], v251 offset:1024
	ds_read_b128 v[168:171], v251 offset:2048
	ds_read_b128 v[172:175], v251 offset:3072
	ds_read_b128 v[176:179], v251 offset:4096
	ds_read_b128 v[180:183], v251 offset:5120
	ds_read_b128 v[184:187], v251 offset:6144
	ds_read_b128 v[188:191], v251 offset:7168
	global_load_lds_dwordx4 v[194:195], off
	v_lshl_add_u64 v[194:195], s[16:17], 0, v[204:205]
	s_add_i32 m0, s45, 0xe000
	s_nop 0
	global_load_lds_dwordx4 v[194:195], off
	s_waitcnt vmcnt(8)
	s_waitcnt lgkmcnt(0)
	s_barrier
	s_setprio 1
	s_waitcnt lgkmcnt(0)
	v_mfma_f32_16x16x32_bf16 v[152:155], v[112:115], v[160:163], 0
	v_mfma_f32_16x16x32_bf16 v[148:151], v[124:127], v[160:163], 0
	v_mfma_f32_16x16x32_bf16 v[108:111], v[112:115], v[168:171], 0
	v_mfma_f32_16x16x32_bf16 v[104:107], v[124:127], v[168:171], 0
	v_mfma_f32_16x16x32_bf16 v[92:95], v[112:115], v[176:179], 0
	v_mfma_f32_16x16x32_bf16 v[88:91], v[124:127], v[176:179], 0
	v_mfma_f32_16x16x32_bf16 v[76:79], v[112:115], v[184:187], 0
	v_mfma_f32_16x16x32_bf16 v[72:75], v[124:127], v[184:187], 0
	v_mfma_f32_16x16x32_bf16 v[152:155], v[120:123], v[164:167], v[152:155]
	v_mfma_f32_16x16x32_bf16 v[148:151], v[128:131], v[164:167], v[148:151]
	v_mfma_f32_16x16x32_bf16 v[108:111], v[120:123], v[172:175], v[108:111]
	v_mfma_f32_16x16x32_bf16 v[104:107], v[128:131], v[172:175], v[104:107]
	v_mfma_f32_16x16x32_bf16 v[92:95], v[120:123], v[180:183], v[92:95]
	v_mfma_f32_16x16x32_bf16 v[88:91], v[128:131], v[180:183], v[88:91]
	v_mfma_f32_16x16x32_bf16 v[76:79], v[120:123], v[188:191], v[76:79]
	v_mfma_f32_16x16x32_bf16 v[72:75], v[128:131], v[188:191], v[72:75]
	s_setprio 0
	s_setprio 1
	v_mfma_f32_16x16x32_bf16 v[132:135], v[136:139], v[160:163], 0
	v_mfma_f32_16x16x32_bf16 v[116:119], v[144:147], v[160:163], 0
	v_mfma_f32_16x16x32_bf16 v[100:103], v[136:139], v[168:171], 0
	v_mfma_f32_16x16x32_bf16 v[96:99], v[144:147], v[168:171], 0
	v_mfma_f32_16x16x32_bf16 v[84:87], v[136:139], v[176:179], 0
	v_mfma_f32_16x16x32_bf16 v[80:83], v[144:147], v[176:179], 0
	v_mfma_f32_16x16x32_bf16 v[68:71], v[136:139], v[184:187], 0
	v_mfma_f32_16x16x32_bf16 v[64:67], v[144:147], v[184:187], 0
	v_mfma_f32_16x16x32_bf16 v[132:135], v[140:143], v[164:167], v[132:135]
	v_mfma_f32_16x16x32_bf16 v[116:119], v[156:159], v[164:167], v[116:119]
	v_mfma_f32_16x16x32_bf16 v[100:103], v[140:143], v[172:175], v[100:103]
	v_mfma_f32_16x16x32_bf16 v[96:99], v[156:159], v[172:175], v[96:99]
	v_mfma_f32_16x16x32_bf16 v[84:87], v[140:143], v[180:183], v[84:87]
	v_mfma_f32_16x16x32_bf16 v[80:83], v[156:159], v[180:183], v[80:83]
	v_mfma_f32_16x16x32_bf16 v[68:71], v[140:143], v[188:191], v[68:71]
	v_mfma_f32_16x16x32_bf16 v[64:67], v[156:159], v[188:191], v[64:67]
	s_setprio 0
	s_barrier
	s_add_i32 s2, s2, s44
	v_lshl_add_u64 v[194:195], s[22:23], 0, v[192:193]
	s_mov_b32 m0, s2
	ds_read_b128 v[160:163], v251 offset:16384
	ds_read_b128 v[164:167], v251 offset:17408
	ds_read_b128 v[168:171], v251 offset:18432
	ds_read_b128 v[172:175], v251 offset:19456
	ds_read_b128 v[176:179], v251 offset:20480
	ds_read_b128 v[180:183], v251 offset:21504
	ds_read_b128 v[184:187], v251 offset:22528
	ds_read_b128 v[188:191], v251 offset:23552
	global_load_lds_dwordx4 v[194:195], off
	s_add_i32 m0, s2, 0x2000
	s_add_u32 s16, s22, 0xb0000
	v_lshl_add_u64 v[196:197], s[22:23], 0, v[198:199]
	s_addc_u32 s17, s23, 0
	s_add_i32 s2, s29, s44
	global_load_lds_dwordx4 v[196:197], off
	v_lshl_add_u64 v[208:209], s[16:17], 0, v[192:193]
	s_mov_b32 m0, s2
	v_lshl_add_u64 v[210:211], s[24:25], 0, v[200:201]
	global_load_lds_dwordx4 v[208:209], off
	v_lshl_add_u64 v[208:209], s[16:17], 0, v[198:199]
	s_add_i32 m0, s2, 0x2000
	s_nop 0
	global_load_lds_dwordx4 v[208:209], off
	v_lshl_add_u64 v[208:209], s[24:25], 0, v[202:203]
	s_mov_b32 m0, s45
	s_nop 0
	global_load_lds_dwordx4 v[208:209], off
	s_mov_b32 m0, s46
	s_nop 0
	global_load_lds_dwordx4 v[210:211], off
	s_waitcnt vmcnt(8)
	s_waitcnt lgkmcnt(0)
	s_barrier
; #define PG8_STAGE(bufoff, gbase, voff) do { _Pragma("unroll") for (int _i = 0; _i < 2; ++_i) \
;         __builtin_amdgcn_global_load_lds((const unsigned*)((const char*)(gbase) + (voff)[_i]), (PG8_LAS unsigned*)(lds + (bufoff) + ldsw + _i * 8192), 16, 0, 0); } while (0)
; #define PG8_LDA(dst, b, h) do { _Pragma("unroll") for (int m = 0; m < 4; ++m) _Pragma("unroll") for (int k = 0; k < 2; ++k) dst[m][k] = *(const PG8_LAS bf16x8*)(lds + PG8_SA(b, h) + aoff + m * 2048 + k * 1024); } while (0)
; #define PG8_LDB(dst, b, h) do { _Pragma("unroll") for (int n = 0; n < 2; ++n) _Pragma("unroll") for (int k = 0; k < 2; ++k) dst[n][k] = *(const PG8_LAS bf16x8*)(lds + PG8_SB(b, h) + boff + n * 2048 + k * 1024); } while (0)
; #define PG8_MMA(ai, bj, At, Bt) do { __builtin_amdgcn_s_setprio(1); _Pragma("unroll") for (int m = 0; m < 4; ++m) _Pragma("unroll") for (int n = 0; n < 2; ++n) _Pragma("unroll") for (int k = 0; k < 2; ++k) \
;         acc[ai][bj][m][n] = __builtin_amdgcn_mfma_f32_16x16x32_bf16(Bt[n][k], At[m][k], acc[ai][bj][m][n], 0, 0, 0); __builtin_amdgcn_s_setprio(0); } while (0)
; #define PG8_WAIT_V(n) asm volatile("s_waitcnt vmcnt(" #n ")" ::: "memory")
; #define PG8_WAIT_L(n) asm volatile("s_waitcnt lgkmcnt(" #n ")" ::: "memory")
; #define PG8_BAR __builtin_amdgcn_s_barrier()
; #define PG8_SCHED __builtin_amdgcn_sched_barrier(0)
; template <class Epi, class Sched, bool ALIGN_EPI = false, bool SP2 = false>
; __device__ __forceinline__ void gemm_phase(PG8_LAS unsigned char* lds, const Gemm g, const Sched& S, const Epi& E, int wave_in) {
;     ...
;             PG8_WAIT_V(8); PG8_WAIT_L(0); PG8_BAR; PG8_MMA(1, 0, At, B0); PG8_MMA(1, 1, At, B1); PG8_BAR; PG8_SCHED;
;             PG8_LDB(B0, 1, 0); PG8_LDB(B1, 1, 1); PG8_SCHED; PG8_LDA(At, 1, 0); PG8_STAGE(PG8_SA(0, 1), a2 + hstep, voffA);
;             PG8_WAIT_V(8); PG8_WAIT_L(0); PG8_BAR; PG8_MMA(0, 0, At, B0); PG8_MMA(0, 1, At, B1); PG8_BAR; PG8_SCHED;
	s_setprio 1
	s_waitcnt lgkmcnt(0)
	v_mfma_f32_16x16x32_bf16 v[60:63], v[112:115], v[160:163], 0
	v_mfma_f32_16x16x32_bf16 v[56:59], v[124:127], v[160:163], 0
	v_mfma_f32_16x16x32_bf16 v[44:47], v[112:115], v[168:171], 0
	v_mfma_f32_16x16x32_bf16 v[40:43], v[124:127], v[168:171], 0
	v_mfma_f32_16x16x32_bf16 v[28:31], v[112:115], v[176:179], 0
	v_mfma_f32_16x16x32_bf16 v[24:27], v[124:127], v[176:179], 0
	v_mfma_f32_16x16x32_bf16 v[12:15], v[112:115], v[184:187], 0
	v_mfma_f32_16x16x32_bf16 v[8:11], v[124:127], v[184:187], 0
	v_mfma_f32_16x16x32_bf16 v[60:63], v[120:123], v[164:167], v[60:63]
	v_mfma_f32_16x16x32_bf16 v[56:59], v[128:131], v[164:167], v[56:59]
	v_mfma_f32_16x16x32_bf16 v[44:47], v[120:123], v[172:175], v[44:47]
	v_mfma_f32_16x16x32_bf16 v[40:43], v[128:131], v[172:175], v[40:43]
	v_mfma_f32_16x16x32_bf16 v[28:31], v[120:123], v[180:183], v[28:31]
	v_mfma_f32_16x16x32_bf16 v[24:27], v[128:131], v[180:183], v[24:27]
	v_mfma_f32_16x16x32_bf16 v[12:15], v[120:123], v[188:191], v[12:15]
	v_mfma_f32_16x16x32_bf16 v[8:11], v[128:131], v[188:191], v[8:11]
	s_setprio 0
	s_setprio 1
	v_mfma_f32_16x16x32_bf16 v[52:55], v[136:139], v[160:163], 0
	v_mfma_f32_16x16x32_bf16 v[48:51], v[144:147], v[160:163], 0
	v_mfma_f32_16x16x32_bf16 v[36:39], v[136:139], v[168:171], 0
	v_mfma_f32_16x16x32_bf16 v[32:35], v[144:147], v[168:171], 0
	v_mfma_f32_16x16x32_bf16 v[20:23], v[136:139], v[176:179], 0
	v_mfma_f32_16x16x32_bf16 v[16:19], v[144:147], v[176:179], 0
	v_mfma_f32_16x16x32_bf16 v[4:7], v[136:139], v[184:187], 0
	v_mfma_f32_16x16x32_bf16 v[0:3], v[144:147], v[184:187], 0
	v_mfma_f32_16x16x32_bf16 v[52:55], v[140:143], v[164:167], v[52:55]
	v_mfma_f32_16x16x32_bf16 v[48:51], v[156:159], v[164:167], v[48:51]
	v_mfma_f32_16x16x32_bf16 v[36:39], v[140:143], v[172:175], v[36:39]
	v_mfma_f32_16x16x32_bf16 v[32:35], v[156:159], v[172:175], v[32:35]
	v_mfma_f32_16x16x32_bf16 v[20:23], v[140:143], v[180:183], v[20:23]
	v_mfma_f32_16x16x32_bf16 v[16:19], v[156:159], v[180:183], v[16:19]
	v_mfma_f32_16x16x32_bf16 v[4:7], v[140:143], v[188:191], v[4:7]
	v_mfma_f32_16x16x32_bf16 v[0:3], v[156:159], v[188:191], v[0:3]
	s_setprio 0
	s_barrier
	s_add_i32 s2, s65, 0x100
	s_add_i32 s29, s52, 0x100
	v_add_u32_e32 v128, s2, v249
	v_add_u32_e32 v156, s29, v249
	ds_read_b128 v[112:115], v128
	ds_read_b128 v[120:123], v128 offset:1024
	ds_read_b128 v[124:127], v128 offset:2048
	ds_read_b128 v[128:131], v128 offset:3072
	ds_read_b128 v[136:139], v156
	ds_read_b128 v[140:143], v156 offset:1024
	ds_read_b128 v[144:147], v156 offset:2048
	ds_read_b128 v[156:159], v156 offset:3072
	s_add_u32 s16, s24, 0xb0000
	s_addc_u32 s17, s25, 0
	s_mov_b32 m0, s47
	v_lshl_add_u64 v[212:213], s[16:17], 0, v[202:203]
	ds_read_b128 v[160:163], v251 offset:32768
	ds_read_b128 v[164:167], v251 offset:33792
	ds_read_b128 v[168:171], v251 offset:34816
	ds_read_b128 v[172:175], v251 offset:35840
	ds_read_b128 v[176:179], v251 offset:36864
	ds_read_b128 v[180:183], v251 offset:37888
	ds_read_b128 v[184:187], v251 offset:38912
	ds_read_b128 v[188:191], v251 offset:39936
	global_load_lds_dwordx4 v[212:213], off
	v_lshl_add_u64 v[212:213], s[16:17], 0, v[200:201]
	s_mov_b32 m0, s60
	s_nop 0
	global_load_lds_dwordx4 v[212:213], off
	s_waitcnt vmcnt(8)
	s_waitcnt lgkmcnt(0)
	s_barrier
	s_setprio 1
	s_waitcnt lgkmcnt(0)
	v_mfma_f32_16x16x32_bf16 v[152:155], v[112:115], v[160:163], v[152:155]
	v_mfma_f32_16x16x32_bf16 v[148:151], v[124:127], v[160:163], v[148:151]
	v_mfma_f32_16x16x32_bf16 v[108:111], v[112:115], v[168:171], v[108:111]
	v_mfma_f32_16x16x32_bf16 v[104:107], v[124:127], v[168:171], v[104:107]
	v_mfma_f32_16x16x32_bf16 v[92:95], v[112:115], v[176:179], v[92:95]
	v_mfma_f32_16x16x32_bf16 v[88:91], v[124:127], v[176:179], v[88:91]
	v_mfma_f32_16x16x32_bf16 v[76:79], v[112:115], v[184:187], v[76:79]
	v_mfma_f32_16x16x32_bf16 v[72:75], v[124:127], v[184:187], v[72:75]
	v_mfma_f32_16x16x32_bf16 v[152:155], v[120:123], v[164:167], v[152:155]
	v_mfma_f32_16x16x32_bf16 v[148:151], v[128:131], v[164:167], v[148:151]
	v_mfma_f32_16x16x32_bf16 v[108:111], v[120:123], v[172:175], v[108:111]
	v_mfma_f32_16x16x32_bf16 v[104:107], v[128:131], v[172:175], v[104:107]
	v_mfma_f32_16x16x32_bf16 v[92:95], v[120:123], v[180:183], v[92:95]
	v_mfma_f32_16x16x32_bf16 v[88:91], v[128:131], v[180:183], v[88:91]
	v_mfma_f32_16x16x32_bf16 v[76:79], v[120:123], v[188:191], v[76:79]
	v_mfma_f32_16x16x32_bf16 v[72:75], v[128:131], v[188:191], v[72:75]
	s_setprio 0
	s_setprio 1
	v_mfma_f32_16x16x32_bf16 v[132:135], v[136:139], v[160:163], v[132:135]
	v_mfma_f32_16x16x32_bf16 v[116:119], v[144:147], v[160:163], v[116:119]
	v_mfma_f32_16x16x32_bf16 v[100:103], v[136:139], v[168:171], v[100:103]
	v_mfma_f32_16x16x32_bf16 v[96:99], v[144:147], v[168:171], v[96:99]
	v_mfma_f32_16x16x32_bf16 v[84:87], v[136:139], v[176:179], v[84:87]
	v_mfma_f32_16x16x32_bf16 v[80:83], v[144:147], v[176:179], v[80:83]
	v_mfma_f32_16x16x32_bf16 v[68:71], v[136:139], v[184:187], v[68:71]
	v_mfma_f32_16x16x32_bf16 v[64:67], v[144:147], v[184:187], v[64:67]
	v_mfma_f32_16x16x32_bf16 v[132:135], v[140:143], v[164:167], v[132:135]
	v_mfma_f32_16x16x32_bf16 v[116:119], v[156:159], v[164:167], v[116:119]
	v_mfma_f32_16x16x32_bf16 v[100:103], v[140:143], v[172:175], v[100:103]
	v_mfma_f32_16x16x32_bf16 v[96:99], v[156:159], v[172:175], v[96:99]
	v_mfma_f32_16x16x32_bf16 v[84:87], v[140:143], v[180:183], v[84:87]
	v_mfma_f32_16x16x32_bf16 v[80:83], v[156:159], v[180:183], v[80:83]
	v_mfma_f32_16x16x32_bf16 v[68:71], v[140:143], v[188:191], v[68:71]
	v_mfma_f32_16x16x32_bf16 v[64:67], v[156:159], v[188:191], v[64:67]
	s_setprio 0
	s_barrier
; #define PG8_STAGE(bufoff, gbase, voff) do { _Pragma("unroll") for (int _i = 0; _i < 2; ++_i) \
;         __builtin_amdgcn_global_load_lds((const unsigned*)((const char*)(gbase) + (voff)[_i]), (PG8_LAS unsigned*)(lds + (bufoff) + ldsw + _i * 8192), 16, 0, 0); } while (0)
; #define PG8_LDA(dst, b, h) do { _Pragma("unroll") for (int m = 0; m < 4; ++m) _Pragma("unroll") for (int k = 0; k < 2; ++k) dst[m][k] = *(const PG8_LAS bf16x8*)(lds + PG8_SA(b, h) + aoff + m * 2048 + k * 1024); } while (0)
; #define PG8_MMA(ai, bj, At, Bt) do { __builtin_amdgcn_s_setprio(1); _Pragma("unroll") for (int m = 0; m < 4; ++m) _Pragma("unroll") for (int n = 0; n < 2; ++n) _Pragma("unroll") for (int k = 0; k < 2; ++k) \
;         acc[ai][bj][m][n] = __builtin_amdgcn_mfma_f32_16x16x32_bf16(Bt[n][k], At[m][k], acc[ai][bj][m][n], 0, 0, 0); __builtin_amdgcn_s_setprio(0); } while (0)
; #define PG8_WAIT_V(n) asm volatile("s_waitcnt vmcnt(" #n ")" ::: "memory")
; #define PG8_WAIT_L(n) asm volatile("s_waitcnt lgkmcnt(" #n ")" ::: "memory")
; #define PG8_BAR __builtin_amdgcn_s_barrier()
; #define PG8_SCHED __builtin_amdgcn_sched_barrier(0)
; template <class Epi, class Sched, bool ALIGN_EPI = false, bool SP2 = false>
; __device__ __forceinline__ void gemm_phase(PG8_LAS unsigned char* lds, const Gemm g, const Sched& S, const Epi& E, int wave_in) {
;     ...
;         for (int t = 0; t < nt; t += 2) {
;             const bool last = (t == nt - 2);
;     ...
;             PG8_LDA(At, 1, 1); PG8_STAGE(PG8_SB(1, 0), b3, voffB); PG8_STAGE(PG8_SB(1, 1), b3 + hstep, voffB); PG8_STAGE(PG8_SA(1, 0), a3, voffA);
;             PG8_WAIT_V(8); PG8_WAIT_L(0); PG8_BAR; PG8_MMA(1, 0, At, B0); PG8_MMA(1, 1, At, B1); PG8_BAR; PG8_SCHED;
	s_add_i32 s2, s2, s44
	v_lshl_add_u64 v[194:195], v[194:195], 0, s[88:89]
	s_mov_b32 m0, s2
	ds_read_b128 v[160:163], v251 offset:49152
	ds_read_b128 v[164:167], v251 offset:50176
	ds_read_b128 v[168:171], v251 offset:51200
	ds_read_b128 v[172:175], v251 offset:52224
	ds_read_b128 v[176:179], v251 offset:53248
	ds_read_b128 v[180:183], v251 offset:54272
	ds_read_b128 v[184:187], v251 offset:55296
	ds_read_b128 v[188:191], v251 offset:56320
	global_load_lds_dwordx4 v[194:195], off
	s_add_i32 m0, s2, 0x2000
	s_add_u32 s16, s22, 0xb0080
	v_lshl_add_u64 v[194:195], v[196:197], 0, s[88:89]
	s_addc_u32 s17, s23, 0
	s_add_i32 s2, s29, s44
	global_load_lds_dwordx4 v[194:195], off
	v_lshl_add_u64 v[194:195], s[16:17], 0, v[192:193]
	s_mov_b32 m0, s2
	s_nop 0
	global_load_lds_dwordx4 v[194:195], off
	v_lshl_add_u64 v[194:195], s[16:17], 0, v[198:199]
	s_add_i32 m0, s2, 0x2000
	s_nop 0
	global_load_lds_dwordx4 v[194:195], off
	v_lshl_add_u64 v[194:195], v[208:209], 0, s[88:89]
	s_mov_b32 m0, s62
	s_nop 0
	global_load_lds_dwordx4 v[194:195], off
	v_lshl_add_u64 v[194:195], v[210:211], 0, s[88:89]
	s_mov_b32 m0, s63
	s_nop 0
	global_load_lds_dwordx4 v[194:195], off
	s_waitcnt vmcnt(8)
	s_waitcnt lgkmcnt(0)
	s_barrier
	s_setprio 1
	s_waitcnt lgkmcnt(0)
	v_mfma_f32_16x16x32_bf16 v[60:63], v[112:115], v[160:163], v[60:63]
	v_mfma_f32_16x16x32_bf16 v[56:59], v[124:127], v[160:163], v[56:59]
	v_mfma_f32_16x16x32_bf16 v[44:47], v[112:115], v[168:171], v[44:47]
	v_mfma_f32_16x16x32_bf16 v[40:43], v[124:127], v[168:171], v[40:43]
	v_mfma_f32_16x16x32_bf16 v[28:31], v[112:115], v[176:179], v[28:31]
	v_mfma_f32_16x16x32_bf16 v[24:27], v[124:127], v[176:179], v[24:27]
	v_mfma_f32_16x16x32_bf16 v[12:15], v[112:115], v[184:187], v[12:15]
	v_mfma_f32_16x16x32_bf16 v[8:11], v[124:127], v[184:187], v[8:11]
	v_mfma_f32_16x16x32_bf16 v[60:63], v[120:123], v[164:167], v[60:63]
	v_mfma_f32_16x16x32_bf16 v[56:59], v[128:131], v[164:167], v[56:59]
	v_mfma_f32_16x16x32_bf16 v[44:47], v[120:123], v[172:175], v[44:47]
	v_mfma_f32_16x16x32_bf16 v[40:43], v[128:131], v[172:175], v[40:43]
	v_mfma_f32_16x16x32_bf16 v[28:31], v[120:123], v[180:183], v[28:31]
	v_mfma_f32_16x16x32_bf16 v[24:27], v[128:131], v[180:183], v[24:27]
	v_mfma_f32_16x16x32_bf16 v[12:15], v[120:123], v[188:191], v[12:15]
	v_mfma_f32_16x16x32_bf16 v[8:11], v[128:131], v[188:191], v[8:11]
	s_setprio 0
	s_setprio 1
	v_mfma_f32_16x16x32_bf16 v[52:55], v[136:139], v[160:163], v[52:55]
	v_mfma_f32_16x16x32_bf16 v[48:51], v[144:147], v[160:163], v[48:51]
	v_mfma_f32_16x16x32_bf16 v[36:39], v[136:139], v[168:171], v[36:39]
	v_mfma_f32_16x16x32_bf16 v[32:35], v[144:147], v[168:171], v[32:35]
	v_mfma_f32_16x16x32_bf16 v[20:23], v[136:139], v[176:179], v[20:23]
	v_mfma_f32_16x16x32_bf16 v[16:19], v[144:147], v[176:179], v[16:19]
	v_mfma_f32_16x16x32_bf16 v[4:7], v[136:139], v[184:187], v[4:7]
	v_mfma_f32_16x16x32_bf16 v[0:3], v[144:147], v[184:187], v[0:3]
	v_mfma_f32_16x16x32_bf16 v[52:55], v[140:143], v[164:167], v[52:55]
	v_mfma_f32_16x16x32_bf16 v[48:51], v[156:159], v[164:167], v[48:51]
	v_mfma_f32_16x16x32_bf16 v[36:39], v[140:143], v[172:175], v[36:39]
	v_mfma_f32_16x16x32_bf16 v[32:35], v[156:159], v[172:175], v[32:35]
	v_mfma_f32_16x16x32_bf16 v[20:23], v[140:143], v[180:183], v[20:23]
	v_mfma_f32_16x16x32_bf16 v[16:19], v[156:159], v[180:183], v[16:19]
	v_mfma_f32_16x16x32_bf16 v[4:7], v[140:143], v[188:191], v[4:7]
	v_mfma_f32_16x16x32_bf16 v[0:3], v[156:159], v[188:191], v[0:3]
	s_setprio 0
	s_barrier
	s_add_i32 s43, s43, 2
	s_add_u32 s34, s34, 0x100
	s_addc_u32 s42, s42, 0
	s_cmp_gt_u32 s43, 41
	s_mov_b64 s[16:17], s[20:21]
	s_cbranch_scc1 .Lkexit_7
	.p2alignl 6, 3212836864
